# v036 + redundant post-barrier lgkmcnt(0) removed + compiler-inserted vmcnt(0) at each GEMM unit start removed (epilogue stores stay in flight as the source's counted waits intend)
# baseline (speedup 1.0000x reference)
; __device__ __forceinline__ int lane_id() { int l; asm volatile("v_mbcnt_lo_u32_b32 %0, -1, 0\n\tv_mbcnt_hi_u32_b32 %0, -1, %0" : "=v"(l)); return l; }
;     __device__ __forceinline__ bool next(int i, UnitG& u) const { if (!P.next(i, u)) return false; u.O = O + ((size_t)u.x0 * 256 * 2048 + (size_t)u.x1 * 256) * 2; u.ldo = 2048; u.kind = 0; return true; }
; template <class Epi, class Sched>
; __device__ __forceinline__ void gemm_phase(PG8_LAS unsigned char* lds, const Sched& S, const Epi& E, int tid_in) {
;     ...
;         int aoff, boff; { const int l3 = lane_id(), fr3 = l3 & 15, fq3 = l3 >> 4; aoff = lds_byte(wr * 64 + fr3, fq3 * 8); boff = lds_byte(wc * 32 + fr3, fq3 * 8); }
;         const bool has_next = S.next(ui + 1, nxt);
;         const char* nA = has_next ? nxt.A : cA; const char* nB = has_next ? nxt.B : cB;
;         const int nlda = has_next ? nxt.lda : cur.lda, nldb = has_next ? nxt.ldb : cur.ldb;
;         unsigned nvA, nvB; { int r2, c2; stage_rc((wid * 64 + lane_id()) * 16, r2, c2); const int rb2 = Epi::PERM ? ((r2 & ~31) + perm32(r2 & 31)) : r2;
;             nvA = (unsigned)(r2 * nlda + c2) * 2u; nvB = (unsigned)(rb2 * nldb + c2) * 2u; }
;         const unsigned nqA = (unsigned)nlda * 128u, nqB = (unsigned)nldb * 128u;
;         const int nt = cur.K / BK;
.LBB0_206:
	v_and_b32_e32 v1, 15, v0
	v_or_b32_e32 v2, s50, v1
	v_ashrrev_i32_e32 v3, 6, v0
	v_lshlrev_b32_e32 v4, 6, v2
	v_and_b32_e32 v5, 48, v0
	s_movk_i32 s57, 0x3c0
	v_lshlrev_b32_e32 v2, 2, v2
	v_and_or_b32 v4, v4, s57, v5
	v_lshl_add_u32 v6, v3, 10, s51
	v_and_b32_e32 v2, 32, v2
	v_lshlrev_b32_e32 v0, 2, v0
	s_nop 0
	v_bitop3_b32 v32, v4, v6, v2 bitop3:0xde
	v_lshl_or_b32 v1, v1, 6, v5
	v_add_lshl_u32 v2, v3, s53, 10
	v_and_b32_e32 v0, 32, v0
	v_bitop3_b32 v137, v1, v2, v0 bitop3:0xde
	v_mbcnt_lo_u32_b32 v0, -1, 0
	v_mbcnt_hi_u32_b32 v0, -1, v0
	s_mov_b32 s57, 0xfffe0
	v_add_u32_e32 v0, s54, v0
	v_ashrrev_i32_e32 v2, 31, v0
	v_lshrrev_b32_e32 v2, 26, v2
	v_lshlrev_b32_e32 v1, 4, v0
	v_add_u32_e32 v2, v0, v2
	v_bfe_i32 v0, v0, 27, 1
	v_lshrrev_b32_e32 v0, 22, v0
	v_add_u32_e32 v0, v1, v0
	v_and_b32_e32 v0, 0xfffffc00, v0
	v_sub_u32_e32 v0, v1, v0
	v_lshrrev_b32_e32 v1, 4, v0
	v_bitop3_b32 v0, v1, v0, 32 bitop3:0x6c
	v_ashrrev_i32_e32 v3, 31, v0
	v_lshrrev_b32_e32 v3, 26, v3
	v_ashrrev_i32_e32 v2, 6, v2
	v_add_u32_e32 v3, v0, v3
	v_lshlrev_b32_e32 v1, 3, v2
	v_ashrrev_i32_e32 v4, 6, v3
	v_and_b32_e32 v3, 0xc0, v3
	v_and_b32_e32 v1, -16, v1
	v_sub_u32_e32 v0, v0, v3
	v_add_u32_e32 v1, v4, v1
	v_lshlrev_b32_e32 v2, 5, v2
	v_ashrrev_i16_sdwa v0, v205, sext(v0) dst_sel:DWORD dst_unused:UNUSED_PAD src0_sel:DWORD src1_sel:BYTE_0
	v_and_b32_e32 v2, 32, v2
	v_bfe_i32 v0, v0, 0, 16
	v_lshlrev_b32_e32 v3, 1, v1
	v_lshrrev_b32_e32 v5, 2, v1
	v_and_b32_e32 v4, 3, v4
	s_add_i32 s59, 0, 0x10000
	s_add_i32 s61, 0, 0x14000
	v_and_b32_e32 v3, 24, v3
	v_and_b32_e32 v5, 4, v5
	v_and_or_b32 v4, v1, s57, v4
	v_add_lshl_u32 v34, v2, v0, 1
	v_add_u32_e32 v134, s59, v137
	v_add_u32_e32 v135, s61, v137
	v_or3_b32 v33, v4, v5, v3
	v_lshl_add_u32 v128, v1, 12, v34
	ds_read_b128 v[0:3], v134
	ds_read_b128 v[4:7], v134 offset:1024
	ds_read_b128 v[8:11], v134 offset:2048
	ds_read_b128 v[12:15], v134 offset:3072
	ds_read_b128 v[16:19], v135
	ds_read_b128 v[20:23], v135 offset:1024
	ds_read_b128 v[24:27], v135 offset:2048
	ds_read_b128 v[28:31], v135 offset:3072
	v_lshl_add_u32 v129, v33, 12, v34
	v_mov_b32_e32 v133, v185
	v_lshl_add_u64 v[182:183], s[20:21], 0, v[132:133]
	s_add_i32 s57, s7, 0xc000
	v_add_u32_e32 v136, 0, v32
	v_lshl_add_u64 v[64:65], v[182:183], 0, s[80:81]
	s_mov_b32 m0, s57
	s_add_i32 s58, s7, 0xe000
	ds_read_b128 v[32:35], v136
	ds_read_b128 v[36:39], v136 offset:1024
	ds_read_b128 v[40:43], v136 offset:2048
	ds_read_b128 v[44:47], v136 offset:3072
	ds_read_b128 v[48:51], v136 offset:4096
	ds_read_b128 v[52:55], v136 offset:5120
	ds_read_b128 v[56:59], v136 offset:6144
	ds_read_b128 v[60:63], v136 offset:7168
	global_load_lds_dwordx4 v[64:65], off
	v_lshl_add_u64 v[64:65], v[182:183], 0, s[78:79]
	s_mov_b32 m0, s58
	s_nop 0
	global_load_lds_dwordx4 v[64:65], off
	s_waitcnt vmcnt(16)
	s_waitcnt lgkmcnt(0)
	s_barrier
	v_mfma_f32_16x16x32_bf16 v[64:67], v[0:3], v[32:35], 0
	v_mfma_f32_16x16x32_bf16 v[68:71], v[8:11], v[32:35], 0
	v_mfma_f32_16x16x32_bf16 v[72:75], v[0:3], v[40:43], 0
	v_mfma_f32_16x16x32_bf16 v[76:79], v[8:11], v[40:43], 0
	v_mfma_f32_16x16x32_bf16 v[80:83], v[0:3], v[48:51], 0
	v_mfma_f32_16x16x32_bf16 v[84:87], v[8:11], v[48:51], 0
	v_mfma_f32_16x16x32_bf16 v[88:91], v[0:3], v[56:59], 0
	v_mfma_f32_16x16x32_bf16 v[92:95], v[8:11], v[56:59], 0
	v_mfma_f32_16x16x32_bf16 v[64:67], v[4:7], v[36:39], v[64:67]
	v_mfma_f32_16x16x32_bf16 v[68:71], v[12:15], v[36:39], v[68:71]
	v_mfma_f32_16x16x32_bf16 v[72:75], v[4:7], v[44:47], v[72:75]
	v_mfma_f32_16x16x32_bf16 v[76:79], v[12:15], v[44:47], v[76:79]
	v_mfma_f32_16x16x32_bf16 v[80:83], v[4:7], v[52:55], v[80:83]
	v_mfma_f32_16x16x32_bf16 v[84:87], v[12:15], v[52:55], v[84:87]
	v_mfma_f32_16x16x32_bf16 v[88:91], v[4:7], v[60:63], v[88:91]
	v_mfma_f32_16x16x32_bf16 v[100:103], v[12:15], v[60:63], v[92:95]
	v_mfma_f32_16x16x32_bf16 v[92:95], v[16:19], v[32:35], 0
	v_mfma_f32_16x16x32_bf16 v[32:35], v[24:27], v[32:35], 0
	v_mfma_f32_16x16x32_bf16 v[104:107], v[20:23], v[36:39], v[92:95]
	v_mfma_f32_16x16x32_bf16 v[32:35], v[28:31], v[36:39], v[32:35]
	v_mfma_f32_16x16x32_bf16 v[36:39], v[16:19], v[40:43], 0
	v_mfma_f32_16x16x32_bf16 v[40:43], v[24:27], v[40:43], 0
	v_mfma_f32_16x16x32_bf16 v[36:39], v[20:23], v[44:47], v[36:39]
	v_mfma_f32_16x16x32_bf16 v[40:43], v[28:31], v[44:47], v[40:43]
	v_mfma_f32_16x16x32_bf16 v[44:47], v[16:19], v[48:51], 0
	v_mfma_f32_16x16x32_bf16 v[48:51], v[24:27], v[48:51], 0
	v_mfma_f32_16x16x32_bf16 v[44:47], v[20:23], v[52:55], v[44:47]
	v_mfma_f32_16x16x32_bf16 v[48:51], v[28:31], v[52:55], v[48:51]
	v_mfma_f32_16x16x32_bf16 v[52:55], v[16:19], v[56:59], 0
	v_mfma_f32_16x16x32_bf16 v[56:59], v[24:27], v[56:59], 0
	v_mfma_f32_16x16x32_bf16 v[52:55], v[20:23], v[60:63], v[52:55]
	v_mfma_f32_16x16x32_bf16 v[56:59], v[28:31], v[60:63], v[56:59]
	s_barrier
	v_mov_b32_e32 v131, v185
	v_lshl_add_u64 v[248:249], s[22:23], 0, v[130:131]
	s_mov_b64 s[64:65], 0x100
	s_add_i32 s59, s59, s30
	v_lshl_add_u64 v[138:139], v[248:249], 0, s[64:65]
	s_mov_b32 m0, s59
	s_mov_b64 s[66:67], 0x40100
	s_add_i32 s60, s59, 0x2000
	ds_read_b128 v[60:63], v136 offset:16384
	ds_read_b128 v[92:95], v136 offset:17408
	ds_read_b128 v[96:99], v136 offset:18432
	ds_read_b128 v[108:111], v136 offset:19456
	ds_read_b128 v[112:115], v136 offset:20480
	ds_read_b128 v[116:119], v136 offset:21504
	ds_read_b128 v[120:123], v136 offset:22528
	ds_read_b128 v[124:127], v136 offset:23552
	global_load_lds_dwordx4 v[138:139], off
	v_lshl_add_u64 v[138:139], v[248:249], 0, s[66:67]
	s_mov_b32 m0, s60
	s_mov_b64 s[70:71], 0x80100
	s_add_i32 s61, s61, s30
	global_load_lds_dwordx4 v[138:139], off
	v_lshl_add_u64 v[138:139], v[248:249], 0, s[70:71]
	s_mov_b32 m0, s61
	s_mov_b64 s[72:73], 0xc0100
	s_add_i32 s62, s61, 0x2000
	global_load_lds_dwordx4 v[138:139], off
	v_lshl_add_u64 v[138:139], v[248:249], 0, s[72:73]
	s_mov_b32 m0, s62
	s_nop 0
	global_load_lds_dwordx4 v[138:139], off
	v_lshl_add_u64 v[138:139], v[182:183], 0, s[64:65]
	s_mov_b32 m0, s7
	s_nop 0
	global_load_lds_dwordx4 v[138:139], off
	v_lshl_add_u64 v[138:139], v[182:183], 0, s[66:67]
	s_mov_b32 m0, s31
	s_nop 0
	global_load_lds_dwordx4 v[138:139], off
	s_waitcnt vmcnt(16)
	s_waitcnt lgkmcnt(0)
	s_barrier
	v_mfma_f32_16x16x32_bf16 v[138:141], v[0:3], v[60:63], 0
	v_mfma_f32_16x16x32_bf16 v[146:149], v[0:3], v[96:99], 0
	v_mfma_f32_16x16x32_bf16 v[154:157], v[0:3], v[112:115], 0
	v_mfma_f32_16x16x32_bf16 v[0:3], v[0:3], v[120:123], 0
	v_mfma_f32_16x16x32_bf16 v[138:141], v[4:7], v[92:95], v[138:141]
	v_mfma_f32_16x16x32_bf16 v[146:149], v[4:7], v[108:111], v[146:149]
	v_mfma_f32_16x16x32_bf16 v[154:157], v[4:7], v[116:119], v[154:157]
	v_mfma_f32_16x16x32_bf16 v[0:3], v[4:7], v[124:127], v[0:3]
	v_mfma_f32_16x16x32_bf16 v[4:7], v[8:11], v[120:123], 0
	v_mfma_f32_16x16x32_bf16 v[142:145], v[8:11], v[60:63], 0
	v_mfma_f32_16x16x32_bf16 v[150:153], v[8:11], v[96:99], 0
	v_mfma_f32_16x16x32_bf16 v[158:161], v[8:11], v[112:115], 0
	v_mfma_f32_16x16x32_bf16 v[4:7], v[12:15], v[124:127], v[4:7]
	v_mfma_f32_16x16x32_bf16 v[142:145], v[12:15], v[92:95], v[142:145]
	v_mfma_f32_16x16x32_bf16 v[150:153], v[12:15], v[108:111], v[150:153]
	v_mfma_f32_16x16x32_bf16 v[158:161], v[12:15], v[116:119], v[158:161]
	v_mfma_f32_16x16x32_bf16 v[12:15], v[24:27], v[60:63], 0
	v_mfma_f32_16x16x32_bf16 v[162:165], v[28:31], v[92:95], v[12:15]
	v_mfma_f32_16x16x32_bf16 v[12:15], v[16:19], v[96:99], 0
	v_mfma_f32_16x16x32_bf16 v[166:169], v[20:23], v[108:111], v[12:15]
	v_mfma_f32_16x16x32_bf16 v[12:15], v[24:27], v[96:99], 0
	v_mfma_f32_16x16x32_bf16 v[170:173], v[28:31], v[108:111], v[12:15]
	v_mfma_f32_16x16x32_bf16 v[12:15], v[16:19], v[112:115], 0
	v_mfma_f32_16x16x32_bf16 v[174:177], v[20:23], v[116:119], v[12:15]
	v_mfma_f32_16x16x32_bf16 v[12:15], v[24:27], v[112:115], 0
	v_mfma_f32_16x16x32_bf16 v[8:11], v[16:19], v[60:63], 0
	v_mfma_f32_16x16x32_bf16 v[178:181], v[28:31], v[116:119], v[12:15]
	v_mfma_f32_16x16x32_bf16 v[12:15], v[16:19], v[120:123], 0
	v_mfma_f32_16x16x32_bf16 v[8:11], v[20:23], v[92:95], v[8:11]
	v_mfma_f32_16x16x32_bf16 v[188:191], v[20:23], v[124:127], v[12:15]
	v_mfma_f32_16x16x32_bf16 v[12:15], v[24:27], v[120:123], 0
	v_mfma_f32_16x16x32_bf16 v[192:195], v[28:31], v[124:127], v[12:15]
	s_barrier
	s_add_i32 s63, 0, 0x18000
	s_add_i32 s65, 0, 0x1c000
	v_add_u32_e32 v131, s63, v137
	v_add_u32_e32 v137, s65, v137
	s_nop 0
	ds_read_b128 v[12:15], v131
	ds_read_b128 v[20:23], v131 offset:1024
	ds_read_b128 v[24:27], v131 offset:2048
	ds_read_b128 v[196:199], v131 offset:3072
	ds_read_b128 v[200:203], v137
	ds_read_b128 v[212:215], v137 offset:1024
	ds_read_b128 v[216:219], v137 offset:2048
	ds_read_b128 v[220:223], v137 offset:3072
	s_mov_b32 m0, s34
	v_lshl_add_u64 v[92:93], v[182:183], 0, s[70:71]
	ds_read_b128 v[16:19], v136 offset:32768
	ds_read_b128 v[28:31], v136 offset:33792
	ds_read_b128 v[60:63], v136 offset:34816
	ds_read_b128 v[224:227], v136 offset:35840
	ds_read_b128 v[228:231], v136 offset:36864
	ds_read_b128 v[232:235], v136 offset:37888
	ds_read_b128 v[236:239], v136 offset:38912
	ds_read_b128 v[240:243], v136 offset:39936
	global_load_lds_dwordx4 v[92:93], off
	v_lshl_add_u64 v[92:93], v[182:183], 0, s[72:73]
	s_mov_b32 m0, s35
	s_nop 0
	global_load_lds_dwordx4 v[92:93], off
	s_waitcnt vmcnt(8)
	s_waitcnt lgkmcnt(0)
	s_barrier
	v_mfma_f32_16x16x32_bf16 v[64:67], v[12:15], v[16:19], v[64:67]
	v_mfma_f32_16x16x32_bf16 v[124:127], v[20:23], v[28:31], v[64:67]
	v_mfma_f32_16x16x32_bf16 v[64:67], v[24:27], v[16:19], v[68:71]
	v_mfma_f32_16x16x32_bf16 v[112:115], v[196:199], v[28:31], v[64:67]
	v_mfma_f32_16x16x32_bf16 v[64:67], v[12:15], v[60:63], v[72:75]
	v_mfma_f32_16x16x32_bf16 v[108:111], v[20:23], v[224:227], v[64:67]
	v_mfma_f32_16x16x32_bf16 v[64:67], v[24:27], v[60:63], v[76:79]
	v_mfma_f32_16x16x32_bf16 v[96:99], v[196:199], v[224:227], v[64:67]
	v_mfma_f32_16x16x32_bf16 v[64:67], v[12:15], v[228:231], v[80:83]
	v_mfma_f32_16x16x32_bf16 v[92:95], v[20:23], v[232:235], v[64:67]
	v_mfma_f32_16x16x32_bf16 v[64:67], v[24:27], v[228:231], v[84:87]
	v_mfma_f32_16x16x32_bf16 v[80:83], v[196:199], v[232:235], v[64:67]
	v_mfma_f32_16x16x32_bf16 v[64:67], v[12:15], v[236:239], v[88:91]
	v_mfma_f32_16x16x32_bf16 v[76:79], v[20:23], v[240:243], v[64:67]
	v_mfma_f32_16x16x32_bf16 v[64:67], v[24:27], v[236:239], v[100:103]
	v_mfma_f32_16x16x32_bf16 v[64:67], v[196:199], v[240:243], v[64:67]
	v_mfma_f32_16x16x32_bf16 v[68:71], v[200:203], v[16:19], v[104:107]
	v_mfma_f32_16x16x32_bf16 v[16:19], v[216:219], v[16:19], v[32:35]
	v_mfma_f32_16x16x32_bf16 v[116:119], v[220:223], v[28:31], v[16:19]
	v_mfma_f32_16x16x32_bf16 v[16:19], v[200:203], v[60:63], v[36:39]
	v_mfma_f32_16x16x32_bf16 v[104:107], v[212:215], v[224:227], v[16:19]
	v_mfma_f32_16x16x32_bf16 v[16:19], v[216:219], v[60:63], v[40:43]
	v_mfma_f32_16x16x32_bf16 v[100:103], v[220:223], v[224:227], v[16:19]
	v_mfma_f32_16x16x32_bf16 v[16:19], v[200:203], v[228:231], v[44:47]
	v_mfma_f32_16x16x32_bf16 v[88:91], v[212:215], v[232:235], v[16:19]
	v_mfma_f32_16x16x32_bf16 v[16:19], v[216:219], v[228:231], v[48:51]
	v_mfma_f32_16x16x32_bf16 v[84:87], v[220:223], v[232:235], v[16:19]
	v_mfma_f32_16x16x32_bf16 v[16:19], v[200:203], v[236:239], v[52:55]
	v_mfma_f32_16x16x32_bf16 v[72:75], v[212:215], v[240:243], v[16:19]
	v_mfma_f32_16x16x32_bf16 v[16:19], v[216:219], v[236:239], v[56:59]
	v_mfma_f32_16x16x32_bf16 v[120:123], v[212:215], v[28:31], v[68:71]
	v_mfma_f32_16x16x32_bf16 v[68:71], v[220:223], v[240:243], v[16:19]
	s_barrier
; #define PG8_WAIT_V(n) asm volatile("s_waitcnt vmcnt(" #n ")" ::: "memory")
; #define PG8_WAIT_VP() asm volatile("s_waitcnt vmcnt(%0)" :: "n"(8 + Epi::NST) : "memory")
; template <class Epi, class Sched>
; __device__ __forceinline__ void gemm_phase(PG8_LAS unsigned char* lds, const Sched& S, const Epi& E, int tid_in) {
;     ...
;         { const int t = 0; PG8_KITER(PG8_WAIT_VP()); }
;         for (int t = 2; t < nt; t += 2) PG8_KITER(PG8_WAIT_V(8));
	s_mov_b64 s[70:71], 0x180
	s_add_i32 s63, s63, s30
	s_nop 1
	v_lshl_add_u64 v[16:17], v[248:249], 0, s[70:71]
	s_mov_b32 m0, s63
	s_mov_b64 s[72:73], 0x40180
	s_add_i32 s64, s63, 0x2000
	ds_read_b128 v[36:39], v136 offset:49152
	ds_read_b128 v[40:43], v136 offset:50176
	ds_read_b128 v[224:227], v136 offset:51200
	ds_read_b128 v[228:231], v136 offset:52224
	ds_read_b128 v[232:235], v136 offset:53248
	ds_read_b128 v[236:239], v136 offset:54272
	ds_read_b128 v[240:243], v136 offset:55296
	ds_read_b128 v[244:247], v136 offset:56320
	global_load_lds_dwordx4 v[16:17], off
	v_lshl_add_u64 v[16:17], v[248:249], 0, s[72:73]
	s_mov_b32 m0, s64
	s_add_i32 s65, s65, s30
	global_load_lds_dwordx4 v[16:17], off
	v_lshl_add_u64 v[16:17], v[248:249], 0, s[92:93]
	s_mov_b32 m0, s65
	s_add_i32 s66, s65, 0x2000
	global_load_lds_dwordx4 v[16:17], off
	v_lshl_add_u64 v[16:17], v[248:249], 0, vcc
	s_mov_b32 m0, s66
	s_nop 0
	global_load_lds_dwordx4 v[16:17], off
	v_lshl_add_u64 v[16:17], v[182:183], 0, s[70:71]
	s_mov_b32 m0, s48
	s_nop 0
	global_load_lds_dwordx4 v[16:17], off
	v_lshl_add_u64 v[16:17], v[182:183], 0, s[72:73]
	s_mov_b32 m0, s49
	s_nop 0
	global_load_lds_dwordx4 v[16:17], off
	s_waitcnt vmcnt(8)
	s_waitcnt lgkmcnt(0)
	s_barrier
	v_mfma_f32_16x16x32_bf16 v[16:19], v[12:15], v[36:39], v[138:141]
	v_mfma_f32_16x16x32_bf16 v[60:63], v[20:23], v[40:43], v[16:19]
	v_mfma_f32_16x16x32_bf16 v[16:19], v[24:27], v[36:39], v[142:145]
	v_mfma_f32_16x16x32_bf16 v[48:51], v[196:199], v[40:43], v[16:19]
	v_mfma_f32_16x16x32_bf16 v[16:19], v[12:15], v[224:227], v[146:149]
	v_mfma_f32_16x16x32_bf16 v[44:47], v[20:23], v[228:231], v[16:19]
	v_mfma_f32_16x16x32_bf16 v[16:19], v[24:27], v[224:227], v[150:153]
	v_mfma_f32_16x16x32_bf16 v[32:35], v[196:199], v[228:231], v[16:19]
	v_mfma_f32_16x16x32_bf16 v[16:19], v[12:15], v[232:235], v[154:157]
	v_mfma_f32_16x16x32_bf16 v[0:3], v[12:15], v[240:243], v[0:3]
	v_mfma_f32_16x16x32_bf16 v[28:31], v[20:23], v[236:239], v[16:19]
	v_mfma_f32_16x16x32_bf16 v[16:19], v[24:27], v[232:235], v[158:161]
	v_mfma_f32_16x16x32_bf16 v[12:15], v[20:23], v[244:247], v[0:3]
	v_mfma_f32_16x16x32_bf16 v[0:3], v[24:27], v[240:243], v[4:7]
	v_mfma_f32_16x16x32_bf16 v[16:19], v[196:199], v[236:239], v[16:19]
	v_mfma_f32_16x16x32_bf16 v[0:3], v[196:199], v[244:247], v[0:3]
	v_mfma_f32_16x16x32_bf16 v[4:7], v[200:203], v[36:39], v[8:11]
	v_mfma_f32_16x16x32_bf16 v[56:59], v[212:215], v[40:43], v[4:7]
	v_mfma_f32_16x16x32_bf16 v[4:7], v[216:219], v[36:39], v[162:165]
	v_mfma_f32_16x16x32_bf16 v[52:55], v[220:223], v[40:43], v[4:7]
	v_mfma_f32_16x16x32_bf16 v[4:7], v[200:203], v[224:227], v[166:169]
	v_mfma_f32_16x16x32_bf16 v[40:43], v[212:215], v[228:231], v[4:7]
	v_mfma_f32_16x16x32_bf16 v[4:7], v[216:219], v[224:227], v[170:173]
	v_mfma_f32_16x16x32_bf16 v[36:39], v[220:223], v[228:231], v[4:7]
	v_mfma_f32_16x16x32_bf16 v[4:7], v[200:203], v[232:235], v[174:177]
	v_mfma_f32_16x16x32_bf16 v[24:27], v[212:215], v[236:239], v[4:7]
	v_mfma_f32_16x16x32_bf16 v[4:7], v[216:219], v[232:235], v[178:181]
	v_mfma_f32_16x16x32_bf16 v[20:23], v[220:223], v[236:239], v[4:7]
	v_mfma_f32_16x16x32_bf16 v[4:7], v[200:203], v[240:243], v[188:191]
	v_mfma_f32_16x16x32_bf16 v[8:11], v[212:215], v[244:247], v[4:7]
	v_mfma_f32_16x16x32_bf16 v[4:7], v[216:219], v[240:243], v[192:195]
	v_mfma_f32_16x16x32_bf16 v[4:7], v[220:223], v[244:247], v[4:7]
	s_barrier
	s_add_u32 s20, s20, 0x80180
	s_addc_u32 s21, s21, 0
	s_add_u32 s67, s22, 0x200
	s_addc_u32 s68, s23, 0
	s_mov_b32 s70, 0
.LBB0_207:
	ds_read_b128 v[138:141], v134
	ds_read_b128 v[142:145], v134 offset:1024
	ds_read_b128 v[146:149], v134 offset:2048
	ds_read_b128 v[150:153], v134 offset:3072
	ds_read_b128 v[154:157], v135
	ds_read_b128 v[158:161], v135 offset:1024
	ds_read_b128 v[162:165], v135 offset:2048
	ds_read_b128 v[166:169], v135 offset:3072
	s_add_u32 s71, s20, 0xfff80080
	s_addc_u32 s72, s21, -1
	s_cmp_eq_u32 s70, 28
	s_cselect_b64 vcc, -1, 0
	s_and_b64 s[22:23], vcc, exec
	v_cndmask_b32_e32 v184, v132, v128, vcc
	s_cselect_b32 s23, s15, s72
	s_cselect_b32 s22, s14, s71
	v_cndmask_b32_e32 v182, v130, v129, vcc
	s_cselect_b32 s73, s17, s68
	s_cselect_b32 s72, s16, s67
	s_mov_b32 m0, s57
	v_lshl_add_u64 v[216:217], s[20:21], 0, v[132:133]
	ds_read_b128 v[170:173], v136
	ds_read_b128 v[174:177], v136 offset:1024
	ds_read_b128 v[178:181], v136 offset:2048
	ds_read_b128 v[188:191], v136 offset:3072
	ds_read_b128 v[192:195], v136 offset:4096
	ds_read_b128 v[196:199], v136 offset:5120
	ds_read_b128 v[200:203], v136 offset:6144
	ds_read_b128 v[212:215], v136 offset:7168
	global_load_lds_dwordx4 v[216:217], off
	v_lshl_add_u64 v[216:217], v[216:217], 0, s[88:89]
	s_mov_b32 m0, s58
	s_nop 0
	global_load_lds_dwordx4 v[216:217], off
	s_waitcnt vmcnt(8)
	s_waitcnt lgkmcnt(0)
	s_barrier
	v_mfma_f32_16x16x32_bf16 v[124:127], v[138:141], v[170:173], v[124:127]
	v_mfma_f32_16x16x32_bf16 v[112:115], v[146:149], v[170:173], v[112:115]
	v_mfma_f32_16x16x32_bf16 v[108:111], v[138:141], v[178:181], v[108:111]
	v_mfma_f32_16x16x32_bf16 v[96:99], v[146:149], v[178:181], v[96:99]
	v_mfma_f32_16x16x32_bf16 v[92:95], v[138:141], v[192:195], v[92:95]
	v_mfma_f32_16x16x32_bf16 v[80:83], v[146:149], v[192:195], v[80:83]
	v_mfma_f32_16x16x32_bf16 v[76:79], v[138:141], v[200:203], v[76:79]
	v_mfma_f32_16x16x32_bf16 v[64:67], v[146:149], v[200:203], v[64:67]
	v_mfma_f32_16x16x32_bf16 v[124:127], v[142:145], v[174:177], v[124:127]
	v_mfma_f32_16x16x32_bf16 v[112:115], v[150:153], v[174:177], v[112:115]
	v_mfma_f32_16x16x32_bf16 v[108:111], v[142:145], v[188:191], v[108:111]
	v_mfma_f32_16x16x32_bf16 v[96:99], v[150:153], v[188:191], v[96:99]
	v_mfma_f32_16x16x32_bf16 v[92:95], v[142:145], v[196:199], v[92:95]
	v_mfma_f32_16x16x32_bf16 v[80:83], v[150:153], v[196:199], v[80:83]
	v_mfma_f32_16x16x32_bf16 v[76:79], v[142:145], v[212:215], v[76:79]
	v_mfma_f32_16x16x32_bf16 v[64:67], v[150:153], v[212:215], v[64:67]
	v_mfma_f32_16x16x32_bf16 v[120:123], v[154:157], v[170:173], v[120:123]
	v_mfma_f32_16x16x32_bf16 v[116:119], v[162:165], v[170:173], v[116:119]
	v_mfma_f32_16x16x32_bf16 v[104:107], v[154:157], v[178:181], v[104:107]
	v_mfma_f32_16x16x32_bf16 v[100:103], v[162:165], v[178:181], v[100:103]
	v_mfma_f32_16x16x32_bf16 v[88:91], v[154:157], v[192:195], v[88:91]
	v_mfma_f32_16x16x32_bf16 v[84:87], v[162:165], v[192:195], v[84:87]
	v_mfma_f32_16x16x32_bf16 v[72:75], v[154:157], v[200:203], v[72:75]
	v_mfma_f32_16x16x32_bf16 v[68:71], v[162:165], v[200:203], v[68:71]
	v_mfma_f32_16x16x32_bf16 v[120:123], v[158:161], v[174:177], v[120:123]
	v_mfma_f32_16x16x32_bf16 v[116:119], v[166:169], v[174:177], v[116:119]
	v_mfma_f32_16x16x32_bf16 v[104:107], v[158:161], v[188:191], v[104:107]
	v_mfma_f32_16x16x32_bf16 v[100:103], v[166:169], v[188:191], v[100:103]
	v_mfma_f32_16x16x32_bf16 v[88:91], v[158:161], v[196:199], v[88:91]
	v_mfma_f32_16x16x32_bf16 v[84:87], v[166:169], v[196:199], v[84:87]
	v_mfma_f32_16x16x32_bf16 v[72:75], v[158:161], v[212:215], v[72:75]
	v_mfma_f32_16x16x32_bf16 v[68:71], v[166:169], v[212:215], v[68:71]
	s_barrier
	v_mov_b32_e32 v183, v185
	s_mov_b32 m0, s59
	v_lshl_add_u64 v[216:217], s[72:73], 0, v[182:183]
	ds_read_b128 v[170:173], v136 offset:16384
	ds_read_b128 v[174:177], v136 offset:17408
	ds_read_b128 v[178:181], v136 offset:18432
	ds_read_b128 v[188:191], v136 offset:19456
	ds_read_b128 v[192:195], v136 offset:20480
	ds_read_b128 v[196:199], v136 offset:21504
	ds_read_b128 v[200:203], v136 offset:22528
	ds_read_b128 v[212:215], v136 offset:23552
	global_load_lds_dwordx4 v182, s[72:73]
	v_lshl_add_u64 v[182:183], v[216:217], 0, s[88:89]
	s_mov_b32 m0, s60
	s_nop 0
	global_load_lds_dwordx4 v[182:183], off
	v_lshl_add_u64 v[182:183], v[216:217], 0, s[90:91]
	s_mov_b32 m0, s61
	s_nop 0
	global_load_lds_dwordx4 v[182:183], off
	v_lshl_add_u64 v[182:183], v[216:217], 0, s[96:97]
	s_mov_b32 m0, s62
	s_nop 0
	global_load_lds_dwordx4 v[182:183], off
	v_lshl_add_u64 v[182:183], s[22:23], 0, v[184:185]
	s_mov_b32 m0, s7
	v_lshl_add_u64 v[218:219], v[182:183], 0, s[88:89]
	global_load_lds_dwordx4 v[182:183], off
	s_mov_b32 m0, s31
	s_nop 0
	global_load_lds_dwordx4 v[218:219], off
	s_waitcnt vmcnt(8)
	s_waitcnt lgkmcnt(0)
	s_barrier
	v_mfma_f32_16x16x32_bf16 v[60:63], v[138:141], v[170:173], v[60:63]
	v_mfma_f32_16x16x32_bf16 v[48:51], v[146:149], v[170:173], v[48:51]
	v_mfma_f32_16x16x32_bf16 v[44:47], v[138:141], v[178:181], v[44:47]
	v_mfma_f32_16x16x32_bf16 v[32:35], v[146:149], v[178:181], v[32:35]
	v_mfma_f32_16x16x32_bf16 v[28:31], v[138:141], v[192:195], v[28:31]
	v_mfma_f32_16x16x32_bf16 v[16:19], v[146:149], v[192:195], v[16:19]
	v_mfma_f32_16x16x32_bf16 v[12:15], v[138:141], v[200:203], v[12:15]
	v_mfma_f32_16x16x32_bf16 v[0:3], v[146:149], v[200:203], v[0:3]
	v_mfma_f32_16x16x32_bf16 v[60:63], v[142:145], v[174:177], v[60:63]
	v_mfma_f32_16x16x32_bf16 v[48:51], v[150:153], v[174:177], v[48:51]
	v_mfma_f32_16x16x32_bf16 v[44:47], v[142:145], v[188:191], v[44:47]
	v_mfma_f32_16x16x32_bf16 v[32:35], v[150:153], v[188:191], v[32:35]
	v_mfma_f32_16x16x32_bf16 v[28:31], v[142:145], v[196:199], v[28:31]
	v_mfma_f32_16x16x32_bf16 v[16:19], v[150:153], v[196:199], v[16:19]
	v_mfma_f32_16x16x32_bf16 v[12:15], v[142:145], v[212:215], v[12:15]
	v_mfma_f32_16x16x32_bf16 v[0:3], v[150:153], v[212:215], v[0:3]
	v_mfma_f32_16x16x32_bf16 v[56:59], v[154:157], v[170:173], v[56:59]
	v_mfma_f32_16x16x32_bf16 v[52:55], v[162:165], v[170:173], v[52:55]
	v_mfma_f32_16x16x32_bf16 v[40:43], v[154:157], v[178:181], v[40:43]
	v_mfma_f32_16x16x32_bf16 v[36:39], v[162:165], v[178:181], v[36:39]
	v_mfma_f32_16x16x32_bf16 v[24:27], v[154:157], v[192:195], v[24:27]
	v_mfma_f32_16x16x32_bf16 v[20:23], v[162:165], v[192:195], v[20:23]
	v_mfma_f32_16x16x32_bf16 v[8:11], v[154:157], v[200:203], v[8:11]
	v_mfma_f32_16x16x32_bf16 v[4:7], v[162:165], v[200:203], v[4:7]
	v_mfma_f32_16x16x32_bf16 v[56:59], v[158:161], v[174:177], v[56:59]
	v_mfma_f32_16x16x32_bf16 v[52:55], v[166:169], v[174:177], v[52:55]
	v_mfma_f32_16x16x32_bf16 v[40:43], v[158:161], v[188:191], v[40:43]
	v_mfma_f32_16x16x32_bf16 v[36:39], v[166:169], v[188:191], v[36:39]
	v_mfma_f32_16x16x32_bf16 v[24:27], v[158:161], v[196:199], v[24:27]
	v_mfma_f32_16x16x32_bf16 v[20:23], v[166:169], v[196:199], v[20:23]
	v_mfma_f32_16x16x32_bf16 v[8:11], v[158:161], v[212:215], v[8:11]
	v_mfma_f32_16x16x32_bf16 v[4:7], v[166:169], v[212:215], v[4:7]
	s_barrier
; #define PG8_WAIT_V(n) asm volatile("s_waitcnt vmcnt(" #n ")" ::: "memory")
; #define PG8_WAIT_VP() asm volatile("s_waitcnt vmcnt(%0)" :: "n"(8 + Epi::NST) : "memory")
; #define PG8_BAR __builtin_amdgcn_s_barrier()
; template <class Epi, class Sched>
; __device__ __forceinline__ void gemm_phase(PG8_LAS unsigned char* lds, const Sched& S, const Epi& E, int tid_in) {
;     ...
;         { const int t = 0; PG8_KITER(PG8_WAIT_VP()); }
;         for (int t = 2; t < nt; t += 2) PG8_KITER(PG8_WAIT_V(8));
;     ...
;         if (wr == 0) PG8_BAR;
	ds_read_b128 v[138:141], v131
	ds_read_b128 v[142:145], v131 offset:1024
	ds_read_b128 v[146:149], v131 offset:2048
	ds_read_b128 v[150:153], v131 offset:3072
	ds_read_b128 v[154:157], v137
	ds_read_b128 v[158:161], v137 offset:1024
	ds_read_b128 v[162:165], v137 offset:2048
	ds_read_b128 v[166:169], v137 offset:3072
	s_mov_b32 m0, s34
	v_lshl_add_u64 v[218:219], v[182:183], 0, s[90:91]
	ds_read_b128 v[170:173], v136 offset:32768
	ds_read_b128 v[174:177], v136 offset:33792
	ds_read_b128 v[178:181], v136 offset:34816
	ds_read_b128 v[188:191], v136 offset:35840
	ds_read_b128 v[192:195], v136 offset:36864
	ds_read_b128 v[196:199], v136 offset:37888
	ds_read_b128 v[200:203], v136 offset:38912
	ds_read_b128 v[212:215], v136 offset:39936
	global_load_lds_dwordx4 v[218:219], off
	v_lshl_add_u64 v[218:219], v[182:183], 0, s[96:97]
	s_mov_b32 m0, s35
	s_nop 0
	global_load_lds_dwordx4 v[218:219], off
	s_waitcnt vmcnt(8)
	s_waitcnt lgkmcnt(0)
	s_barrier
	v_mfma_f32_16x16x32_bf16 v[124:127], v[138:141], v[170:173], v[124:127]
	v_mfma_f32_16x16x32_bf16 v[112:115], v[146:149], v[170:173], v[112:115]
	v_mfma_f32_16x16x32_bf16 v[108:111], v[138:141], v[178:181], v[108:111]
	v_mfma_f32_16x16x32_bf16 v[96:99], v[146:149], v[178:181], v[96:99]
	v_mfma_f32_16x16x32_bf16 v[92:95], v[138:141], v[192:195], v[92:95]
	v_mfma_f32_16x16x32_bf16 v[80:83], v[146:149], v[192:195], v[80:83]
	v_mfma_f32_16x16x32_bf16 v[76:79], v[138:141], v[200:203], v[76:79]
	v_mfma_f32_16x16x32_bf16 v[64:67], v[146:149], v[200:203], v[64:67]
	v_mfma_f32_16x16x32_bf16 v[124:127], v[142:145], v[174:177], v[124:127]
	v_mfma_f32_16x16x32_bf16 v[112:115], v[150:153], v[174:177], v[112:115]
	v_mfma_f32_16x16x32_bf16 v[108:111], v[142:145], v[188:191], v[108:111]
	v_mfma_f32_16x16x32_bf16 v[96:99], v[150:153], v[188:191], v[96:99]
	v_mfma_f32_16x16x32_bf16 v[92:95], v[142:145], v[196:199], v[92:95]
	v_mfma_f32_16x16x32_bf16 v[80:83], v[150:153], v[196:199], v[80:83]
	v_mfma_f32_16x16x32_bf16 v[76:79], v[142:145], v[212:215], v[76:79]
	v_mfma_f32_16x16x32_bf16 v[64:67], v[150:153], v[212:215], v[64:67]
	v_mfma_f32_16x16x32_bf16 v[120:123], v[154:157], v[170:173], v[120:123]
	v_mfma_f32_16x16x32_bf16 v[116:119], v[162:165], v[170:173], v[116:119]
	v_mfma_f32_16x16x32_bf16 v[104:107], v[154:157], v[178:181], v[104:107]
	v_mfma_f32_16x16x32_bf16 v[100:103], v[162:165], v[178:181], v[100:103]
	v_mfma_f32_16x16x32_bf16 v[88:91], v[154:157], v[192:195], v[88:91]
	v_mfma_f32_16x16x32_bf16 v[84:87], v[162:165], v[192:195], v[84:87]
	v_mfma_f32_16x16x32_bf16 v[72:75], v[154:157], v[200:203], v[72:75]
	v_mfma_f32_16x16x32_bf16 v[68:71], v[162:165], v[200:203], v[68:71]
	v_mfma_f32_16x16x32_bf16 v[120:123], v[158:161], v[174:177], v[120:123]
	v_mfma_f32_16x16x32_bf16 v[116:119], v[166:169], v[174:177], v[116:119]
	v_mfma_f32_16x16x32_bf16 v[104:107], v[158:161], v[188:191], v[104:107]
	v_mfma_f32_16x16x32_bf16 v[100:103], v[166:169], v[188:191], v[100:103]
	v_mfma_f32_16x16x32_bf16 v[88:91], v[158:161], v[196:199], v[88:91]
	v_mfma_f32_16x16x32_bf16 v[84:87], v[166:169], v[196:199], v[84:87]
	v_mfma_f32_16x16x32_bf16 v[72:75], v[158:161], v[212:215], v[72:75]
	v_mfma_f32_16x16x32_bf16 v[68:71], v[166:169], v[212:215], v[68:71]
	s_barrier
	s_mov_b32 m0, s63
	v_lshl_add_u64 v[218:219], v[216:217], 0, s[84:85]
	ds_read_b128 v[170:173], v136 offset:49152
	ds_read_b128 v[174:177], v136 offset:50176
	ds_read_b128 v[178:181], v136 offset:51200
	ds_read_b128 v[188:191], v136 offset:52224
	ds_read_b128 v[192:195], v136 offset:53248
	ds_read_b128 v[196:199], v136 offset:54272
	ds_read_b128 v[200:203], v136 offset:55296
	ds_read_b128 v[212:215], v136 offset:56320
	global_load_lds_dwordx4 v[218:219], off
	v_lshl_add_u64 v[218:219], v[216:217], 0, s[94:95]
	s_mov_b32 m0, s64
	s_nop 0
	global_load_lds_dwordx4 v[218:219], off
	v_lshl_add_u64 v[218:219], v[216:217], 0, s[80:81]
	s_mov_b32 m0, s65
	v_lshl_add_u64 v[216:217], v[216:217], 0, s[78:79]
	global_load_lds_dwordx4 v[218:219], off
	s_mov_b32 m0, s66
	s_nop 0
	global_load_lds_dwordx4 v[216:217], off
	v_lshl_add_u64 v[216:217], v[182:183], 0, s[84:85]
	s_mov_b32 m0, s48
	v_lshl_add_u64 v[182:183], v[182:183], 0, s[94:95]
	global_load_lds_dwordx4 v[216:217], off
	s_mov_b32 m0, s49
	s_nop 0
	global_load_lds_dwordx4 v[182:183], off
	s_waitcnt vmcnt(8)
	s_waitcnt lgkmcnt(0)
	s_barrier
	v_mfma_f32_16x16x32_bf16 v[60:63], v[138:141], v[170:173], v[60:63]
	v_mfma_f32_16x16x32_bf16 v[48:51], v[146:149], v[170:173], v[48:51]
	v_mfma_f32_16x16x32_bf16 v[44:47], v[138:141], v[178:181], v[44:47]
	v_mfma_f32_16x16x32_bf16 v[32:35], v[146:149], v[178:181], v[32:35]
	v_mfma_f32_16x16x32_bf16 v[28:31], v[138:141], v[192:195], v[28:31]
	v_mfma_f32_16x16x32_bf16 v[16:19], v[146:149], v[192:195], v[16:19]
	v_mfma_f32_16x16x32_bf16 v[12:15], v[138:141], v[200:203], v[12:15]
	v_mfma_f32_16x16x32_bf16 v[0:3], v[146:149], v[200:203], v[0:3]
	v_mfma_f32_16x16x32_bf16 v[60:63], v[142:145], v[174:177], v[60:63]
	v_mfma_f32_16x16x32_bf16 v[48:51], v[150:153], v[174:177], v[48:51]
	v_mfma_f32_16x16x32_bf16 v[44:47], v[142:145], v[188:191], v[44:47]
	v_mfma_f32_16x16x32_bf16 v[32:35], v[150:153], v[188:191], v[32:35]
	v_mfma_f32_16x16x32_bf16 v[28:31], v[142:145], v[196:199], v[28:31]
	v_mfma_f32_16x16x32_bf16 v[16:19], v[150:153], v[196:199], v[16:19]
	v_mfma_f32_16x16x32_bf16 v[12:15], v[142:145], v[212:215], v[12:15]
	v_mfma_f32_16x16x32_bf16 v[0:3], v[150:153], v[212:215], v[0:3]
	v_mfma_f32_16x16x32_bf16 v[56:59], v[154:157], v[170:173], v[56:59]
	v_mfma_f32_16x16x32_bf16 v[52:55], v[162:165], v[170:173], v[52:55]
	v_mfma_f32_16x16x32_bf16 v[40:43], v[154:157], v[178:181], v[40:43]
	v_mfma_f32_16x16x32_bf16 v[36:39], v[162:165], v[178:181], v[36:39]
	v_mfma_f32_16x16x32_bf16 v[24:27], v[154:157], v[192:195], v[24:27]
	v_mfma_f32_16x16x32_bf16 v[20:23], v[162:165], v[192:195], v[20:23]
	v_mfma_f32_16x16x32_bf16 v[8:11], v[154:157], v[200:203], v[8:11]
	v_mfma_f32_16x16x32_bf16 v[4:7], v[162:165], v[200:203], v[4:7]
	v_mfma_f32_16x16x32_bf16 v[56:59], v[158:161], v[174:177], v[56:59]
	v_mfma_f32_16x16x32_bf16 v[52:55], v[166:169], v[174:177], v[52:55]
	v_mfma_f32_16x16x32_bf16 v[40:43], v[158:161], v[188:191], v[40:43]
	v_mfma_f32_16x16x32_bf16 v[36:39], v[166:169], v[188:191], v[36:39]
	v_mfma_f32_16x16x32_bf16 v[24:27], v[158:161], v[196:199], v[24:27]
	v_mfma_f32_16x16x32_bf16 v[20:23], v[166:169], v[196:199], v[20:23]
	v_mfma_f32_16x16x32_bf16 v[8:11], v[158:161], v[212:215], v[8:11]
	v_mfma_f32_16x16x32_bf16 v[4:7], v[166:169], v[212:215], v[4:7]
	s_barrier
	s_add_i32 s70, s70, 2
	s_add_u32 s20, s20, 0x100
	s_addc_u32 s21, s21, 0
	s_add_u32 s67, s67, 0x100
	s_addc_u32 s68, s68, 0
	s_cmp_gt_u32 s70, 29
	s_cbranch_scc0 .LBB0_207
	s_and_b64 vcc, exec, s[12:13]
	s_cbranch_vccz .LBB0_210
	s_barrier

; __device__ __forceinline__ int lane_id() { int l; asm volatile("v_mbcnt_lo_u32_b32 %0, -1, 0\n\tv_mbcnt_hi_u32_b32 %0, -1, %0" : "=v"(l)); return l; }
;     __device__ __forceinline__ bool next(int i, UnitG& u) const { if (!P.next(i, u)) return false; u.O = O + ((size_t)u.x0 * 256 * 2048 + (size_t)u.x1 * 256) * 2; u.ldo = 2048; u.kind = 0; return true; }
; template <class Epi, class Sched>
; __device__ __forceinline__ void gemm_phase(PG8_LAS unsigned char* lds, const Sched& S, const Epi& E, int tid_in) {
;     ...
;         int aoff, boff; { const int l3 = lane_id(), fr3 = l3 & 15, fq3 = l3 >> 4; aoff = lds_byte(wr * 64 + fr3, fq3 * 8); boff = lds_byte(wc * 32 + fr3, fq3 * 8); }
;         const bool has_next = S.next(ui + 1, nxt);
;         const char* nA = has_next ? nxt.A : cA; const char* nB = has_next ? nxt.B : cB;
;         const int nlda = has_next ? nxt.lda : cur.lda, nldb = has_next ? nxt.ldb : cur.ldb;
;         unsigned nvA, nvB; { int r2, c2; stage_rc((wid * 64 + lane_id()) * 16, r2, c2); const int rb2 = Epi::PERM ? ((r2 & ~31) + perm32(r2 & 31)) : r2;
;             nvA = (unsigned)(r2 * nlda + c2) * 2u; nvB = (unsigned)(rb2 * nldb + c2) * 2u; }
;         const unsigned nqA = (unsigned)nlda * 128u, nqB = (unsigned)nldb * 128u;
;         const int nt = cur.K / BK;
.LBB0_273:
	v_and_b32_e32 v1, 15, v0
	v_or_b32_e32 v2, s50, v1
	v_ashrrev_i32_e32 v3, 6, v0
	v_lshlrev_b32_e32 v4, 6, v2
	v_and_b32_e32 v5, 48, v0
	s_movk_i32 s57, 0x3c0
	v_lshlrev_b32_e32 v2, 2, v2
	v_and_or_b32 v4, v4, s57, v5
	v_lshl_add_u32 v6, v3, 10, s51
	v_and_b32_e32 v2, 32, v2
	v_lshlrev_b32_e32 v0, 2, v0
	s_nop 0
	v_bitop3_b32 v32, v4, v6, v2 bitop3:0xde
	v_lshl_or_b32 v1, v1, 6, v5
	v_add_lshl_u32 v2, v3, s53, 10
	v_and_b32_e32 v0, 32, v0
	v_bitop3_b32 v119, v1, v2, v0 bitop3:0xde
	v_mbcnt_lo_u32_b32 v0, -1, 0
	v_mbcnt_hi_u32_b32 v0, -1, v0
	s_mov_b32 s57, 0x7fffe0
	v_add_u32_e32 v0, s54, v0
	v_ashrrev_i32_e32 v2, 31, v0
	v_lshrrev_b32_e32 v2, 26, v2
	v_lshlrev_b32_e32 v1, 4, v0
	v_add_u32_e32 v2, v0, v2
	v_bfe_i32 v0, v0, 27, 1
	v_lshrrev_b32_e32 v0, 22, v0
	v_add_u32_e32 v0, v1, v0
	v_and_b32_e32 v0, 0xfffffc00, v0
	v_sub_u32_e32 v0, v1, v0
	v_lshrrev_b32_e32 v1, 4, v0
	v_bitop3_b32 v0, v1, v0, 32 bitop3:0x6c
	v_ashrrev_i32_e32 v3, 31, v0
	v_ashrrev_i32_e32 v2, 6, v2
	v_lshrrev_b32_e32 v3, 26, v3
	v_lshlrev_b32_e32 v1, 3, v2
	v_add_u32_e32 v3, v0, v3
	v_and_b32_e32 v1, -16, v1
	v_ashrrev_i32_e32 v4, 6, v3
	v_add_u32_e32 v33, v4, v1
	v_lshlrev_b32_e32 v1, 5, v2
	v_and_b32_e32 v2, 0xc0, v3
	v_sub_u32_e32 v0, v0, v2
	v_and_b32_e32 v1, 32, v1
	v_ashrrev_i16_sdwa v0, v205, sext(v0) dst_sel:DWORD dst_unused:UNUSED_PAD src0_sel:DWORD src1_sel:BYTE_0
	v_add_u32_sdwa v34, v1, sext(v0) dst_sel:DWORD dst_unused:UNUSED_PAD src0_sel:DWORD src1_sel:WORD_0
	v_lshlrev_b32_e32 v0, 1, v33
	v_lshrrev_b32_e32 v1, 2, v33
	v_and_b32_e32 v2, 3, v4
	s_add_i32 s59, 0, 0x10000
	s_add_i32 s61, 0, 0x14000
	v_and_b32_e32 v0, 24, v0
	v_and_b32_e32 v1, 4, v1
	v_and_or_b32 v2, v33, s57, v2
	v_add_u32_e32 v116, s59, v119
	v_add_u32_e32 v117, s61, v119
	v_or3_b32 v35, v2, v1, v0
	ds_read_b128 v[0:3], v116
	ds_read_b128 v[4:7], v116 offset:1024
	ds_read_b128 v[8:11], v116 offset:2048
	ds_read_b128 v[12:15], v116 offset:3072
	ds_read_b128 v[16:19], v117
	ds_read_b128 v[20:23], v117 offset:1024
	ds_read_b128 v[24:27], v117 offset:2048
	ds_read_b128 v[28:31], v117 offset:3072
	s_movk_i32 s57, 0x1600
	v_mul_lo_u32 v33, v33, s57
	v_add_lshl_u32 v186, v34, v33, 1
	v_mul_u32_u24_e32 v33, 0x1600, v35
	v_add_lshl_u32 v211, v33, v34, 1
	v_mov_b32_e32 v115, v185
	v_lshl_add_u64 v[244:245], s[20:21], 0, v[114:115]
	s_add_i32 s57, s31, 0xc000
	v_add_u32_e32 v118, 0, v32
	v_lshl_add_u64 v[64:65], v[244:245], 0, s[40:41]
	s_mov_b32 m0, s57
	s_add_i32 s58, s31, 0xe000
	ds_read_b128 v[32:35], v118
	ds_read_b128 v[36:39], v118 offset:1024
	ds_read_b128 v[40:43], v118 offset:2048
	ds_read_b128 v[44:47], v118 offset:3072
	ds_read_b128 v[48:51], v118 offset:4096
	ds_read_b128 v[52:55], v118 offset:5120
	ds_read_b128 v[56:59], v118 offset:6144
	ds_read_b128 v[60:63], v118 offset:7168
	global_load_lds_dwordx4 v[64:65], off
	v_lshl_add_u64 v[64:65], v[244:245], 0, s[42:43]
	s_mov_b32 m0, s58
	s_nop 0
	global_load_lds_dwordx4 v[64:65], off
	s_waitcnt vmcnt(24)
	s_waitcnt lgkmcnt(0)
	s_barrier
	v_mfma_f32_16x16x32_bf16 v[88:91], v[0:3], v[56:59], 0
	v_mfma_f32_16x16x32_bf16 v[64:67], v[0:3], v[32:35], 0
	v_mfma_f32_16x16x32_bf16 v[68:71], v[8:11], v[32:35], 0
	v_mfma_f32_16x16x32_bf16 v[72:75], v[0:3], v[40:43], 0
	v_mfma_f32_16x16x32_bf16 v[76:79], v[8:11], v[40:43], 0
	v_mfma_f32_16x16x32_bf16 v[80:83], v[0:3], v[48:51], 0
	v_mfma_f32_16x16x32_bf16 v[84:87], v[8:11], v[48:51], 0
	v_mfma_f32_16x16x32_bf16 v[96:99], v[4:7], v[60:63], v[88:91]
	v_mfma_f32_16x16x32_bf16 v[88:91], v[8:11], v[56:59], 0
	v_mfma_f32_16x16x32_bf16 v[64:67], v[4:7], v[36:39], v[64:67]
	v_mfma_f32_16x16x32_bf16 v[68:71], v[12:15], v[36:39], v[68:71]
	v_mfma_f32_16x16x32_bf16 v[72:75], v[4:7], v[44:47], v[72:75]
	v_mfma_f32_16x16x32_bf16 v[76:79], v[12:15], v[44:47], v[76:79]
	v_mfma_f32_16x16x32_bf16 v[80:83], v[4:7], v[52:55], v[80:83]
	v_mfma_f32_16x16x32_bf16 v[84:87], v[12:15], v[52:55], v[84:87]
	v_mfma_f32_16x16x32_bf16 v[100:103], v[12:15], v[60:63], v[88:91]
	v_mfma_f32_16x16x32_bf16 v[88:91], v[16:19], v[32:35], 0
	v_mfma_f32_16x16x32_bf16 v[32:35], v[24:27], v[32:35], 0
	v_mfma_f32_16x16x32_bf16 v[120:123], v[20:23], v[36:39], v[88:91]
	v_mfma_f32_16x16x32_bf16 v[32:35], v[28:31], v[36:39], v[32:35]
	v_mfma_f32_16x16x32_bf16 v[36:39], v[16:19], v[40:43], 0
	v_mfma_f32_16x16x32_bf16 v[40:43], v[24:27], v[40:43], 0
	v_mfma_f32_16x16x32_bf16 v[36:39], v[20:23], v[44:47], v[36:39]
	v_mfma_f32_16x16x32_bf16 v[40:43], v[28:31], v[44:47], v[40:43]
	v_mfma_f32_16x16x32_bf16 v[44:47], v[16:19], v[48:51], 0
	v_mfma_f32_16x16x32_bf16 v[48:51], v[24:27], v[48:51], 0
	v_mfma_f32_16x16x32_bf16 v[44:47], v[20:23], v[52:55], v[44:47]
	v_mfma_f32_16x16x32_bf16 v[48:51], v[28:31], v[52:55], v[48:51]
	v_mfma_f32_16x16x32_bf16 v[52:55], v[16:19], v[56:59], 0
	v_mfma_f32_16x16x32_bf16 v[56:59], v[24:27], v[56:59], 0
	v_mfma_f32_16x16x32_bf16 v[52:55], v[20:23], v[60:63], v[52:55]
	v_mfma_f32_16x16x32_bf16 v[56:59], v[28:31], v[60:63], v[56:59]
	s_barrier
	v_mov_b32_e32 v113, v185
	v_lshl_add_u64 v[246:247], s[22:23], 0, v[112:113]
	s_mov_b64 s[64:65], 0x100
	s_add_i32 s59, s59, s30
	v_lshl_add_u64 v[136:137], v[246:247], 0, s[64:65]
	s_mov_b32 m0, s59
	s_mov_b64 s[66:67], 0xb0100
	s_add_i32 s60, s59, 0x2000
	ds_read_b128 v[60:63], v118 offset:16384
	ds_read_b128 v[88:91], v118 offset:17408
	ds_read_b128 v[92:95], v118 offset:18432
	ds_read_b128 v[104:107], v118 offset:19456
	ds_read_b128 v[108:111], v118 offset:20480
	ds_read_b128 v[124:127], v118 offset:21504
	ds_read_b128 v[128:131], v118 offset:22528
	ds_read_b128 v[132:135], v118 offset:23552
	global_load_lds_dwordx4 v[136:137], off
	v_lshl_add_u64 v[136:137], v[246:247], 0, s[66:67]
	s_mov_b32 m0, s60
	s_mov_b64 s[70:71], 0x160100
	s_add_i32 s61, s61, s30
	global_load_lds_dwordx4 v[136:137], off
	v_lshl_add_u64 v[136:137], v[246:247], 0, s[70:71]
	s_mov_b32 m0, s61
	s_mov_b64 s[72:73], 0x210100
	s_add_i32 s62, s61, 0x2000
	global_load_lds_dwordx4 v[136:137], off
	v_lshl_add_u64 v[136:137], v[246:247], 0, s[72:73]
	s_mov_b32 m0, s62
	s_nop 0
	global_load_lds_dwordx4 v[136:137], off
	v_lshl_add_u64 v[136:137], v[244:245], 0, s[64:65]
	s_mov_b32 m0, s31
	s_nop 0
	global_load_lds_dwordx4 v[136:137], off
	v_lshl_add_u64 v[136:137], v[244:245], 0, s[66:67]
	s_mov_b32 m0, s35
	s_nop 0
	global_load_lds_dwordx4 v[136:137], off
	s_waitcnt vmcnt(24)
	s_waitcnt lgkmcnt(0)
	s_barrier
	v_mfma_f32_16x16x32_bf16 v[136:139], v[0:3], v[60:63], 0
	v_mfma_f32_16x16x32_bf16 v[144:147], v[0:3], v[92:95], 0
	v_mfma_f32_16x16x32_bf16 v[152:155], v[0:3], v[108:111], 0
	v_mfma_f32_16x16x32_bf16 v[0:3], v[0:3], v[128:131], 0
	v_mfma_f32_16x16x32_bf16 v[136:139], v[4:7], v[88:91], v[136:139]
	v_mfma_f32_16x16x32_bf16 v[144:147], v[4:7], v[104:107], v[144:147]
	v_mfma_f32_16x16x32_bf16 v[152:155], v[4:7], v[124:127], v[152:155]
	v_mfma_f32_16x16x32_bf16 v[0:3], v[4:7], v[132:135], v[0:3]
	v_mfma_f32_16x16x32_bf16 v[4:7], v[8:11], v[128:131], 0
	v_mfma_f32_16x16x32_bf16 v[140:143], v[8:11], v[60:63], 0
	v_mfma_f32_16x16x32_bf16 v[148:151], v[8:11], v[92:95], 0
	v_mfma_f32_16x16x32_bf16 v[156:159], v[8:11], v[108:111], 0
	v_mfma_f32_16x16x32_bf16 v[4:7], v[12:15], v[132:135], v[4:7]
	v_mfma_f32_16x16x32_bf16 v[140:143], v[12:15], v[88:91], v[140:143]
	v_mfma_f32_16x16x32_bf16 v[148:151], v[12:15], v[104:107], v[148:151]
	v_mfma_f32_16x16x32_bf16 v[156:159], v[12:15], v[124:127], v[156:159]
	v_mfma_f32_16x16x32_bf16 v[8:11], v[16:19], v[60:63], 0
	v_mfma_f32_16x16x32_bf16 v[160:163], v[20:23], v[88:91], v[8:11]
	v_mfma_f32_16x16x32_bf16 v[8:11], v[24:27], v[60:63], 0
	v_mfma_f32_16x16x32_bf16 v[180:183], v[28:31], v[88:91], v[8:11]
	v_mfma_f32_16x16x32_bf16 v[8:11], v[16:19], v[92:95], 0
	v_mfma_f32_16x16x32_bf16 v[188:191], v[20:23], v[104:107], v[8:11]
	v_mfma_f32_16x16x32_bf16 v[8:11], v[24:27], v[92:95], 0
	v_mfma_f32_16x16x32_bf16 v[192:195], v[28:31], v[104:107], v[8:11]
	v_mfma_f32_16x16x32_bf16 v[8:11], v[16:19], v[108:111], 0
	v_mfma_f32_16x16x32_bf16 v[196:199], v[20:23], v[124:127], v[8:11]
	v_mfma_f32_16x16x32_bf16 v[8:11], v[24:27], v[108:111], 0
	v_mfma_f32_16x16x32_bf16 v[124:127], v[28:31], v[124:127], v[8:11]
	v_mfma_f32_16x16x32_bf16 v[8:11], v[16:19], v[128:131], 0
	v_mfma_f32_16x16x32_bf16 v[200:203], v[20:23], v[132:135], v[8:11]
	v_mfma_f32_16x16x32_bf16 v[8:11], v[24:27], v[128:131], 0
	v_mfma_f32_16x16x32_bf16 v[128:131], v[28:31], v[132:135], v[8:11]
	s_barrier
	s_add_i32 s63, 0, 0x18000
	s_add_i32 s65, 0, 0x1c000
	v_add_u32_e32 v113, s63, v119
	v_add_u32_e32 v119, s65, v119
	s_nop 0
	ds_read_b128 v[8:11], v113
	ds_read_b128 v[12:15], v113 offset:1024
	ds_read_b128 v[16:19], v113 offset:2048
	ds_read_b128 v[20:23], v113 offset:3072
	ds_read_b128 v[132:135], v119
	ds_read_b128 v[212:215], v119 offset:1024
	ds_read_b128 v[216:219], v119 offset:2048
	ds_read_b128 v[220:223], v119 offset:3072
	s_mov_b32 m0, s48
	v_lshl_add_u64 v[88:89], v[244:245], 0, s[70:71]
	ds_read_b128 v[24:27], v118 offset:32768
	ds_read_b128 v[28:31], v118 offset:33792
	ds_read_b128 v[60:63], v118 offset:34816
	ds_read_b128 v[224:227], v118 offset:35840
	ds_read_b128 v[228:231], v118 offset:36864
	ds_read_b128 v[232:235], v118 offset:37888
	ds_read_b128 v[236:239], v118 offset:38912
	ds_read_b128 v[240:243], v118 offset:39936
	global_load_lds_dwordx4 v[88:89], off
	v_lshl_add_u64 v[88:89], v[244:245], 0, s[72:73]
	s_mov_b32 m0, s49
	s_nop 0
	global_load_lds_dwordx4 v[88:89], off
	s_waitcnt vmcnt(8)
	s_waitcnt lgkmcnt(0)
	s_barrier
	v_mfma_f32_16x16x32_bf16 v[64:67], v[8:11], v[24:27], v[64:67]
	v_mfma_f32_16x16x32_bf16 v[172:175], v[12:15], v[28:31], v[64:67]
	v_mfma_f32_16x16x32_bf16 v[64:67], v[16:19], v[24:27], v[68:71]
	v_mfma_f32_16x16x32_bf16 v[164:167], v[20:23], v[28:31], v[64:67]
	v_mfma_f32_16x16x32_bf16 v[64:67], v[8:11], v[60:63], v[72:75]
	v_mfma_f32_16x16x32_bf16 v[108:111], v[12:15], v[224:227], v[64:67]
	v_mfma_f32_16x16x32_bf16 v[64:67], v[16:19], v[60:63], v[76:79]
	v_mfma_f32_16x16x32_bf16 v[104:107], v[20:23], v[224:227], v[64:67]
	v_mfma_f32_16x16x32_bf16 v[64:67], v[8:11], v[228:231], v[80:83]
	v_mfma_f32_16x16x32_bf16 v[92:95], v[12:15], v[232:235], v[64:67]
	v_mfma_f32_16x16x32_bf16 v[64:67], v[16:19], v[228:231], v[84:87]
	v_mfma_f32_16x16x32_bf16 v[88:91], v[20:23], v[232:235], v[64:67]
	v_mfma_f32_16x16x32_bf16 v[64:67], v[8:11], v[236:239], v[96:99]
	v_mfma_f32_16x16x32_bf16 v[76:79], v[12:15], v[240:243], v[64:67]
	v_mfma_f32_16x16x32_bf16 v[64:67], v[16:19], v[236:239], v[100:103]
	v_mfma_f32_16x16x32_bf16 v[68:71], v[20:23], v[240:243], v[64:67]
	v_mfma_f32_16x16x32_bf16 v[64:67], v[132:135], v[24:27], v[120:123]
	v_mfma_f32_16x16x32_bf16 v[24:27], v[216:219], v[24:27], v[32:35]
	v_mfma_f32_16x16x32_bf16 v[168:171], v[220:223], v[28:31], v[24:27]
	v_mfma_f32_16x16x32_bf16 v[24:27], v[132:135], v[60:63], v[36:39]
	v_mfma_f32_16x16x32_bf16 v[100:103], v[212:215], v[224:227], v[24:27]
	v_mfma_f32_16x16x32_bf16 v[24:27], v[216:219], v[60:63], v[40:43]
	v_mfma_f32_16x16x32_bf16 v[96:99], v[220:223], v[224:227], v[24:27]
	v_mfma_f32_16x16x32_bf16 v[24:27], v[132:135], v[228:231], v[44:47]
	v_mfma_f32_16x16x32_bf16 v[84:87], v[212:215], v[232:235], v[24:27]
	v_mfma_f32_16x16x32_bf16 v[24:27], v[216:219], v[228:231], v[48:51]
	v_mfma_f32_16x16x32_bf16 v[80:83], v[220:223], v[232:235], v[24:27]
	v_mfma_f32_16x16x32_bf16 v[24:27], v[132:135], v[236:239], v[52:55]
	v_mfma_f32_16x16x32_bf16 v[176:179], v[212:215], v[28:31], v[64:67]
	v_mfma_f32_16x16x32_bf16 v[64:67], v[212:215], v[240:243], v[24:27]
	v_mfma_f32_16x16x32_bf16 v[24:27], v[216:219], v[236:239], v[56:59]
	v_mfma_f32_16x16x32_bf16 v[52:55], v[220:223], v[240:243], v[24:27]
	s_barrier
; #define PG8_WAIT_V(n) asm volatile("s_waitcnt vmcnt(" #n ")" ::: "memory")
; #define PG8_WAIT_VP() asm volatile("s_waitcnt vmcnt(%0)" :: "n"(8 + Epi::NST) : "memory")
; template <class Epi, class Sched>
; __device__ __forceinline__ void gemm_phase(PG8_LAS unsigned char* lds, const Sched& S, const Epi& E, int tid_in) {
;     ...
;         { const int t = 0; PG8_KITER(PG8_WAIT_VP()); }
;         for (int t = 2; t < nt; t += 2) PG8_KITER(PG8_WAIT_V(8));
	s_mov_b64 s[70:71], 0x180
	s_add_i32 s63, s63, s30
	s_nop 2
	v_lshl_add_u64 v[24:25], v[246:247], 0, s[70:71]
	s_mov_b32 m0, s63
	s_mov_b64 s[72:73], 0xb0180
	s_add_i32 s64, s63, 0x2000
	ds_read_b128 v[32:35], v118 offset:49152
	ds_read_b128 v[36:39], v118 offset:50176
	ds_read_b128 v[120:123], v118 offset:51200
	ds_read_b128 v[224:227], v118 offset:52224
	ds_read_b128 v[228:231], v118 offset:53248
	ds_read_b128 v[232:235], v118 offset:54272
	ds_read_b128 v[236:239], v118 offset:55296
	ds_read_b128 v[240:243], v118 offset:56320
	global_load_lds_dwordx4 v[24:25], off
	v_lshl_add_u64 v[24:25], v[246:247], 0, s[72:73]
	s_mov_b32 m0, s64
	s_mov_b64 s[66:67], 0x160180
	s_add_i32 s65, s65, s30
	global_load_lds_dwordx4 v[24:25], off
	v_lshl_add_u64 v[24:25], v[246:247], 0, s[66:67]
	s_mov_b32 m0, s65
	s_mov_b64 s[66:67], 0x210180
	global_load_lds_dwordx4 v[24:25], off
	v_lshl_add_u64 v[24:25], v[246:247], 0, s[66:67]
	s_add_i32 s66, s65, 0x2000
	s_mov_b32 m0, s66
	s_nop 0
	global_load_lds_dwordx4 v[24:25], off
	v_lshl_add_u64 v[24:25], v[244:245], 0, s[70:71]
	s_mov_b32 m0, s46
	s_nop 0
	global_load_lds_dwordx4 v[24:25], off
	v_lshl_add_u64 v[24:25], v[244:245], 0, s[72:73]
	s_mov_b32 m0, s47
	s_nop 0
	global_load_lds_dwordx4 v[24:25], off
	s_waitcnt vmcnt(8)
	s_waitcnt lgkmcnt(0)
	s_barrier
	v_mfma_f32_16x16x32_bf16 v[24:27], v[8:11], v[32:35], v[136:139]
	v_mfma_f32_16x16x32_bf16 v[72:75], v[12:15], v[36:39], v[24:27]
	v_mfma_f32_16x16x32_bf16 v[24:27], v[16:19], v[32:35], v[140:143]
	v_mfma_f32_16x16x32_bf16 v[60:63], v[20:23], v[36:39], v[24:27]
	v_mfma_f32_16x16x32_bf16 v[24:27], v[8:11], v[120:123], v[144:147]
	v_mfma_f32_16x16x32_bf16 v[44:47], v[12:15], v[224:227], v[24:27]
	v_mfma_f32_16x16x32_bf16 v[24:27], v[16:19], v[120:123], v[148:151]
	v_mfma_f32_16x16x32_bf16 v[40:43], v[20:23], v[224:227], v[24:27]
	v_mfma_f32_16x16x32_bf16 v[24:27], v[8:11], v[228:231], v[152:155]
	v_mfma_f32_16x16x32_bf16 v[0:3], v[8:11], v[236:239], v[0:3]
	v_mfma_f32_16x16x32_bf16 v[28:31], v[12:15], v[232:235], v[24:27]
	v_mfma_f32_16x16x32_bf16 v[24:27], v[16:19], v[228:231], v[156:159]
	v_mfma_f32_16x16x32_bf16 v[12:15], v[12:15], v[240:243], v[0:3]
	v_mfma_f32_16x16x32_bf16 v[0:3], v[16:19], v[236:239], v[4:7]
	v_mfma_f32_16x16x32_bf16 v[24:27], v[20:23], v[232:235], v[24:27]
	v_mfma_f32_16x16x32_bf16 v[8:11], v[20:23], v[240:243], v[0:3]
	v_mfma_f32_16x16x32_bf16 v[0:3], v[132:135], v[32:35], v[160:163]
	v_mfma_f32_16x16x32_bf16 v[56:59], v[212:215], v[36:39], v[0:3]
	v_mfma_f32_16x16x32_bf16 v[0:3], v[216:219], v[32:35], v[180:183]
	v_mfma_f32_16x16x32_bf16 v[48:51], v[220:223], v[36:39], v[0:3]
	v_mfma_f32_16x16x32_bf16 v[0:3], v[132:135], v[120:123], v[188:191]
	v_mfma_f32_16x16x32_bf16 v[36:39], v[212:215], v[224:227], v[0:3]
	v_mfma_f32_16x16x32_bf16 v[0:3], v[216:219], v[120:123], v[192:195]
	v_mfma_f32_16x16x32_bf16 v[32:35], v[220:223], v[224:227], v[0:3]
	v_mfma_f32_16x16x32_bf16 v[0:3], v[132:135], v[228:231], v[196:199]
	v_mfma_f32_16x16x32_bf16 v[20:23], v[212:215], v[232:235], v[0:3]
	v_mfma_f32_16x16x32_bf16 v[0:3], v[216:219], v[228:231], v[124:127]
	v_mfma_f32_16x16x32_bf16 v[16:19], v[220:223], v[232:235], v[0:3]
	v_mfma_f32_16x16x32_bf16 v[0:3], v[132:135], v[236:239], v[200:203]
	v_mfma_f32_16x16x32_bf16 v[4:7], v[212:215], v[240:243], v[0:3]
	v_mfma_f32_16x16x32_bf16 v[0:3], v[216:219], v[236:239], v[128:131]
	v_mfma_f32_16x16x32_bf16 v[0:3], v[220:223], v[240:243], v[0:3]
	s_barrier
	s_add_u32 s20, s20, 0x160180
	s_addc_u32 s21, s21, 0
	s_add_u32 s67, s22, 0x200
	s_addc_u32 s68, s23, 0
	s_mov_b32 s70, 0
.LBB0_274:
	ds_read_b128 v[120:123], v116
	ds_read_b128 v[124:127], v116 offset:1024
	ds_read_b128 v[128:131], v116 offset:2048
	ds_read_b128 v[132:135], v116 offset:3072
	ds_read_b128 v[136:139], v117
	ds_read_b128 v[140:143], v117 offset:1024
	ds_read_b128 v[144:147], v117 offset:2048
	ds_read_b128 v[148:151], v117 offset:3072
	s_add_u32 s71, s20, 0xffea0080
	s_addc_u32 s72, s21, -1
	s_cmpk_eq_i32 s70, 0x54
	s_cselect_b64 vcc, -1, 0
	s_and_b64 s[22:23], vcc, exec
	v_cndmask_b32_e32 v184, v114, v186, vcc
	s_cselect_b32 s23, s15, s72
	s_cselect_b32 s22, s14, s71
	v_cndmask_b32_e32 v212, v112, v211, vcc
	s_cselect_b32 s73, s17, s68
	s_cselect_b32 s72, s16, s67
	s_mov_b32 m0, s57
	v_lshl_add_u64 v[214:215], s[20:21], 0, v[114:115]
	ds_read_b128 v[152:155], v118
	ds_read_b128 v[156:159], v118 offset:1024
	ds_read_b128 v[160:163], v118 offset:2048
	ds_read_b128 v[180:183], v118 offset:3072
	ds_read_b128 v[188:191], v118 offset:4096
	ds_read_b128 v[192:195], v118 offset:5120
	ds_read_b128 v[196:199], v118 offset:6144
	ds_read_b128 v[200:203], v118 offset:7168
	global_load_lds_dwordx4 v[214:215], off
	v_lshl_add_u64 v[214:215], v[214:215], 0, s[0:1]
	s_mov_b32 m0, s58
	s_nop 0
	global_load_lds_dwordx4 v[214:215], off
	s_waitcnt vmcnt(8)
	s_waitcnt lgkmcnt(0)
	s_barrier
	v_mfma_f32_16x16x32_bf16 v[172:175], v[120:123], v[152:155], v[172:175]
	v_mfma_f32_16x16x32_bf16 v[164:167], v[128:131], v[152:155], v[164:167]
	v_mfma_f32_16x16x32_bf16 v[108:111], v[120:123], v[160:163], v[108:111]
	v_mfma_f32_16x16x32_bf16 v[104:107], v[128:131], v[160:163], v[104:107]
	v_mfma_f32_16x16x32_bf16 v[92:95], v[120:123], v[188:191], v[92:95]
	v_mfma_f32_16x16x32_bf16 v[88:91], v[128:131], v[188:191], v[88:91]
	v_mfma_f32_16x16x32_bf16 v[76:79], v[120:123], v[196:199], v[76:79]
	v_mfma_f32_16x16x32_bf16 v[68:71], v[128:131], v[196:199], v[68:71]
	v_mfma_f32_16x16x32_bf16 v[172:175], v[124:127], v[156:159], v[172:175]
	v_mfma_f32_16x16x32_bf16 v[164:167], v[132:135], v[156:159], v[164:167]
	v_mfma_f32_16x16x32_bf16 v[108:111], v[124:127], v[180:183], v[108:111]
	v_mfma_f32_16x16x32_bf16 v[104:107], v[132:135], v[180:183], v[104:107]
	v_mfma_f32_16x16x32_bf16 v[92:95], v[124:127], v[192:195], v[92:95]
	v_mfma_f32_16x16x32_bf16 v[88:91], v[132:135], v[192:195], v[88:91]
	v_mfma_f32_16x16x32_bf16 v[76:79], v[124:127], v[200:203], v[76:79]
	v_mfma_f32_16x16x32_bf16 v[68:71], v[132:135], v[200:203], v[68:71]
	v_mfma_f32_16x16x32_bf16 v[176:179], v[136:139], v[152:155], v[176:179]
	v_mfma_f32_16x16x32_bf16 v[100:103], v[136:139], v[160:163], v[100:103]
	v_mfma_f32_16x16x32_bf16 v[96:99], v[144:147], v[160:163], v[96:99]
	v_mfma_f32_16x16x32_bf16 v[84:87], v[136:139], v[188:191], v[84:87]
	v_mfma_f32_16x16x32_bf16 v[80:83], v[144:147], v[188:191], v[80:83]
	v_mfma_f32_16x16x32_bf16 v[64:67], v[136:139], v[196:199], v[64:67]
	v_mfma_f32_16x16x32_bf16 v[52:55], v[144:147], v[196:199], v[52:55]
	v_mfma_f32_16x16x32_bf16 v[176:179], v[140:143], v[156:159], v[176:179]
	v_mfma_f32_16x16x32_bf16 v[152:155], v[144:147], v[152:155], v[168:171]
	v_mfma_f32_16x16x32_bf16 v[100:103], v[140:143], v[180:183], v[100:103]
	v_mfma_f32_16x16x32_bf16 v[96:99], v[148:151], v[180:183], v[96:99]
	v_mfma_f32_16x16x32_bf16 v[84:87], v[140:143], v[192:195], v[84:87]
	v_mfma_f32_16x16x32_bf16 v[80:83], v[148:151], v[192:195], v[80:83]
	v_mfma_f32_16x16x32_bf16 v[64:67], v[140:143], v[200:203], v[64:67]
	v_mfma_f32_16x16x32_bf16 v[52:55], v[148:151], v[200:203], v[52:55]
	v_mfma_f32_16x16x32_bf16 v[152:155], v[148:151], v[156:159], v[152:155]
	s_barrier
	v_mov_b32_e32 v213, v185
	s_mov_b32 m0, s59
	v_lshl_add_u64 v[216:217], s[72:73], 0, v[212:213]
	ds_read_b128 v[156:159], v118 offset:16384
	ds_read_b128 v[160:163], v118 offset:17408
	ds_read_b128 v[168:171], v118 offset:18432
	ds_read_b128 v[180:183], v118 offset:19456
	ds_read_b128 v[188:191], v118 offset:20480
	ds_read_b128 v[192:195], v118 offset:21504
	ds_read_b128 v[196:199], v118 offset:22528
	ds_read_b128 v[200:203], v118 offset:23552
	global_load_lds_dwordx4 v212, s[72:73]
	v_lshl_add_u64 v[212:213], v[216:217], 0, s[0:1]
	s_mov_b32 m0, s60
	v_lshl_add_u64 v[218:219], s[22:23], 0, v[184:185]
	global_load_lds_dwordx4 v[212:213], off
	v_lshl_add_u64 v[212:213], v[216:217], 0, s[2:3]
	s_mov_b32 m0, s61
	s_nop 0
	global_load_lds_dwordx4 v[212:213], off
	v_lshl_add_u64 v[212:213], v[216:217], 0, s[36:37]
	s_mov_b32 m0, s62
	s_nop 0
	global_load_lds_dwordx4 v[212:213], off
	s_mov_b32 m0, s31
	v_lshl_add_u64 v[212:213], v[218:219], 0, s[0:1]
	global_load_lds_dwordx4 v[218:219], off
	s_mov_b32 m0, s35
	s_nop 0
	global_load_lds_dwordx4 v[212:213], off
	s_waitcnt vmcnt(8)
	s_waitcnt lgkmcnt(0)
	s_barrier
	v_mfma_f32_16x16x32_bf16 v[72:75], v[120:123], v[156:159], v[72:75]
	v_mfma_f32_16x16x32_bf16 v[60:63], v[128:131], v[156:159], v[60:63]
	v_mfma_f32_16x16x32_bf16 v[44:47], v[120:123], v[168:171], v[44:47]
	v_mfma_f32_16x16x32_bf16 v[40:43], v[128:131], v[168:171], v[40:43]
	v_mfma_f32_16x16x32_bf16 v[28:31], v[120:123], v[188:191], v[28:31]
	v_mfma_f32_16x16x32_bf16 v[24:27], v[128:131], v[188:191], v[24:27]
	v_mfma_f32_16x16x32_bf16 v[12:15], v[120:123], v[196:199], v[12:15]
	v_mfma_f32_16x16x32_bf16 v[8:11], v[128:131], v[196:199], v[8:11]
	v_mfma_f32_16x16x32_bf16 v[72:75], v[124:127], v[160:163], v[72:75]
	v_mfma_f32_16x16x32_bf16 v[60:63], v[132:135], v[160:163], v[60:63]
	v_mfma_f32_16x16x32_bf16 v[44:47], v[124:127], v[180:183], v[44:47]
	v_mfma_f32_16x16x32_bf16 v[40:43], v[132:135], v[180:183], v[40:43]
	v_mfma_f32_16x16x32_bf16 v[28:31], v[124:127], v[192:195], v[28:31]
	v_mfma_f32_16x16x32_bf16 v[24:27], v[132:135], v[192:195], v[24:27]
	v_mfma_f32_16x16x32_bf16 v[12:15], v[124:127], v[200:203], v[12:15]
	v_mfma_f32_16x16x32_bf16 v[8:11], v[132:135], v[200:203], v[8:11]
	v_mfma_f32_16x16x32_bf16 v[56:59], v[136:139], v[156:159], v[56:59]
	v_mfma_f32_16x16x32_bf16 v[48:51], v[144:147], v[156:159], v[48:51]
	v_mfma_f32_16x16x32_bf16 v[36:39], v[136:139], v[168:171], v[36:39]
	v_mfma_f32_16x16x32_bf16 v[32:35], v[144:147], v[168:171], v[32:35]
	v_mfma_f32_16x16x32_bf16 v[20:23], v[136:139], v[188:191], v[20:23]
	v_mfma_f32_16x16x32_bf16 v[16:19], v[144:147], v[188:191], v[16:19]
	v_mfma_f32_16x16x32_bf16 v[4:7], v[136:139], v[196:199], v[4:7]
	v_mfma_f32_16x16x32_bf16 v[0:3], v[144:147], v[196:199], v[0:3]
	v_mfma_f32_16x16x32_bf16 v[56:59], v[140:143], v[160:163], v[56:59]
	v_mfma_f32_16x16x32_bf16 v[48:51], v[148:151], v[160:163], v[48:51]
	v_mfma_f32_16x16x32_bf16 v[36:39], v[140:143], v[180:183], v[36:39]
	v_mfma_f32_16x16x32_bf16 v[32:35], v[148:151], v[180:183], v[32:35]
	v_mfma_f32_16x16x32_bf16 v[20:23], v[140:143], v[192:195], v[20:23]
	v_mfma_f32_16x16x32_bf16 v[16:19], v[148:151], v[192:195], v[16:19]
	v_mfma_f32_16x16x32_bf16 v[4:7], v[140:143], v[200:203], v[4:7]
	v_mfma_f32_16x16x32_bf16 v[0:3], v[148:151], v[200:203], v[0:3]
	s_barrier
; #define PG8_WAIT_V(n) asm volatile("s_waitcnt vmcnt(" #n ")" ::: "memory")
; #define PG8_WAIT_VP() asm volatile("s_waitcnt vmcnt(%0)" :: "n"(8 + Epi::NST) : "memory")
; #define PG8_BAR __builtin_amdgcn_s_barrier()
; template <class Epi, class Sched>
; __device__ __forceinline__ void gemm_phase(PG8_LAS unsigned char* lds, const Sched& S, const Epi& E, int tid_in) {
;     ...
;         { const int t = 0; PG8_KITER(PG8_WAIT_VP()); }
;         for (int t = 2; t < nt; t += 2) PG8_KITER(PG8_WAIT_V(8));
;     ...
;         if (wr == 0) PG8_BAR;
	ds_read_b128 v[120:123], v113
	ds_read_b128 v[124:127], v113 offset:1024
	ds_read_b128 v[128:131], v113 offset:2048
	ds_read_b128 v[132:135], v113 offset:3072
	ds_read_b128 v[136:139], v119
	ds_read_b128 v[140:143], v119 offset:1024
	ds_read_b128 v[144:147], v119 offset:2048
	ds_read_b128 v[148:151], v119 offset:3072
	s_mov_b32 m0, s48
	v_lshl_add_u64 v[168:169], v[218:219], 0, s[2:3]
	ds_read_b128 v[156:159], v118 offset:32768
	ds_read_b128 v[160:163], v118 offset:33792
	ds_read_b128 v[180:183], v118 offset:34816
	ds_read_b128 v[188:191], v118 offset:35840
	ds_read_b128 v[192:195], v118 offset:36864
	ds_read_b128 v[196:199], v118 offset:37888
	ds_read_b128 v[200:203], v118 offset:38912
	ds_read_b128 v[212:215], v118 offset:39936
	global_load_lds_dwordx4 v[168:169], off
	v_lshl_add_u64 v[168:169], v[218:219], 0, s[36:37]
	s_mov_b32 m0, s49
	s_nop 0
	global_load_lds_dwordx4 v[168:169], off
	s_waitcnt vmcnt(8)
	s_waitcnt lgkmcnt(0)
	s_barrier
	v_mfma_f32_16x16x32_bf16 v[168:171], v[120:123], v[156:159], v[172:175]
	v_mfma_f32_16x16x32_bf16 v[164:167], v[128:131], v[156:159], v[164:167]
	v_mfma_f32_16x16x32_bf16 v[108:111], v[120:123], v[180:183], v[108:111]
	v_mfma_f32_16x16x32_bf16 v[104:107], v[128:131], v[180:183], v[104:107]
	v_mfma_f32_16x16x32_bf16 v[92:95], v[120:123], v[192:195], v[92:95]
	v_mfma_f32_16x16x32_bf16 v[88:91], v[128:131], v[192:195], v[88:91]
	v_mfma_f32_16x16x32_bf16 v[76:79], v[120:123], v[200:203], v[76:79]
	v_mfma_f32_16x16x32_bf16 v[68:71], v[128:131], v[200:203], v[68:71]
	v_mfma_f32_16x16x32_bf16 v[172:175], v[124:127], v[160:163], v[168:171]
	v_mfma_f32_16x16x32_bf16 v[164:167], v[132:135], v[160:163], v[164:167]
	v_mfma_f32_16x16x32_bf16 v[108:111], v[124:127], v[188:191], v[108:111]
	v_mfma_f32_16x16x32_bf16 v[104:107], v[132:135], v[188:191], v[104:107]
	v_mfma_f32_16x16x32_bf16 v[92:95], v[124:127], v[196:199], v[92:95]
	v_mfma_f32_16x16x32_bf16 v[88:91], v[132:135], v[196:199], v[88:91]
	v_mfma_f32_16x16x32_bf16 v[76:79], v[124:127], v[212:215], v[76:79]
	v_mfma_f32_16x16x32_bf16 v[68:71], v[132:135], v[212:215], v[68:71]
	v_mfma_f32_16x16x32_bf16 v[168:171], v[136:139], v[156:159], v[176:179]
	v_mfma_f32_16x16x32_bf16 v[152:155], v[144:147], v[156:159], v[152:155]
	v_mfma_f32_16x16x32_bf16 v[100:103], v[136:139], v[180:183], v[100:103]
	v_mfma_f32_16x16x32_bf16 v[96:99], v[144:147], v[180:183], v[96:99]
	v_mfma_f32_16x16x32_bf16 v[84:87], v[136:139], v[192:195], v[84:87]
	v_mfma_f32_16x16x32_bf16 v[80:83], v[144:147], v[192:195], v[80:83]
	v_mfma_f32_16x16x32_bf16 v[64:67], v[136:139], v[200:203], v[64:67]
	v_mfma_f32_16x16x32_bf16 v[52:55], v[144:147], v[200:203], v[52:55]
	v_mfma_f32_16x16x32_bf16 v[176:179], v[140:143], v[160:163], v[168:171]
	v_mfma_f32_16x16x32_bf16 v[168:171], v[148:151], v[160:163], v[152:155]
	v_mfma_f32_16x16x32_bf16 v[100:103], v[140:143], v[188:191], v[100:103]
	v_mfma_f32_16x16x32_bf16 v[96:99], v[148:151], v[188:191], v[96:99]
	v_mfma_f32_16x16x32_bf16 v[84:87], v[140:143], v[196:199], v[84:87]
	v_mfma_f32_16x16x32_bf16 v[80:83], v[148:151], v[196:199], v[80:83]
	v_mfma_f32_16x16x32_bf16 v[64:67], v[140:143], v[212:215], v[64:67]
	v_mfma_f32_16x16x32_bf16 v[52:55], v[148:151], v[212:215], v[52:55]
	s_barrier
	s_mov_b32 m0, s63
	v_lshl_add_u64 v[212:213], v[216:217], 0, s[84:85]
	ds_read_b128 v[152:155], v118 offset:49152
	ds_read_b128 v[156:159], v118 offset:50176
	ds_read_b128 v[160:163], v118 offset:51200
	ds_read_b128 v[180:183], v118 offset:52224
	ds_read_b128 v[188:191], v118 offset:53248
	ds_read_b128 v[192:195], v118 offset:54272
	ds_read_b128 v[196:199], v118 offset:55296
	ds_read_b128 v[200:203], v118 offset:56320
	global_load_lds_dwordx4 v[212:213], off
	v_lshl_add_u64 v[212:213], v[216:217], 0, s[38:39]
	s_mov_b32 m0, s64
	s_nop 0
	global_load_lds_dwordx4 v[212:213], off
	v_lshl_add_u64 v[212:213], v[216:217], 0, s[40:41]
	s_mov_b32 m0, s65
	s_nop 0
	global_load_lds_dwordx4 v[212:213], off
	v_lshl_add_u64 v[212:213], v[216:217], 0, s[42:43]
	s_mov_b32 m0, s66
	s_nop 0
	global_load_lds_dwordx4 v[212:213], off
	v_lshl_add_u64 v[212:213], v[218:219], 0, s[84:85]
	s_mov_b32 m0, s46
	s_nop 0
	global_load_lds_dwordx4 v[212:213], off
	v_lshl_add_u64 v[212:213], v[218:219], 0, s[38:39]
	s_mov_b32 m0, s47
	s_nop 0
	global_load_lds_dwordx4 v[212:213], off
	s_waitcnt vmcnt(8)
	s_waitcnt lgkmcnt(0)
	s_barrier
	v_mfma_f32_16x16x32_bf16 v[72:75], v[120:123], v[152:155], v[72:75]
	v_mfma_f32_16x16x32_bf16 v[60:63], v[128:131], v[152:155], v[60:63]
	v_mfma_f32_16x16x32_bf16 v[44:47], v[120:123], v[160:163], v[44:47]
	v_mfma_f32_16x16x32_bf16 v[40:43], v[128:131], v[160:163], v[40:43]
	v_mfma_f32_16x16x32_bf16 v[28:31], v[120:123], v[188:191], v[28:31]
	v_mfma_f32_16x16x32_bf16 v[24:27], v[128:131], v[188:191], v[24:27]
	v_mfma_f32_16x16x32_bf16 v[12:15], v[120:123], v[196:199], v[12:15]
	v_mfma_f32_16x16x32_bf16 v[8:11], v[128:131], v[196:199], v[8:11]
	v_mfma_f32_16x16x32_bf16 v[72:75], v[124:127], v[156:159], v[72:75]
	v_mfma_f32_16x16x32_bf16 v[60:63], v[132:135], v[156:159], v[60:63]
	v_mfma_f32_16x16x32_bf16 v[44:47], v[124:127], v[180:183], v[44:47]
	v_mfma_f32_16x16x32_bf16 v[40:43], v[132:135], v[180:183], v[40:43]
	v_mfma_f32_16x16x32_bf16 v[28:31], v[124:127], v[192:195], v[28:31]
	v_mfma_f32_16x16x32_bf16 v[24:27], v[132:135], v[192:195], v[24:27]
	v_mfma_f32_16x16x32_bf16 v[12:15], v[124:127], v[200:203], v[12:15]
	v_mfma_f32_16x16x32_bf16 v[8:11], v[132:135], v[200:203], v[8:11]
	v_mfma_f32_16x16x32_bf16 v[56:59], v[136:139], v[152:155], v[56:59]
	v_mfma_f32_16x16x32_bf16 v[48:51], v[144:147], v[152:155], v[48:51]
	v_mfma_f32_16x16x32_bf16 v[36:39], v[136:139], v[160:163], v[36:39]
	v_mfma_f32_16x16x32_bf16 v[32:35], v[144:147], v[160:163], v[32:35]
	v_mfma_f32_16x16x32_bf16 v[20:23], v[136:139], v[188:191], v[20:23]
	v_mfma_f32_16x16x32_bf16 v[16:19], v[144:147], v[188:191], v[16:19]
	v_mfma_f32_16x16x32_bf16 v[4:7], v[136:139], v[196:199], v[4:7]
	v_mfma_f32_16x16x32_bf16 v[0:3], v[144:147], v[196:199], v[0:3]
	v_mfma_f32_16x16x32_bf16 v[56:59], v[140:143], v[156:159], v[56:59]
	v_mfma_f32_16x16x32_bf16 v[48:51], v[148:151], v[156:159], v[48:51]
	v_mfma_f32_16x16x32_bf16 v[36:39], v[140:143], v[180:183], v[36:39]
	v_mfma_f32_16x16x32_bf16 v[32:35], v[148:151], v[180:183], v[32:35]
	v_mfma_f32_16x16x32_bf16 v[20:23], v[140:143], v[192:195], v[20:23]
	v_mfma_f32_16x16x32_bf16 v[16:19], v[148:151], v[192:195], v[16:19]
	v_mfma_f32_16x16x32_bf16 v[4:7], v[140:143], v[200:203], v[4:7]
	v_mfma_f32_16x16x32_bf16 v[0:3], v[148:151], v[200:203], v[0:3]
	s_barrier
	s_add_i32 s70, s70, 2
	s_add_u32 s20, s20, 0x100
	s_addc_u32 s21, s21, 0
	s_add_u32 s67, s67, 0x100
	s_addc_u32 s68, s68, 0
	s_cmpk_gt_u32 s70, 0x55
	s_cbranch_scc0 .LBB0_274
	s_and_b64 vcc, exec, s[12:13]
	s_cbranch_vccz .LBB0_277
	s_barrier

; __device__ __forceinline__ int lane_id() { int l; asm volatile("v_mbcnt_lo_u32_b32 %0, -1, 0\n\tv_mbcnt_hi_u32_b32 %0, -1, %0" : "=v"(l)); return l; }
;     __device__ __forceinline__ bool next(int i, UnitG& u) const { if (!P.next(i, u)) return false; u.O = O + ((size_t)u.x0 * 256 * 2048 + (size_t)u.x1 * 256) * 2; u.ldo = 2048; u.kind = 0; return true; }
; template <class Epi, class Sched>
; __device__ __forceinline__ void gemm_phase(PG8_LAS unsigned char* lds, const Sched& S, const Epi& E, int tid_in) {
;     ...
;         int aoff, boff; { const int l3 = lane_id(), fr3 = l3 & 15, fq3 = l3 >> 4; aoff = lds_byte(wr * 64 + fr3, fq3 * 8); boff = lds_byte(wc * 32 + fr3, fq3 * 8); }
;         const bool has_next = S.next(ui + 1, nxt);
;         const char* nA = has_next ? nxt.A : cA; const char* nB = has_next ? nxt.B : cB;
;         const int nlda = has_next ? nxt.lda : cur.lda, nldb = has_next ? nxt.ldb : cur.ldb;
;         unsigned nvA, nvB; { int r2, c2; stage_rc((wid * 64 + lane_id()) * 16, r2, c2); const int rb2 = Epi::PERM ? ((r2 & ~31) + perm32(r2 & 31)) : r2;
;             nvA = (unsigned)(r2 * nlda + c2) * 2u; nvB = (unsigned)(rb2 * nldb + c2) * 2u; }
;         const unsigned nqA = (unsigned)nlda * 128u, nqB = (unsigned)nldb * 128u;
;         const int nt = cur.K / BK;
.LBB0_393:
	v_and_b32_e32 v1, 15, v0
	v_or_b32_e32 v2, s47, v1
	v_ashrrev_i32_e32 v3, 6, v0
	v_lshlrev_b32_e32 v4, 6, v2
	v_and_b32_e32 v5, 48, v0
	s_movk_i32 s53, 0x3c0
	v_lshlrev_b32_e32 v2, 2, v2
	v_and_or_b32 v4, v4, s53, v5
	v_lshl_add_u32 v6, v3, 10, s48
	v_and_b32_e32 v2, 32, v2
	v_lshlrev_b32_e32 v0, 2, v0
	s_nop 0
	v_bitop3_b32 v32, v4, v6, v2 bitop3:0xde
	v_lshl_or_b32 v1, v1, 6, v5
	v_add_lshl_u32 v2, v3, s50, 10
	v_and_b32_e32 v0, 32, v0
	v_bitop3_b32 v137, v1, v2, v0 bitop3:0xde
	v_mbcnt_lo_u32_b32 v0, -1, 0
	v_mbcnt_hi_u32_b32 v0, -1, v0
	s_mov_b32 s53, 0xfffe0
	v_add_u32_e32 v0, s51, v0
	v_ashrrev_i32_e32 v2, 31, v0
	v_lshrrev_b32_e32 v2, 26, v2
	v_lshlrev_b32_e32 v1, 4, v0
	v_add_u32_e32 v2, v0, v2
	v_bfe_i32 v0, v0, 27, 1
	v_lshrrev_b32_e32 v0, 22, v0
	v_add_u32_e32 v0, v1, v0
	v_and_b32_e32 v0, 0xfffffc00, v0
	v_sub_u32_e32 v0, v1, v0
	v_lshrrev_b32_e32 v1, 4, v0
	v_bitop3_b32 v0, v1, v0, 32 bitop3:0x6c
	v_ashrrev_i32_e32 v3, 31, v0
	v_lshrrev_b32_e32 v3, 26, v3
	v_ashrrev_i32_e32 v2, 6, v2
	v_add_u32_e32 v3, v0, v3
	v_lshlrev_b32_e32 v1, 3, v2
	v_ashrrev_i32_e32 v4, 6, v3
	v_and_b32_e32 v3, 0xc0, v3
	v_and_b32_e32 v1, -16, v1
	v_sub_u32_e32 v0, v0, v3
	v_add_u32_e32 v1, v4, v1
	v_lshlrev_b32_e32 v2, 5, v2
	v_ashrrev_i16_sdwa v0, v205, sext(v0) dst_sel:DWORD dst_unused:UNUSED_PAD src0_sel:DWORD src1_sel:BYTE_0
	v_and_b32_e32 v2, 32, v2
	v_bfe_i32 v0, v0, 0, 16
	v_lshlrev_b32_e32 v3, 1, v1
	v_lshrrev_b32_e32 v5, 2, v1
	v_and_b32_e32 v4, 3, v4
	s_add_i32 s55, 0, 0x10000
	s_add_i32 s57, 0, 0x14000
	v_and_b32_e32 v3, 24, v3
	v_and_b32_e32 v5, 4, v5
	v_and_or_b32 v4, v1, s53, v4
	v_add_lshl_u32 v34, v2, v0, 1
	v_add_u32_e32 v134, s55, v137
	v_add_u32_e32 v135, s57, v137
	v_or3_b32 v33, v4, v5, v3
	v_lshl_add_u32 v128, v1, 12, v34
	ds_read_b128 v[0:3], v134
	ds_read_b128 v[4:7], v134 offset:1024
	ds_read_b128 v[8:11], v134 offset:2048
	ds_read_b128 v[12:15], v134 offset:3072
	ds_read_b128 v[16:19], v135
	ds_read_b128 v[20:23], v135 offset:1024
	ds_read_b128 v[24:27], v135 offset:2048
	ds_read_b128 v[28:31], v135 offset:3072
	v_lshl_add_u32 v129, v33, 12, v34
	v_mov_b32_e32 v133, v185
	v_lshl_add_u64 v[182:183], s[18:19], 0, v[132:133]
	s_add_i32 s53, s29, 0xc000
	v_add_u32_e32 v136, 0, v32
	v_lshl_add_u64 v[64:65], v[182:183], 0, s[80:81]
	s_mov_b32 m0, s53
	s_add_i32 s54, s29, 0xe000
	ds_read_b128 v[32:35], v136
	ds_read_b128 v[36:39], v136 offset:1024
	ds_read_b128 v[40:43], v136 offset:2048
	ds_read_b128 v[44:47], v136 offset:3072
	ds_read_b128 v[48:51], v136 offset:4096
	ds_read_b128 v[52:55], v136 offset:5120
	ds_read_b128 v[56:59], v136 offset:6144
	ds_read_b128 v[60:63], v136 offset:7168
	global_load_lds_dwordx4 v[64:65], off
	v_lshl_add_u64 v[64:65], v[182:183], 0, s[78:79]
	s_mov_b32 m0, s54
	s_nop 0
	global_load_lds_dwordx4 v[64:65], off
	s_waitcnt vmcnt(24)
	s_waitcnt lgkmcnt(0)
	s_barrier
	v_mfma_f32_16x16x32_bf16 v[64:67], v[0:3], v[32:35], 0
	v_mfma_f32_16x16x32_bf16 v[68:71], v[8:11], v[32:35], 0
	v_mfma_f32_16x16x32_bf16 v[72:75], v[0:3], v[40:43], 0
	v_mfma_f32_16x16x32_bf16 v[76:79], v[8:11], v[40:43], 0
	v_mfma_f32_16x16x32_bf16 v[80:83], v[0:3], v[48:51], 0
	v_mfma_f32_16x16x32_bf16 v[84:87], v[8:11], v[48:51], 0
	v_mfma_f32_16x16x32_bf16 v[88:91], v[0:3], v[56:59], 0
	v_mfma_f32_16x16x32_bf16 v[92:95], v[8:11], v[56:59], 0
	v_mfma_f32_16x16x32_bf16 v[64:67], v[4:7], v[36:39], v[64:67]
	v_mfma_f32_16x16x32_bf16 v[68:71], v[12:15], v[36:39], v[68:71]
	v_mfma_f32_16x16x32_bf16 v[72:75], v[4:7], v[44:47], v[72:75]
	v_mfma_f32_16x16x32_bf16 v[76:79], v[12:15], v[44:47], v[76:79]
	v_mfma_f32_16x16x32_bf16 v[80:83], v[4:7], v[52:55], v[80:83]
	v_mfma_f32_16x16x32_bf16 v[84:87], v[12:15], v[52:55], v[84:87]
	v_mfma_f32_16x16x32_bf16 v[88:91], v[4:7], v[60:63], v[88:91]
	v_mfma_f32_16x16x32_bf16 v[92:95], v[12:15], v[60:63], v[92:95]
	v_mfma_f32_16x16x32_bf16 v[96:99], v[16:19], v[32:35], 0
	v_mfma_f32_16x16x32_bf16 v[32:35], v[24:27], v[32:35], 0
	v_mfma_f32_16x16x32_bf16 v[108:111], v[28:31], v[36:39], v[32:35]
	v_mfma_f32_16x16x32_bf16 v[32:35], v[16:19], v[40:43], 0
	v_mfma_f32_16x16x32_bf16 v[138:141], v[20:23], v[44:47], v[32:35]
	v_mfma_f32_16x16x32_bf16 v[32:35], v[24:27], v[40:43], 0
	v_mfma_f32_16x16x32_bf16 v[40:43], v[28:31], v[44:47], v[32:35]
	v_mfma_f32_16x16x32_bf16 v[32:35], v[16:19], v[48:51], 0
	v_mfma_f32_16x16x32_bf16 v[44:47], v[20:23], v[52:55], v[32:35]
	v_mfma_f32_16x16x32_bf16 v[32:35], v[24:27], v[48:51], 0
	v_mfma_f32_16x16x32_bf16 v[48:51], v[28:31], v[52:55], v[32:35]
	v_mfma_f32_16x16x32_bf16 v[32:35], v[16:19], v[56:59], 0
	v_mfma_f32_16x16x32_bf16 v[52:55], v[20:23], v[60:63], v[32:35]
	v_mfma_f32_16x16x32_bf16 v[32:35], v[24:27], v[56:59], 0
	v_mfma_f32_16x16x32_bf16 v[104:107], v[20:23], v[36:39], v[96:99]
	v_mfma_f32_16x16x32_bf16 v[56:59], v[28:31], v[60:63], v[32:35]
	s_barrier
	v_mov_b32_e32 v131, v185
	v_lshl_add_u64 v[248:249], s[20:21], 0, v[130:131]
	s_mov_b64 s[60:61], 0x100
	s_add_i32 s55, s55, s28
	v_lshl_add_u64 v[124:125], v[248:249], 0, s[60:61]
	s_mov_b32 m0, s55
	s_mov_b64 s[62:63], 0x40100
	s_add_i32 s56, s55, 0x2000
	ds_read_b128 v[32:35], v136 offset:16384
	ds_read_b128 v[36:39], v136 offset:17408
	ds_read_b128 v[60:63], v136 offset:18432
	ds_read_b128 v[96:99], v136 offset:19456
	ds_read_b128 v[100:103], v136 offset:20480
	ds_read_b128 v[112:115], v136 offset:21504
	ds_read_b128 v[116:119], v136 offset:22528
	ds_read_b128 v[120:123], v136 offset:23552
	global_load_lds_dwordx4 v[124:125], off
	v_lshl_add_u64 v[124:125], v[248:249], 0, s[62:63]
	s_mov_b32 m0, s56
	s_mov_b64 s[64:65], 0x80100
	s_add_i32 s57, s57, s28
	global_load_lds_dwordx4 v[124:125], off
	v_lshl_add_u64 v[124:125], v[248:249], 0, s[64:65]
	s_mov_b32 m0, s57
	s_mov_b64 s[66:67], 0xc0100
	s_add_i32 s58, s57, 0x2000
	global_load_lds_dwordx4 v[124:125], off
	v_lshl_add_u64 v[124:125], v[248:249], 0, s[66:67]
	s_mov_b32 m0, s58
	s_nop 0
	global_load_lds_dwordx4 v[124:125], off
	v_lshl_add_u64 v[124:125], v[182:183], 0, s[60:61]
	s_mov_b32 m0, s29
	s_nop 0
	global_load_lds_dwordx4 v[124:125], off
	v_lshl_add_u64 v[124:125], v[182:183], 0, s[62:63]
	s_mov_b32 m0, s30
	s_nop 0
	global_load_lds_dwordx4 v[124:125], off
	s_waitcnt vmcnt(24)
	s_waitcnt lgkmcnt(0)
	s_barrier
	v_mfma_f32_16x16x32_bf16 v[124:127], v[0:3], v[32:35], 0
	v_mfma_f32_16x16x32_bf16 v[142:145], v[4:7], v[36:39], v[124:127]
	v_mfma_f32_16x16x32_bf16 v[124:127], v[8:11], v[32:35], 0
	v_mfma_f32_16x16x32_bf16 v[146:149], v[12:15], v[36:39], v[124:127]
	v_mfma_f32_16x16x32_bf16 v[124:127], v[0:3], v[60:63], 0
	v_mfma_f32_16x16x32_bf16 v[150:153], v[4:7], v[96:99], v[124:127]
	v_mfma_f32_16x16x32_bf16 v[124:127], v[8:11], v[60:63], 0
	v_mfma_f32_16x16x32_bf16 v[154:157], v[12:15], v[96:99], v[124:127]
	v_mfma_f32_16x16x32_bf16 v[124:127], v[0:3], v[100:103], 0
	v_mfma_f32_16x16x32_bf16 v[0:3], v[0:3], v[116:119], 0
	v_mfma_f32_16x16x32_bf16 v[158:161], v[4:7], v[112:115], v[124:127]
	v_mfma_f32_16x16x32_bf16 v[0:3], v[4:7], v[120:123], v[0:3]
	v_mfma_f32_16x16x32_bf16 v[4:7], v[8:11], v[116:119], 0
	v_mfma_f32_16x16x32_bf16 v[124:127], v[8:11], v[100:103], 0
	v_mfma_f32_16x16x32_bf16 v[8:11], v[12:15], v[120:123], v[4:7]
	v_mfma_f32_16x16x32_bf16 v[162:165], v[12:15], v[112:115], v[124:127]
	v_mfma_f32_16x16x32_bf16 v[4:7], v[16:19], v[32:35], 0
	v_mfma_f32_16x16x32_bf16 v[12:15], v[20:23], v[36:39], v[4:7]
	v_mfma_f32_16x16x32_bf16 v[4:7], v[24:27], v[32:35], 0
	v_mfma_f32_16x16x32_bf16 v[166:169], v[28:31], v[36:39], v[4:7]
	v_mfma_f32_16x16x32_bf16 v[4:7], v[16:19], v[60:63], 0
	v_mfma_f32_16x16x32_bf16 v[170:173], v[20:23], v[96:99], v[4:7]
	v_mfma_f32_16x16x32_bf16 v[4:7], v[24:27], v[60:63], 0
	v_mfma_f32_16x16x32_bf16 v[174:177], v[28:31], v[96:99], v[4:7]
	v_mfma_f32_16x16x32_bf16 v[4:7], v[16:19], v[100:103], 0
	v_mfma_f32_16x16x32_bf16 v[178:181], v[20:23], v[112:115], v[4:7]
	v_mfma_f32_16x16x32_bf16 v[4:7], v[24:27], v[100:103], 0
	v_mfma_f32_16x16x32_bf16 v[188:191], v[28:31], v[112:115], v[4:7]
	v_mfma_f32_16x16x32_bf16 v[4:7], v[16:19], v[116:119], 0
	v_mfma_f32_16x16x32_bf16 v[192:195], v[20:23], v[120:123], v[4:7]
	v_mfma_f32_16x16x32_bf16 v[4:7], v[24:27], v[116:119], 0
	v_mfma_f32_16x16x32_bf16 v[196:199], v[28:31], v[120:123], v[4:7]
	s_barrier
	s_add_i32 s59, 0, 0x18000
	s_add_i32 s61, 0, 0x1c000
	v_add_u32_e32 v131, s59, v137
	v_add_u32_e32 v137, s61, v137
	s_nop 0
	ds_read_b128 v[4:7], v131
	ds_read_b128 v[24:27], v131 offset:1024
	ds_read_b128 v[28:31], v131 offset:2048
	ds_read_b128 v[60:63], v131 offset:3072
	ds_read_b128 v[200:203], v137
	ds_read_b128 v[212:215], v137 offset:1024
	ds_read_b128 v[216:219], v137 offset:2048
	ds_read_b128 v[220:223], v137 offset:3072
	s_mov_b32 m0, s31
	v_lshl_add_u64 v[32:33], v[182:183], 0, s[64:65]
	ds_read_b128 v[16:19], v136 offset:32768
	ds_read_b128 v[20:23], v136 offset:33792
	ds_read_b128 v[224:227], v136 offset:34816
	ds_read_b128 v[228:231], v136 offset:35840
	ds_read_b128 v[232:235], v136 offset:36864
	ds_read_b128 v[236:239], v136 offset:37888
	ds_read_b128 v[240:243], v136 offset:38912
	ds_read_b128 v[244:247], v136 offset:39936
	global_load_lds_dwordx4 v[32:33], off
	v_lshl_add_u64 v[32:33], v[182:183], 0, s[66:67]
	s_mov_b32 m0, s34
	s_nop 0
	global_load_lds_dwordx4 v[32:33], off
	s_waitcnt vmcnt(8)
	s_waitcnt lgkmcnt(0)
	s_barrier
	v_mfma_f32_16x16x32_bf16 v[32:35], v[4:7], v[16:19], v[64:67]
	v_mfma_f32_16x16x32_bf16 v[116:119], v[24:27], v[20:23], v[32:35]
	v_mfma_f32_16x16x32_bf16 v[32:35], v[28:31], v[16:19], v[68:71]
	v_mfma_f32_16x16x32_bf16 v[112:115], v[60:63], v[20:23], v[32:35]
	v_mfma_f32_16x16x32_bf16 v[32:35], v[4:7], v[224:227], v[72:75]
	v_mfma_f32_16x16x32_bf16 v[100:103], v[24:27], v[228:231], v[32:35]
	v_mfma_f32_16x16x32_bf16 v[32:35], v[28:31], v[224:227], v[76:79]
	v_mfma_f32_16x16x32_bf16 v[96:99], v[60:63], v[228:231], v[32:35]
	v_mfma_f32_16x16x32_bf16 v[32:35], v[4:7], v[232:235], v[80:83]
	v_mfma_f32_16x16x32_bf16 v[68:71], v[24:27], v[236:239], v[32:35]
	v_mfma_f32_16x16x32_bf16 v[32:35], v[28:31], v[232:235], v[84:87]
	v_mfma_f32_16x16x32_bf16 v[64:67], v[60:63], v[236:239], v[32:35]
	v_mfma_f32_16x16x32_bf16 v[32:35], v[4:7], v[240:243], v[88:91]
	v_mfma_f32_16x16x32_bf16 v[36:39], v[24:27], v[244:247], v[32:35]
	v_mfma_f32_16x16x32_bf16 v[32:35], v[28:31], v[240:243], v[92:95]
	v_mfma_f32_16x16x32_bf16 v[32:35], v[60:63], v[244:247], v[32:35]
	v_mfma_f32_16x16x32_bf16 v[72:75], v[200:203], v[16:19], v[104:107]
	v_mfma_f32_16x16x32_bf16 v[16:19], v[216:219], v[16:19], v[108:111]
	v_mfma_f32_16x16x32_bf16 v[120:123], v[220:223], v[20:23], v[16:19]
	v_mfma_f32_16x16x32_bf16 v[16:19], v[200:203], v[224:227], v[138:141]
	v_mfma_f32_16x16x32_bf16 v[108:111], v[212:215], v[228:231], v[16:19]
	v_mfma_f32_16x16x32_bf16 v[16:19], v[216:219], v[224:227], v[40:43]
	v_mfma_f32_16x16x32_bf16 v[104:107], v[220:223], v[228:231], v[16:19]
	v_mfma_f32_16x16x32_bf16 v[16:19], v[200:203], v[232:235], v[44:47]
	v_mfma_f32_16x16x32_bf16 v[76:79], v[212:215], v[236:239], v[16:19]
	v_mfma_f32_16x16x32_bf16 v[16:19], v[216:219], v[232:235], v[48:51]
	v_mfma_f32_16x16x32_bf16 v[124:127], v[212:215], v[20:23], v[72:75]
	v_mfma_f32_16x16x32_bf16 v[72:75], v[220:223], v[236:239], v[16:19]
	v_mfma_f32_16x16x32_bf16 v[16:19], v[200:203], v[240:243], v[52:55]
	v_mfma_f32_16x16x32_bf16 v[44:47], v[212:215], v[244:247], v[16:19]
	v_mfma_f32_16x16x32_bf16 v[16:19], v[216:219], v[240:243], v[56:59]
	v_mfma_f32_16x16x32_bf16 v[40:43], v[220:223], v[244:247], v[16:19]
	s_barrier
; #define PG8_WAIT_V(n) asm volatile("s_waitcnt vmcnt(" #n ")" ::: "memory")
; #define PG8_WAIT_VP() asm volatile("s_waitcnt vmcnt(%0)" :: "n"(8 + Epi::NST) : "memory")
; template <class Epi, class Sched>
; __device__ __forceinline__ void gemm_phase(PG8_LAS unsigned char* lds, const Sched& S, const Epi& E, int tid_in) {
;     ...
;         { const int t = 0; PG8_KITER(PG8_WAIT_VP()); }
;         for (int t = 2; t < nt; t += 2) PG8_KITER(PG8_WAIT_V(8));
	s_mov_b64 s[64:65], 0x180
	s_add_i32 s59, s59, s28
	s_nop 2
	v_lshl_add_u64 v[16:17], v[248:249], 0, s[64:65]
	s_mov_b32 m0, s59
	s_mov_b64 s[66:67], 0x40180
	s_add_i32 s60, s59, 0x2000
	ds_read_b128 v[56:59], v136 offset:49152
	ds_read_b128 v[88:91], v136 offset:50176
	ds_read_b128 v[138:141], v136 offset:51200
	ds_read_b128 v[224:227], v136 offset:52224
	ds_read_b128 v[228:231], v136 offset:53248
	ds_read_b128 v[232:235], v136 offset:54272
	ds_read_b128 v[236:239], v136 offset:55296
	ds_read_b128 v[240:243], v136 offset:56320
	global_load_lds_dwordx4 v[16:17], off
	v_lshl_add_u64 v[16:17], v[248:249], 0, s[66:67]
	s_mov_b32 m0, s60
	s_add_i32 s61, s61, s28
	global_load_lds_dwordx4 v[16:17], off
	v_lshl_add_u64 v[16:17], v[248:249], 0, s[70:71]
	s_mov_b32 m0, s61
	s_add_i32 s62, s61, 0x2000
	global_load_lds_dwordx4 v[16:17], off
	v_lshl_add_u64 v[16:17], v[248:249], 0, s[72:73]
	s_mov_b32 m0, s62
	s_nop 0
	global_load_lds_dwordx4 v[16:17], off
	v_lshl_add_u64 v[16:17], v[182:183], 0, s[64:65]
	s_mov_b32 m0, s45
	s_nop 0
	global_load_lds_dwordx4 v[16:17], off
	v_lshl_add_u64 v[16:17], v[182:183], 0, s[66:67]
	s_mov_b32 m0, s46
	s_nop 0
	global_load_lds_dwordx4 v[16:17], off
	s_waitcnt vmcnt(8)
	s_waitcnt lgkmcnt(0)
	s_barrier
	v_mfma_f32_16x16x32_bf16 v[16:19], v[4:7], v[56:59], v[142:145]
	v_mfma_f32_16x16x32_bf16 v[84:87], v[24:27], v[88:91], v[16:19]
	v_mfma_f32_16x16x32_bf16 v[16:19], v[28:31], v[56:59], v[146:149]
	v_mfma_f32_16x16x32_bf16 v[80:83], v[60:63], v[88:91], v[16:19]
	v_mfma_f32_16x16x32_bf16 v[16:19], v[4:7], v[138:141], v[150:153]
	v_mfma_f32_16x16x32_bf16 v[52:55], v[24:27], v[224:227], v[16:19]
	v_mfma_f32_16x16x32_bf16 v[16:19], v[28:31], v[138:141], v[154:157]
	v_mfma_f32_16x16x32_bf16 v[48:51], v[60:63], v[224:227], v[16:19]
	v_mfma_f32_16x16x32_bf16 v[16:19], v[4:7], v[228:231], v[158:161]
	v_mfma_f32_16x16x32_bf16 v[0:3], v[4:7], v[236:239], v[0:3]
	v_mfma_f32_16x16x32_bf16 v[20:23], v[24:27], v[232:235], v[16:19]
	v_mfma_f32_16x16x32_bf16 v[16:19], v[28:31], v[228:231], v[162:165]
	v_mfma_f32_16x16x32_bf16 v[4:7], v[24:27], v[240:243], v[0:3]
	v_mfma_f32_16x16x32_bf16 v[0:3], v[28:31], v[236:239], v[8:11]
	v_mfma_f32_16x16x32_bf16 v[16:19], v[60:63], v[232:235], v[16:19]
	v_mfma_f32_16x16x32_bf16 v[0:3], v[60:63], v[240:243], v[0:3]
	v_mfma_f32_16x16x32_bf16 v[8:11], v[200:203], v[56:59], v[12:15]
	v_mfma_f32_16x16x32_bf16 v[92:95], v[212:215], v[88:91], v[8:11]
	v_mfma_f32_16x16x32_bf16 v[8:11], v[216:219], v[56:59], v[166:169]
	v_mfma_f32_16x16x32_bf16 v[88:91], v[220:223], v[88:91], v[8:11]
	v_mfma_f32_16x16x32_bf16 v[8:11], v[200:203], v[138:141], v[170:173]
	v_mfma_f32_16x16x32_bf16 v[60:63], v[212:215], v[224:227], v[8:11]
	v_mfma_f32_16x16x32_bf16 v[8:11], v[216:219], v[138:141], v[174:177]
	v_mfma_f32_16x16x32_bf16 v[56:59], v[220:223], v[224:227], v[8:11]
	v_mfma_f32_16x16x32_bf16 v[8:11], v[200:203], v[228:231], v[178:181]
	v_mfma_f32_16x16x32_bf16 v[28:31], v[212:215], v[232:235], v[8:11]
	v_mfma_f32_16x16x32_bf16 v[8:11], v[216:219], v[228:231], v[188:191]
	v_mfma_f32_16x16x32_bf16 v[24:27], v[220:223], v[232:235], v[8:11]
	v_mfma_f32_16x16x32_bf16 v[8:11], v[200:203], v[236:239], v[192:195]
	v_mfma_f32_16x16x32_bf16 v[12:15], v[212:215], v[240:243], v[8:11]
	v_mfma_f32_16x16x32_bf16 v[8:11], v[216:219], v[236:239], v[196:199]
	v_mfma_f32_16x16x32_bf16 v[8:11], v[220:223], v[240:243], v[8:11]
	s_barrier
	s_add_u32 s18, s18, 0x80180
	s_addc_u32 s19, s19, 0
	s_add_u32 s63, s20, 0x200
	s_addc_u32 s64, s21, 0
	s_mov_b32 s65, 0
.LBB0_394:
	ds_read_b128 v[138:141], v134
	ds_read_b128 v[142:145], v134 offset:1024
	ds_read_b128 v[146:149], v134 offset:2048
	ds_read_b128 v[150:153], v134 offset:3072
	ds_read_b128 v[154:157], v135
	ds_read_b128 v[158:161], v135 offset:1024
	ds_read_b128 v[162:165], v135 offset:2048
	ds_read_b128 v[166:169], v135 offset:3072
	s_add_u32 s66, s18, 0xfff80080
	s_addc_u32 s67, s19, -1
	s_cmp_eq_u32 s65, 28
	s_cselect_b64 vcc, -1, 0
	s_and_b64 s[20:21], vcc, exec
	v_cndmask_b32_e32 v184, v132, v128, vcc
	s_cselect_b32 s21, s13, s67
	s_cselect_b32 s20, s12, s66
	v_cndmask_b32_e32 v182, v130, v129, vcc
	s_cselect_b32 s67, s15, s64
	s_cselect_b32 s66, s14, s63
	s_mov_b32 m0, s53
	v_lshl_add_u64 v[216:217], s[18:19], 0, v[132:133]
	ds_read_b128 v[170:173], v136
	ds_read_b128 v[174:177], v136 offset:1024
	ds_read_b128 v[178:181], v136 offset:2048
	ds_read_b128 v[188:191], v136 offset:3072
	ds_read_b128 v[192:195], v136 offset:4096
	ds_read_b128 v[196:199], v136 offset:5120
	ds_read_b128 v[200:203], v136 offset:6144
	ds_read_b128 v[212:215], v136 offset:7168
	global_load_lds_dwordx4 v[216:217], off
	v_lshl_add_u64 v[216:217], v[216:217], 0, s[88:89]
	s_mov_b32 m0, s54
	s_nop 0
	global_load_lds_dwordx4 v[216:217], off
	s_waitcnt vmcnt(8)
	s_waitcnt lgkmcnt(0)
	s_barrier
	v_mfma_f32_16x16x32_bf16 v[116:119], v[138:141], v[170:173], v[116:119]
	v_mfma_f32_16x16x32_bf16 v[112:115], v[146:149], v[170:173], v[112:115]
	v_mfma_f32_16x16x32_bf16 v[100:103], v[138:141], v[178:181], v[100:103]
	v_mfma_f32_16x16x32_bf16 v[96:99], v[146:149], v[178:181], v[96:99]
	v_mfma_f32_16x16x32_bf16 v[68:71], v[138:141], v[192:195], v[68:71]
	v_mfma_f32_16x16x32_bf16 v[64:67], v[146:149], v[192:195], v[64:67]
	v_mfma_f32_16x16x32_bf16 v[36:39], v[138:141], v[200:203], v[36:39]
	v_mfma_f32_16x16x32_bf16 v[32:35], v[146:149], v[200:203], v[32:35]
	v_mfma_f32_16x16x32_bf16 v[116:119], v[142:145], v[174:177], v[116:119]
	v_mfma_f32_16x16x32_bf16 v[112:115], v[150:153], v[174:177], v[112:115]
	v_mfma_f32_16x16x32_bf16 v[100:103], v[142:145], v[188:191], v[100:103]
	v_mfma_f32_16x16x32_bf16 v[96:99], v[150:153], v[188:191], v[96:99]
	v_mfma_f32_16x16x32_bf16 v[68:71], v[142:145], v[196:199], v[68:71]
	v_mfma_f32_16x16x32_bf16 v[64:67], v[150:153], v[196:199], v[64:67]
	v_mfma_f32_16x16x32_bf16 v[36:39], v[142:145], v[212:215], v[36:39]
	v_mfma_f32_16x16x32_bf16 v[32:35], v[150:153], v[212:215], v[32:35]
	v_mfma_f32_16x16x32_bf16 v[124:127], v[154:157], v[170:173], v[124:127]
	v_mfma_f32_16x16x32_bf16 v[120:123], v[162:165], v[170:173], v[120:123]
	v_mfma_f32_16x16x32_bf16 v[108:111], v[154:157], v[178:181], v[108:111]
	v_mfma_f32_16x16x32_bf16 v[104:107], v[162:165], v[178:181], v[104:107]
	v_mfma_f32_16x16x32_bf16 v[76:79], v[154:157], v[192:195], v[76:79]
	v_mfma_f32_16x16x32_bf16 v[72:75], v[162:165], v[192:195], v[72:75]
	v_mfma_f32_16x16x32_bf16 v[44:47], v[154:157], v[200:203], v[44:47]
	v_mfma_f32_16x16x32_bf16 v[40:43], v[162:165], v[200:203], v[40:43]
	v_mfma_f32_16x16x32_bf16 v[124:127], v[158:161], v[174:177], v[124:127]
	v_mfma_f32_16x16x32_bf16 v[120:123], v[166:169], v[174:177], v[120:123]
	v_mfma_f32_16x16x32_bf16 v[108:111], v[158:161], v[188:191], v[108:111]
	v_mfma_f32_16x16x32_bf16 v[104:107], v[166:169], v[188:191], v[104:107]
	v_mfma_f32_16x16x32_bf16 v[76:79], v[158:161], v[196:199], v[76:79]
	v_mfma_f32_16x16x32_bf16 v[72:75], v[166:169], v[196:199], v[72:75]
	v_mfma_f32_16x16x32_bf16 v[44:47], v[158:161], v[212:215], v[44:47]
	v_mfma_f32_16x16x32_bf16 v[40:43], v[166:169], v[212:215], v[40:43]
	s_barrier
	v_mov_b32_e32 v183, v185
	s_mov_b32 m0, s55
	v_lshl_add_u64 v[216:217], s[66:67], 0, v[182:183]
	ds_read_b128 v[170:173], v136 offset:16384
	ds_read_b128 v[174:177], v136 offset:17408
	ds_read_b128 v[178:181], v136 offset:18432
	ds_read_b128 v[188:191], v136 offset:19456
	ds_read_b128 v[192:195], v136 offset:20480
	ds_read_b128 v[196:199], v136 offset:21504
	ds_read_b128 v[200:203], v136 offset:22528
	ds_read_b128 v[212:215], v136 offset:23552
	global_load_lds_dwordx4 v182, s[66:67]
	v_lshl_add_u64 v[182:183], v[216:217], 0, s[88:89]
	s_mov_b32 m0, s56
	s_nop 0
	global_load_lds_dwordx4 v[182:183], off
	v_lshl_add_u64 v[182:183], v[216:217], 0, s[90:91]
	s_mov_b32 m0, s57
	s_nop 0
	global_load_lds_dwordx4 v[182:183], off
	v_lshl_add_u64 v[182:183], v[216:217], 0, s[96:97]
	s_mov_b32 m0, s58
	s_nop 0
	global_load_lds_dwordx4 v[182:183], off
	v_lshl_add_u64 v[182:183], s[20:21], 0, v[184:185]
	s_mov_b32 m0, s29
	v_lshl_add_u64 v[218:219], v[182:183], 0, s[88:89]
	global_load_lds_dwordx4 v[182:183], off
	s_mov_b32 m0, s30
	s_nop 0
	global_load_lds_dwordx4 v[218:219], off
	s_waitcnt vmcnt(8)
	s_waitcnt lgkmcnt(0)
	s_barrier
	v_mfma_f32_16x16x32_bf16 v[84:87], v[138:141], v[170:173], v[84:87]
	v_mfma_f32_16x16x32_bf16 v[80:83], v[146:149], v[170:173], v[80:83]
	v_mfma_f32_16x16x32_bf16 v[52:55], v[138:141], v[178:181], v[52:55]
	v_mfma_f32_16x16x32_bf16 v[48:51], v[146:149], v[178:181], v[48:51]
	v_mfma_f32_16x16x32_bf16 v[20:23], v[138:141], v[192:195], v[20:23]
	v_mfma_f32_16x16x32_bf16 v[16:19], v[146:149], v[192:195], v[16:19]
	v_mfma_f32_16x16x32_bf16 v[4:7], v[138:141], v[200:203], v[4:7]
	v_mfma_f32_16x16x32_bf16 v[0:3], v[146:149], v[200:203], v[0:3]
	v_mfma_f32_16x16x32_bf16 v[84:87], v[142:145], v[174:177], v[84:87]
	v_mfma_f32_16x16x32_bf16 v[80:83], v[150:153], v[174:177], v[80:83]
	v_mfma_f32_16x16x32_bf16 v[52:55], v[142:145], v[188:191], v[52:55]
	v_mfma_f32_16x16x32_bf16 v[48:51], v[150:153], v[188:191], v[48:51]
	v_mfma_f32_16x16x32_bf16 v[20:23], v[142:145], v[196:199], v[20:23]
	v_mfma_f32_16x16x32_bf16 v[16:19], v[150:153], v[196:199], v[16:19]
	v_mfma_f32_16x16x32_bf16 v[4:7], v[142:145], v[212:215], v[4:7]
	v_mfma_f32_16x16x32_bf16 v[0:3], v[150:153], v[212:215], v[0:3]
	v_mfma_f32_16x16x32_bf16 v[92:95], v[154:157], v[170:173], v[92:95]
	v_mfma_f32_16x16x32_bf16 v[88:91], v[162:165], v[170:173], v[88:91]
	v_mfma_f32_16x16x32_bf16 v[60:63], v[154:157], v[178:181], v[60:63]
	v_mfma_f32_16x16x32_bf16 v[56:59], v[162:165], v[178:181], v[56:59]
	v_mfma_f32_16x16x32_bf16 v[28:31], v[154:157], v[192:195], v[28:31]
	v_mfma_f32_16x16x32_bf16 v[24:27], v[162:165], v[192:195], v[24:27]
	v_mfma_f32_16x16x32_bf16 v[12:15], v[154:157], v[200:203], v[12:15]
	v_mfma_f32_16x16x32_bf16 v[8:11], v[162:165], v[200:203], v[8:11]
	v_mfma_f32_16x16x32_bf16 v[92:95], v[158:161], v[174:177], v[92:95]
	v_mfma_f32_16x16x32_bf16 v[88:91], v[166:169], v[174:177], v[88:91]
	v_mfma_f32_16x16x32_bf16 v[60:63], v[158:161], v[188:191], v[60:63]
	v_mfma_f32_16x16x32_bf16 v[56:59], v[166:169], v[188:191], v[56:59]
	v_mfma_f32_16x16x32_bf16 v[28:31], v[158:161], v[196:199], v[28:31]
	v_mfma_f32_16x16x32_bf16 v[24:27], v[166:169], v[196:199], v[24:27]
	v_mfma_f32_16x16x32_bf16 v[12:15], v[158:161], v[212:215], v[12:15]
	v_mfma_f32_16x16x32_bf16 v[8:11], v[166:169], v[212:215], v[8:11]
	s_barrier
; #define PG8_WAIT_V(n) asm volatile("s_waitcnt vmcnt(" #n ")" ::: "memory")
; #define PG8_WAIT_VP() asm volatile("s_waitcnt vmcnt(%0)" :: "n"(8 + Epi::NST) : "memory")
; #define PG8_BAR __builtin_amdgcn_s_barrier()
; template <class Epi, class Sched>
; __device__ __forceinline__ void gemm_phase(PG8_LAS unsigned char* lds, const Sched& S, const Epi& E, int tid_in) {
;     ...
;         { const int t = 0; PG8_KITER(PG8_WAIT_VP()); }
;         for (int t = 2; t < nt; t += 2) PG8_KITER(PG8_WAIT_V(8));
;     ...
;         if (wr == 0) PG8_BAR;
	ds_read_b128 v[138:141], v131
	ds_read_b128 v[142:145], v131 offset:1024
	ds_read_b128 v[146:149], v131 offset:2048
	ds_read_b128 v[150:153], v131 offset:3072
	ds_read_b128 v[154:157], v137
	ds_read_b128 v[158:161], v137 offset:1024
	ds_read_b128 v[162:165], v137 offset:2048
	ds_read_b128 v[166:169], v137 offset:3072
	s_mov_b32 m0, s31
	v_lshl_add_u64 v[218:219], v[182:183], 0, s[90:91]
	ds_read_b128 v[170:173], v136 offset:32768
	ds_read_b128 v[174:177], v136 offset:33792
	ds_read_b128 v[178:181], v136 offset:34816
	ds_read_b128 v[188:191], v136 offset:35840
	ds_read_b128 v[192:195], v136 offset:36864
	ds_read_b128 v[196:199], v136 offset:37888
	ds_read_b128 v[200:203], v136 offset:38912
	ds_read_b128 v[212:215], v136 offset:39936
	global_load_lds_dwordx4 v[218:219], off
	v_lshl_add_u64 v[218:219], v[182:183], 0, s[96:97]
	s_mov_b32 m0, s34
	s_nop 0
	global_load_lds_dwordx4 v[218:219], off
	s_waitcnt vmcnt(8)
	s_waitcnt lgkmcnt(0)
	s_barrier
	v_mfma_f32_16x16x32_bf16 v[116:119], v[138:141], v[170:173], v[116:119]
	v_mfma_f32_16x16x32_bf16 v[112:115], v[146:149], v[170:173], v[112:115]
	v_mfma_f32_16x16x32_bf16 v[100:103], v[138:141], v[178:181], v[100:103]
	v_mfma_f32_16x16x32_bf16 v[96:99], v[146:149], v[178:181], v[96:99]
	v_mfma_f32_16x16x32_bf16 v[68:71], v[138:141], v[192:195], v[68:71]
	v_mfma_f32_16x16x32_bf16 v[64:67], v[146:149], v[192:195], v[64:67]
	v_mfma_f32_16x16x32_bf16 v[36:39], v[138:141], v[200:203], v[36:39]
	v_mfma_f32_16x16x32_bf16 v[32:35], v[146:149], v[200:203], v[32:35]
	v_mfma_f32_16x16x32_bf16 v[116:119], v[142:145], v[174:177], v[116:119]
	v_mfma_f32_16x16x32_bf16 v[112:115], v[150:153], v[174:177], v[112:115]
	v_mfma_f32_16x16x32_bf16 v[100:103], v[142:145], v[188:191], v[100:103]
	v_mfma_f32_16x16x32_bf16 v[96:99], v[150:153], v[188:191], v[96:99]
	v_mfma_f32_16x16x32_bf16 v[68:71], v[142:145], v[196:199], v[68:71]
	v_mfma_f32_16x16x32_bf16 v[64:67], v[150:153], v[196:199], v[64:67]
	v_mfma_f32_16x16x32_bf16 v[36:39], v[142:145], v[212:215], v[36:39]
	v_mfma_f32_16x16x32_bf16 v[32:35], v[150:153], v[212:215], v[32:35]
	v_mfma_f32_16x16x32_bf16 v[124:127], v[154:157], v[170:173], v[124:127]
	v_mfma_f32_16x16x32_bf16 v[120:123], v[162:165], v[170:173], v[120:123]
	v_mfma_f32_16x16x32_bf16 v[108:111], v[154:157], v[178:181], v[108:111]
	v_mfma_f32_16x16x32_bf16 v[104:107], v[162:165], v[178:181], v[104:107]
	v_mfma_f32_16x16x32_bf16 v[76:79], v[154:157], v[192:195], v[76:79]
	v_mfma_f32_16x16x32_bf16 v[72:75], v[162:165], v[192:195], v[72:75]
	v_mfma_f32_16x16x32_bf16 v[44:47], v[154:157], v[200:203], v[44:47]
	v_mfma_f32_16x16x32_bf16 v[40:43], v[162:165], v[200:203], v[40:43]
	v_mfma_f32_16x16x32_bf16 v[124:127], v[158:161], v[174:177], v[124:127]
	v_mfma_f32_16x16x32_bf16 v[120:123], v[166:169], v[174:177], v[120:123]
	v_mfma_f32_16x16x32_bf16 v[108:111], v[158:161], v[188:191], v[108:111]
	v_mfma_f32_16x16x32_bf16 v[104:107], v[166:169], v[188:191], v[104:107]
	v_mfma_f32_16x16x32_bf16 v[76:79], v[158:161], v[196:199], v[76:79]
	v_mfma_f32_16x16x32_bf16 v[72:75], v[166:169], v[196:199], v[72:75]
	v_mfma_f32_16x16x32_bf16 v[44:47], v[158:161], v[212:215], v[44:47]
	v_mfma_f32_16x16x32_bf16 v[40:43], v[166:169], v[212:215], v[40:43]
	s_barrier
	s_mov_b32 m0, s59
	v_lshl_add_u64 v[218:219], v[216:217], 0, s[84:85]
	ds_read_b128 v[170:173], v136 offset:49152
	ds_read_b128 v[174:177], v136 offset:50176
	ds_read_b128 v[178:181], v136 offset:51200
	ds_read_b128 v[188:191], v136 offset:52224
	ds_read_b128 v[192:195], v136 offset:53248
	ds_read_b128 v[196:199], v136 offset:54272
	ds_read_b128 v[200:203], v136 offset:55296
	ds_read_b128 v[212:215], v136 offset:56320
	global_load_lds_dwordx4 v[218:219], off
	v_lshl_add_u64 v[218:219], v[216:217], 0, s[94:95]
	s_mov_b32 m0, s60
	s_nop 0
	global_load_lds_dwordx4 v[218:219], off
	v_lshl_add_u64 v[218:219], v[216:217], 0, s[80:81]
	s_mov_b32 m0, s61
	v_lshl_add_u64 v[216:217], v[216:217], 0, s[78:79]
	global_load_lds_dwordx4 v[218:219], off
	s_mov_b32 m0, s62
	s_nop 0
	global_load_lds_dwordx4 v[216:217], off
	v_lshl_add_u64 v[216:217], v[182:183], 0, s[84:85]
	s_mov_b32 m0, s45
	v_lshl_add_u64 v[182:183], v[182:183], 0, s[94:95]
	global_load_lds_dwordx4 v[216:217], off
	s_mov_b32 m0, s46
	s_nop 0
	global_load_lds_dwordx4 v[182:183], off
	s_waitcnt vmcnt(8)
	s_waitcnt lgkmcnt(0)
	s_barrier
	v_mfma_f32_16x16x32_bf16 v[84:87], v[138:141], v[170:173], v[84:87]
	v_mfma_f32_16x16x32_bf16 v[80:83], v[146:149], v[170:173], v[80:83]
	v_mfma_f32_16x16x32_bf16 v[52:55], v[138:141], v[178:181], v[52:55]
	v_mfma_f32_16x16x32_bf16 v[48:51], v[146:149], v[178:181], v[48:51]
	v_mfma_f32_16x16x32_bf16 v[20:23], v[138:141], v[192:195], v[20:23]
	v_mfma_f32_16x16x32_bf16 v[16:19], v[146:149], v[192:195], v[16:19]
	v_mfma_f32_16x16x32_bf16 v[4:7], v[138:141], v[200:203], v[4:7]
	v_mfma_f32_16x16x32_bf16 v[0:3], v[146:149], v[200:203], v[0:3]
	v_mfma_f32_16x16x32_bf16 v[84:87], v[142:145], v[174:177], v[84:87]
	v_mfma_f32_16x16x32_bf16 v[80:83], v[150:153], v[174:177], v[80:83]
	v_mfma_f32_16x16x32_bf16 v[52:55], v[142:145], v[188:191], v[52:55]
	v_mfma_f32_16x16x32_bf16 v[48:51], v[150:153], v[188:191], v[48:51]
	v_mfma_f32_16x16x32_bf16 v[20:23], v[142:145], v[196:199], v[20:23]
	v_mfma_f32_16x16x32_bf16 v[16:19], v[150:153], v[196:199], v[16:19]
	v_mfma_f32_16x16x32_bf16 v[4:7], v[142:145], v[212:215], v[4:7]
	v_mfma_f32_16x16x32_bf16 v[0:3], v[150:153], v[212:215], v[0:3]
	v_mfma_f32_16x16x32_bf16 v[92:95], v[154:157], v[170:173], v[92:95]
	v_mfma_f32_16x16x32_bf16 v[88:91], v[162:165], v[170:173], v[88:91]
	v_mfma_f32_16x16x32_bf16 v[60:63], v[154:157], v[178:181], v[60:63]
	v_mfma_f32_16x16x32_bf16 v[56:59], v[162:165], v[178:181], v[56:59]
	v_mfma_f32_16x16x32_bf16 v[28:31], v[154:157], v[192:195], v[28:31]
	v_mfma_f32_16x16x32_bf16 v[24:27], v[162:165], v[192:195], v[24:27]
	v_mfma_f32_16x16x32_bf16 v[12:15], v[154:157], v[200:203], v[12:15]
	v_mfma_f32_16x16x32_bf16 v[8:11], v[162:165], v[200:203], v[8:11]
	v_mfma_f32_16x16x32_bf16 v[92:95], v[158:161], v[174:177], v[92:95]
	v_mfma_f32_16x16x32_bf16 v[88:91], v[166:169], v[174:177], v[88:91]
	v_mfma_f32_16x16x32_bf16 v[60:63], v[158:161], v[188:191], v[60:63]
	v_mfma_f32_16x16x32_bf16 v[56:59], v[166:169], v[188:191], v[56:59]
	v_mfma_f32_16x16x32_bf16 v[28:31], v[158:161], v[196:199], v[28:31]
	v_mfma_f32_16x16x32_bf16 v[24:27], v[166:169], v[196:199], v[24:27]
	v_mfma_f32_16x16x32_bf16 v[12:15], v[158:161], v[212:215], v[12:15]
	v_mfma_f32_16x16x32_bf16 v[8:11], v[166:169], v[212:215], v[8:11]
	s_barrier
	s_add_i32 s65, s65, 2
	s_add_u32 s18, s18, 0x100
	s_addc_u32 s19, s19, 0
	s_add_u32 s63, s63, 0x100
	s_addc_u32 s64, s64, 0
	s_cmp_gt_u32 s65, 29
	s_cbranch_scc0 .LBB0_394
	s_and_b64 vcc, exec, s[10:11]
	s_cbranch_vccz .LBB0_397
	s_barrier

; __device__ __forceinline__ int lane_id() { int l; asm volatile("v_mbcnt_lo_u32_b32 %0, -1, 0\n\tv_mbcnt_hi_u32_b32 %0, -1, %0" : "=v"(l)); return l; }
;     __device__ __forceinline__ bool next(int i, UnitG& u) const { if (!P.next(i, u)) return false; u.O = O + ((size_t)u.x0 * 256 * 2048 + (size_t)u.x1 * 256) * 2; u.ldo = 2048; u.kind = 0; return true; }
; template <class Epi, class Sched>
; __device__ __forceinline__ void gemm_phase(PG8_LAS unsigned char* lds, const Sched& S, const Epi& E, int tid_in) {
;     ...
;         int aoff, boff; { const int l3 = lane_id(), fr3 = l3 & 15, fq3 = l3 >> 4; aoff = lds_byte(wr * 64 + fr3, fq3 * 8); boff = lds_byte(wc * 32 + fr3, fq3 * 8); }
;         const bool has_next = S.next(ui + 1, nxt);
;         const char* nA = has_next ? nxt.A : cA; const char* nB = has_next ? nxt.B : cB;
;         const int nlda = has_next ? nxt.lda : cur.lda, nldb = has_next ? nxt.ldb : cur.ldb;
;         unsigned nvA, nvB; { int r2, c2; stage_rc((wid * 64 + lane_id()) * 16, r2, c2); const int rb2 = Epi::PERM ? ((r2 & ~31) + perm32(r2 & 31)) : r2;
;             nvA = (unsigned)(r2 * nlda + c2) * 2u; nvB = (unsigned)(rb2 * nldb + c2) * 2u; }
;         const unsigned nqA = (unsigned)nlda * 128u, nqB = (unsigned)nldb * 128u;
;         const int nt = cur.K / BK;
.LBB0_541:
	v_and_b32_e32 v1, 15, v0
	v_or_b32_e32 v2, s56, v1
	v_ashrrev_i32_e32 v3, 6, v0
	v_lshlrev_b32_e32 v4, 6, v2
	v_and_b32_e32 v5, 48, v0
	s_movk_i32 s22, 0x3c0
	v_lshlrev_b32_e32 v2, 2, v2
	v_and_or_b32 v4, v4, s22, v5
	v_lshl_add_u32 v6, v3, 10, s57
	v_and_b32_e32 v2, 32, v2
	v_lshlrev_b32_e32 v0, 2, v0
	s_nop 0
	v_bitop3_b32 v32, v4, v6, v2 bitop3:0xde
	v_lshl_or_b32 v1, v1, 6, v5
	v_add_lshl_u32 v2, v3, s59, 10
	v_and_b32_e32 v0, 32, v0
	v_bitop3_b32 v186, v1, v2, v0 bitop3:0xde
	v_mbcnt_lo_u32_b32 v0, -1, 0
	v_mbcnt_hi_u32_b32 v0, -1, v0
	s_mov_b32 s22, 0x1ffffe0
	v_add_u32_e32 v0, s60, v0
	v_ashrrev_i32_e32 v2, 31, v0
	v_lshrrev_b32_e32 v2, 26, v2
	v_lshlrev_b32_e32 v1, 4, v0
	v_add_u32_e32 v2, v0, v2
	v_bfe_i32 v0, v0, 27, 1
	v_lshrrev_b32_e32 v0, 22, v0
	v_add_u32_e32 v0, v1, v0
	v_and_b32_e32 v0, 0xfffffc00, v0
	v_sub_u32_e32 v0, v1, v0
	v_lshrrev_b32_e32 v1, 4, v0
	v_bitop3_b32 v0, v1, v0, 32 bitop3:0x6c
	v_ashrrev_i32_e32 v3, 31, v0
	v_lshrrev_b32_e32 v3, 26, v3
	v_ashrrev_i32_e32 v2, 6, v2
	v_add_u32_e32 v3, v0, v3
	v_lshlrev_b32_e32 v1, 3, v2
	v_ashrrev_i32_e32 v4, 6, v3
	v_and_b32_e32 v3, 0xc0, v3
	v_and_b32_e32 v1, -16, v1
	v_lshlrev_b32_e32 v2, 5, v2
	v_sub_u32_e32 v0, v0, v3
	v_add_u32_e32 v1, v4, v1
	v_and_b32_e32 v2, 32, v2
	v_ashrrev_i16_sdwa v0, v205, sext(v0) dst_sel:DWORD dst_unused:UNUSED_PAD src0_sel:DWORD src1_sel:BYTE_0
	v_add_u32_sdwa v68, v2, sext(v0) dst_sel:DWORD dst_unused:UNUSED_PAD src0_sel:DWORD src1_sel:WORD_0
	v_lshlrev_b32_e32 v0, 1, v1
	v_lshrrev_b32_e32 v2, 2, v1
	v_and_b32_e32 v3, 3, v4
	v_and_b32_e32 v0, 24, v0
	v_and_b32_e32 v2, 4, v2
	v_and_or_b32 v3, v1, s22, v3
	v_or3_b32 v0, v3, v2, v0
	s_movk_i32 s22, 0x180
	v_mul_lo_u32 v69, v1, s22
	v_mul_lo_u32 v0, v0, s22
	s_add_i32 s22, 0, 0x10000
	s_add_i32 s23, 0, 0x14000
	v_add_u32_e32 v12, s22, v186
	v_add_u32_e32 v28, s23, v186
	v_add_lshl_u32 v128, v0, v68, 1
	ds_read_b128 v[0:3], v12
	ds_read_b128 v[4:7], v12 offset:1024
	ds_read_b128 v[8:11], v12 offset:2048
	ds_read_b128 v[12:15], v12 offset:3072
	ds_read_b128 v[16:19], v28
	ds_read_b128 v[20:23], v28 offset:1024
	ds_read_b128 v[24:27], v28 offset:2048
	ds_read_b128 v[28:31], v28 offset:3072
	v_lshl_add_u64 v[64:65], s[20:21], 0, v[184:185]
	s_mov_b64 s[66:67], 0x18080
	v_add_u32_e32 v187, 0, v32
	v_lshl_add_u64 v[66:67], v[64:65], 0, s[66:67]
	s_add_i32 m0, s49, 0xc000
	s_mov_b64 s[70:71], 0x24080
	ds_read_b128 v[32:35], v187
	ds_read_b128 v[36:39], v187 offset:1024
	ds_read_b128 v[40:43], v187 offset:2048
	ds_read_b128 v[44:47], v187 offset:3072
	ds_read_b128 v[48:51], v187 offset:4096
	ds_read_b128 v[52:55], v187 offset:5120
	ds_read_b128 v[56:59], v187 offset:6144
	ds_read_b128 v[60:63], v187 offset:7168
	global_load_lds_dwordx4 v[66:67], off
	v_lshl_add_u64 v[64:65], v[64:65], 0, s[70:71]
	s_add_i32 m0, s49, 0xe000
	v_add_lshl_u32 v134, v68, v69, 1
	global_load_lds_dwordx4 v[64:65], off
	s_waitcnt vmcnt(24)
	s_waitcnt lgkmcnt(0)
	s_barrier
	v_mfma_f32_16x16x32_bf16 v[88:91], v[0:3], v[56:59], 0
	v_mfma_f32_16x16x32_bf16 v[64:67], v[0:3], v[32:35], 0
	v_mfma_f32_16x16x32_bf16 v[68:71], v[8:11], v[32:35], 0
	v_mfma_f32_16x16x32_bf16 v[72:75], v[0:3], v[40:43], 0
	v_mfma_f32_16x16x32_bf16 v[76:79], v[8:11], v[40:43], 0
	v_mfma_f32_16x16x32_bf16 v[80:83], v[0:3], v[48:51], 0
	v_mfma_f32_16x16x32_bf16 v[84:87], v[8:11], v[48:51], 0
	v_mfma_f32_16x16x32_bf16 v[96:99], v[4:7], v[60:63], v[88:91]
	v_mfma_f32_16x16x32_bf16 v[88:91], v[8:11], v[56:59], 0
	v_mfma_f32_16x16x32_bf16 v[64:67], v[4:7], v[36:39], v[64:67]
	v_mfma_f32_16x16x32_bf16 v[68:71], v[12:15], v[36:39], v[68:71]
	v_mfma_f32_16x16x32_bf16 v[72:75], v[4:7], v[44:47], v[72:75]
	v_mfma_f32_16x16x32_bf16 v[76:79], v[12:15], v[44:47], v[76:79]
	v_mfma_f32_16x16x32_bf16 v[80:83], v[4:7], v[52:55], v[80:83]
	v_mfma_f32_16x16x32_bf16 v[84:87], v[12:15], v[52:55], v[84:87]
	v_mfma_f32_16x16x32_bf16 v[100:103], v[12:15], v[60:63], v[88:91]
	v_mfma_f32_16x16x32_bf16 v[88:91], v[16:19], v[32:35], 0
	v_mfma_f32_16x16x32_bf16 v[32:35], v[24:27], v[32:35], 0
	v_mfma_f32_16x16x32_bf16 v[112:115], v[20:23], v[36:39], v[88:91]
	v_mfma_f32_16x16x32_bf16 v[32:35], v[28:31], v[36:39], v[32:35]
	v_mfma_f32_16x16x32_bf16 v[36:39], v[16:19], v[40:43], 0
	v_mfma_f32_16x16x32_bf16 v[40:43], v[24:27], v[40:43], 0
	v_mfma_f32_16x16x32_bf16 v[36:39], v[20:23], v[44:47], v[36:39]
	v_mfma_f32_16x16x32_bf16 v[40:43], v[28:31], v[44:47], v[40:43]
	v_mfma_f32_16x16x32_bf16 v[44:47], v[16:19], v[48:51], 0
	v_mfma_f32_16x16x32_bf16 v[48:51], v[24:27], v[48:51], 0
	v_mfma_f32_16x16x32_bf16 v[44:47], v[20:23], v[52:55], v[44:47]
	v_mfma_f32_16x16x32_bf16 v[48:51], v[28:31], v[52:55], v[48:51]
	v_mfma_f32_16x16x32_bf16 v[52:55], v[16:19], v[56:59], 0
	v_mfma_f32_16x16x32_bf16 v[56:59], v[24:27], v[56:59], 0
	v_mfma_f32_16x16x32_bf16 v[52:55], v[20:23], v[60:63], v[52:55]
	v_mfma_f32_16x16x32_bf16 v[56:59], v[28:31], v[60:63], v[56:59]
	s_barrier
	v_mov_b32_e32 v129, v185
	s_add_i32 s20, s22, s47
	v_lshl_add_u64 v[240:241], s[8:9], 0, v[128:129]
	s_mov_b32 m0, s20
	s_mov_b64 s[24:25], 0xc000
	ds_read_b128 v[60:63], v187 offset:16384
	ds_read_b128 v[88:91], v187 offset:17408
	ds_read_b128 v[92:95], v187 offset:18432
	ds_read_b128 v[104:107], v187 offset:19456
	ds_read_b128 v[108:111], v187 offset:20480
	ds_read_b128 v[116:119], v187 offset:21504
	ds_read_b128 v[120:123], v187 offset:22528
	ds_read_b128 v[124:127], v187 offset:23552
	global_load_lds_dwordx4 v128, s[8:9]
	v_lshl_add_u64 v[128:129], v[240:241], 0, s[24:25]
	s_add_i32 m0, s20, 0x2000
	s_mov_b64 s[64:65], 0x18000
	s_add_i32 s20, s23, s47
	global_load_lds_dwordx4 v[128:129], off
	v_lshl_add_u64 v[128:129], v[240:241], 0, s[64:65]
	s_mov_b32 m0, s20
	s_mov_b64 s[22:23], 0x24000
	global_load_lds_dwordx4 v[128:129], off
	v_lshl_add_u64 v[128:129], v[240:241], 0, s[22:23]
	s_add_i32 m0, s20, 0x2000
	v_mov_b32_e32 v135, v185
	global_load_lds_dwordx4 v[128:129], off
	v_lshl_add_u64 v[242:243], s[16:17], 0, v[134:135]
	s_mov_b32 m0, s49
	v_lshl_add_u64 v[128:129], v[242:243], 0, s[24:25]
	global_load_lds_dwordx4 v134, s[16:17]
	s_mov_b32 m0, s51
	s_nop 0
	global_load_lds_dwordx4 v[128:129], off
	s_waitcnt vmcnt(24)
	s_waitcnt lgkmcnt(0)
	s_barrier
	v_mfma_f32_16x16x32_bf16 v[128:131], v[0:3], v[60:63], 0
	v_mfma_f32_16x16x32_bf16 v[140:143], v[0:3], v[92:95], 0
	v_mfma_f32_16x16x32_bf16 v[148:151], v[0:3], v[108:111], 0
	v_mfma_f32_16x16x32_bf16 v[0:3], v[0:3], v[120:123], 0
	v_mfma_f32_16x16x32_bf16 v[128:131], v[4:7], v[88:91], v[128:131]
	v_mfma_f32_16x16x32_bf16 v[140:143], v[4:7], v[104:107], v[140:143]
	v_mfma_f32_16x16x32_bf16 v[148:151], v[4:7], v[116:119], v[148:151]
	v_mfma_f32_16x16x32_bf16 v[0:3], v[4:7], v[124:127], v[0:3]
	v_mfma_f32_16x16x32_bf16 v[4:7], v[8:11], v[120:123], 0
	v_mfma_f32_16x16x32_bf16 v[136:139], v[8:11], v[60:63], 0
	v_mfma_f32_16x16x32_bf16 v[144:147], v[8:11], v[92:95], 0
	v_mfma_f32_16x16x32_bf16 v[152:155], v[8:11], v[108:111], 0
	v_mfma_f32_16x16x32_bf16 v[4:7], v[12:15], v[124:127], v[4:7]
	v_mfma_f32_16x16x32_bf16 v[136:139], v[12:15], v[88:91], v[136:139]
	v_mfma_f32_16x16x32_bf16 v[144:147], v[12:15], v[104:107], v[144:147]
	v_mfma_f32_16x16x32_bf16 v[152:155], v[12:15], v[116:119], v[152:155]
	v_mfma_f32_16x16x32_bf16 v[8:11], v[16:19], v[60:63], 0
	v_mfma_f32_16x16x32_bf16 v[156:159], v[20:23], v[88:91], v[8:11]
	v_mfma_f32_16x16x32_bf16 v[8:11], v[24:27], v[60:63], 0
	v_mfma_f32_16x16x32_bf16 v[160:163], v[28:31], v[88:91], v[8:11]
	v_mfma_f32_16x16x32_bf16 v[8:11], v[16:19], v[92:95], 0
	v_mfma_f32_16x16x32_bf16 v[164:167], v[20:23], v[104:107], v[8:11]
	v_mfma_f32_16x16x32_bf16 v[8:11], v[24:27], v[92:95], 0
	v_mfma_f32_16x16x32_bf16 v[168:171], v[28:31], v[104:107], v[8:11]
	v_mfma_f32_16x16x32_bf16 v[8:11], v[16:19], v[108:111], 0
	v_mfma_f32_16x16x32_bf16 v[172:175], v[20:23], v[116:119], v[8:11]
	v_mfma_f32_16x16x32_bf16 v[8:11], v[24:27], v[108:111], 0
	v_mfma_f32_16x16x32_bf16 v[176:179], v[28:31], v[116:119], v[8:11]
	v_mfma_f32_16x16x32_bf16 v[8:11], v[16:19], v[120:123], 0
	v_mfma_f32_16x16x32_bf16 v[180:183], v[20:23], v[124:127], v[8:11]
	v_mfma_f32_16x16x32_bf16 v[8:11], v[24:27], v[120:123], 0
	v_mfma_f32_16x16x32_bf16 v[188:191], v[28:31], v[124:127], v[8:11]
	s_barrier
	s_add_i32 s20, 0, 0x18000
	s_add_i32 s21, 0, 0x1c000
	v_add_u32_e32 v20, s20, v186
	v_add_u32_e32 v24, s21, v186
	s_nop 0
	ds_read_b128 v[8:11], v20
	ds_read_b128 v[12:15], v20 offset:1024
	ds_read_b128 v[16:19], v20 offset:2048
	ds_read_b128 v[20:23], v20 offset:3072
	ds_read_b128 v[192:195], v24
	ds_read_b128 v[196:199], v24 offset:1024
	ds_read_b128 v[200:203], v24 offset:2048
	ds_read_b128 v[212:215], v24 offset:3072
	s_mov_b32 m0, s52
	v_lshl_add_u64 v[88:89], v[242:243], 0, s[64:65]
	ds_read_b128 v[24:27], v187 offset:32768
	ds_read_b128 v[28:31], v187 offset:33792
	ds_read_b128 v[60:63], v187 offset:34816
	ds_read_b128 v[216:219], v187 offset:35840
	ds_read_b128 v[220:223], v187 offset:36864
	ds_read_b128 v[224:227], v187 offset:37888
	ds_read_b128 v[228:231], v187 offset:38912
	ds_read_b128 v[232:235], v187 offset:39936
	global_load_lds_dwordx4 v[88:89], off
	v_lshl_add_u64 v[88:89], v[242:243], 0, s[22:23]
	s_mov_b32 m0, s53
	s_nop 0
	global_load_lds_dwordx4 v[88:89], off
	s_waitcnt vmcnt(8)
	s_waitcnt lgkmcnt(0)
	s_barrier
	v_mfma_f32_16x16x32_bf16 v[64:67], v[8:11], v[24:27], v[64:67]
	v_mfma_f32_16x16x32_bf16 v[124:127], v[12:15], v[28:31], v[64:67]
	v_mfma_f32_16x16x32_bf16 v[64:67], v[16:19], v[24:27], v[68:71]
	v_mfma_f32_16x16x32_bf16 v[120:123], v[20:23], v[28:31], v[64:67]
	v_mfma_f32_16x16x32_bf16 v[64:67], v[8:11], v[60:63], v[72:75]
	v_mfma_f32_16x16x32_bf16 v[108:111], v[12:15], v[216:219], v[64:67]
	v_mfma_f32_16x16x32_bf16 v[64:67], v[16:19], v[60:63], v[76:79]
	v_mfma_f32_16x16x32_bf16 v[104:107], v[20:23], v[216:219], v[64:67]
	v_mfma_f32_16x16x32_bf16 v[64:67], v[8:11], v[220:223], v[80:83]
	v_mfma_f32_16x16x32_bf16 v[92:95], v[12:15], v[224:227], v[64:67]
	v_mfma_f32_16x16x32_bf16 v[64:67], v[16:19], v[220:223], v[84:87]
	v_mfma_f32_16x16x32_bf16 v[88:91], v[20:23], v[224:227], v[64:67]
	v_mfma_f32_16x16x32_bf16 v[64:67], v[8:11], v[228:231], v[96:99]
	v_mfma_f32_16x16x32_bf16 v[76:79], v[12:15], v[232:235], v[64:67]
	v_mfma_f32_16x16x32_bf16 v[64:67], v[16:19], v[228:231], v[100:103]
	v_mfma_f32_16x16x32_bf16 v[72:75], v[20:23], v[232:235], v[64:67]
	v_mfma_f32_16x16x32_bf16 v[64:67], v[192:195], v[24:27], v[112:115]
	v_mfma_f32_16x16x32_bf16 v[24:27], v[200:203], v[24:27], v[32:35]
	v_mfma_f32_16x16x32_bf16 v[112:115], v[212:215], v[28:31], v[24:27]
	v_mfma_f32_16x16x32_bf16 v[24:27], v[192:195], v[60:63], v[36:39]
	v_mfma_f32_16x16x32_bf16 v[100:103], v[196:199], v[216:219], v[24:27]
	v_mfma_f32_16x16x32_bf16 v[24:27], v[200:203], v[60:63], v[40:43]
	v_mfma_f32_16x16x32_bf16 v[96:99], v[212:215], v[216:219], v[24:27]
	v_mfma_f32_16x16x32_bf16 v[24:27], v[192:195], v[220:223], v[44:47]
	v_mfma_f32_16x16x32_bf16 v[84:87], v[196:199], v[224:227], v[24:27]
	v_mfma_f32_16x16x32_bf16 v[24:27], v[200:203], v[220:223], v[48:51]
	v_mfma_f32_16x16x32_bf16 v[80:83], v[212:215], v[224:227], v[24:27]
	v_mfma_f32_16x16x32_bf16 v[24:27], v[192:195], v[228:231], v[52:55]
	v_mfma_f32_16x16x32_bf16 v[68:71], v[196:199], v[232:235], v[24:27]
	v_mfma_f32_16x16x32_bf16 v[24:27], v[200:203], v[228:231], v[56:59]
	v_mfma_f32_16x16x32_bf16 v[116:119], v[196:199], v[28:31], v[64:67]
	v_mfma_f32_16x16x32_bf16 v[64:67], v[212:215], v[232:235], v[24:27]
	s_barrier
; #define PG8_WAIT_V(n) asm volatile("s_waitcnt vmcnt(" #n ")" ::: "memory")
; #define PG8_WAIT_VP() asm volatile("s_waitcnt vmcnt(%0)" :: "n"(8 + Epi::NST) : "memory")
; #define PG8_BAR __builtin_amdgcn_s_barrier()
; template <class Epi, class Sched>
; __device__ __forceinline__ void gemm_phase(PG8_LAS unsigned char* lds, const Sched& S, const Epi& E, int tid_in) {
;     ...
;         { const int t = 0; PG8_KITER(PG8_WAIT_VP()); }
;         for (int t = 2; t < nt; t += 2) PG8_KITER(PG8_WAIT_V(8));
;     ...
;         if (wr == 0) PG8_BAR;
	s_add_i32 s20, s20, s47
	s_nop 2
	v_lshl_add_u64 v[24:25], v[240:241], 0, s[84:85]
	s_mov_b32 m0, s20
	s_mov_b64 s[22:23], 0xc080
	ds_read_b128 v[32:35], v187 offset:49152
	ds_read_b128 v[36:39], v187 offset:50176
	ds_read_b128 v[216:219], v187 offset:51200
	ds_read_b128 v[220:223], v187 offset:52224
	ds_read_b128 v[224:227], v187 offset:53248
	ds_read_b128 v[228:231], v187 offset:54272
	ds_read_b128 v[232:235], v187 offset:55296
	ds_read_b128 v[236:239], v187 offset:56320
	global_load_lds_dwordx4 v[24:25], off
	v_lshl_add_u64 v[24:25], v[240:241], 0, s[22:23]
	s_add_i32 m0, s20, 0x2000
	s_add_i32 s20, s21, s47
	global_load_lds_dwordx4 v[24:25], off
	v_lshl_add_u64 v[24:25], v[240:241], 0, s[66:67]
	s_mov_b32 m0, s20
	s_nop 0
	global_load_lds_dwordx4 v[24:25], off
	v_lshl_add_u64 v[24:25], v[240:241], 0, s[70:71]
	s_add_i32 m0, s20, 0x2000
	s_nop 0
	global_load_lds_dwordx4 v[24:25], off
	v_lshl_add_u64 v[24:25], v[242:243], 0, s[84:85]
	s_mov_b32 m0, s54
	s_nop 0
	global_load_lds_dwordx4 v[24:25], off
	v_lshl_add_u64 v[24:25], v[242:243], 0, s[22:23]
	s_mov_b32 m0, s55
	s_nop 0
	global_load_lds_dwordx4 v[24:25], off
	s_waitcnt vmcnt(8)
	s_waitcnt lgkmcnt(0)
	s_barrier
	v_mfma_f32_16x16x32_bf16 v[24:27], v[8:11], v[32:35], v[128:131]
	v_mfma_f32_16x16x32_bf16 v[60:63], v[12:15], v[36:39], v[24:27]
	v_mfma_f32_16x16x32_bf16 v[24:27], v[16:19], v[32:35], v[136:139]
	v_mfma_f32_16x16x32_bf16 v[56:59], v[20:23], v[36:39], v[24:27]
	v_mfma_f32_16x16x32_bf16 v[24:27], v[8:11], v[216:219], v[140:143]
	v_mfma_f32_16x16x32_bf16 v[44:47], v[12:15], v[220:223], v[24:27]
	v_mfma_f32_16x16x32_bf16 v[24:27], v[16:19], v[216:219], v[144:147]
	v_mfma_f32_16x16x32_bf16 v[40:43], v[20:23], v[220:223], v[24:27]
	v_mfma_f32_16x16x32_bf16 v[24:27], v[8:11], v[224:227], v[148:151]
	v_mfma_f32_16x16x32_bf16 v[0:3], v[8:11], v[232:235], v[0:3]
	v_mfma_f32_16x16x32_bf16 v[28:31], v[12:15], v[228:231], v[24:27]
	v_mfma_f32_16x16x32_bf16 v[24:27], v[16:19], v[224:227], v[152:155]
	v_mfma_f32_16x16x32_bf16 v[12:15], v[12:15], v[236:239], v[0:3]
	v_mfma_f32_16x16x32_bf16 v[0:3], v[16:19], v[232:235], v[4:7]
	v_mfma_f32_16x16x32_bf16 v[24:27], v[20:23], v[228:231], v[24:27]
	v_mfma_f32_16x16x32_bf16 v[8:11], v[20:23], v[236:239], v[0:3]
	v_mfma_f32_16x16x32_bf16 v[0:3], v[192:195], v[32:35], v[156:159]
	v_mfma_f32_16x16x32_bf16 v[52:55], v[196:199], v[36:39], v[0:3]
	v_mfma_f32_16x16x32_bf16 v[0:3], v[200:203], v[32:35], v[160:163]
	v_mfma_f32_16x16x32_bf16 v[48:51], v[212:215], v[36:39], v[0:3]
	v_mfma_f32_16x16x32_bf16 v[0:3], v[192:195], v[216:219], v[164:167]
	v_mfma_f32_16x16x32_bf16 v[36:39], v[196:199], v[220:223], v[0:3]
	v_mfma_f32_16x16x32_bf16 v[0:3], v[200:203], v[216:219], v[168:171]
	v_mfma_f32_16x16x32_bf16 v[32:35], v[212:215], v[220:223], v[0:3]
	v_mfma_f32_16x16x32_bf16 v[0:3], v[192:195], v[224:227], v[172:175]
	v_mfma_f32_16x16x32_bf16 v[20:23], v[196:199], v[228:231], v[0:3]
	v_mfma_f32_16x16x32_bf16 v[0:3], v[200:203], v[224:227], v[176:179]
	v_mfma_f32_16x16x32_bf16 v[16:19], v[212:215], v[228:231], v[0:3]
	v_mfma_f32_16x16x32_bf16 v[0:3], v[192:195], v[232:235], v[180:183]
	v_mfma_f32_16x16x32_bf16 v[4:7], v[196:199], v[236:239], v[0:3]
	v_mfma_f32_16x16x32_bf16 v[0:3], v[200:203], v[232:235], v[188:191]
	v_mfma_f32_16x16x32_bf16 v[0:3], v[212:215], v[236:239], v[0:3]
	s_barrier
	s_andn2_b64 vcc, exec, s[14:15]
	s_cbranch_vccnz .LBB0_543
	s_barrier

; __device__ __forceinline__ int lane_id() { int l; asm volatile("v_mbcnt_lo_u32_b32 %0, -1, 0\n\tv_mbcnt_hi_u32_b32 %0, -1, %0" : "=v"(l)); return l; }
;     __device__ __forceinline__ bool next(int i, UnitG& u) const { if (!P.next(i, u)) return false; u.O = O + ((size_t)u.x0 * 256 * 2048 + (size_t)u.x1 * 256) * 2; u.ldo = 2048; u.kind = 0; return true; }
; template <class Epi, class Sched>
; __device__ __forceinline__ void gemm_phase(PG8_LAS unsigned char* lds, const Sched& S, const Epi& E, int tid_in) {
;     ...
;         int aoff, boff; { const int l3 = lane_id(), fr3 = l3 & 15, fq3 = l3 >> 4; aoff = lds_byte(wr * 64 + fr3, fq3 * 8); boff = lds_byte(wc * 32 + fr3, fq3 * 8); }
;         const bool has_next = S.next(ui + 1, nxt);
;         const char* nA = has_next ? nxt.A : cA; const char* nB = has_next ? nxt.B : cB;
;         const int nlda = has_next ? nxt.lda : cur.lda, nldb = has_next ? nxt.ldb : cur.ldb;
;         unsigned nvA, nvB; { int r2, c2; stage_rc((wid * 64 + lane_id()) * 16, r2, c2); const int rb2 = Epi::PERM ? ((r2 & ~31) + perm32(r2 & 31)) : r2;
;             nvA = (unsigned)(r2 * nlda + c2) * 2u; nvB = (unsigned)(rb2 * nldb + c2) * 2u; }
;         const unsigned nqA = (unsigned)nlda * 128u, nqB = (unsigned)nldb * 128u;
;         const int nt = cur.K / BK;
.LBB0_914:
	v_and_b32_e32 v1, 15, v0
	v_and_b32_e32 v2, 48, v0
	v_lshl_or_b32 v1, v1, 6, v2
	v_lshlrev_b32_e32 v2, 4, v0
	v_and_b32_e32 v2, 0xfffffc00, v2
	v_readlane_b32 s4, v255, 5
	v_lshlrev_b32_e32 v0, 2, v0
	v_and_b32_e32 v0, 32, v0
	v_add_u32_e32 v3, s4, v2
	v_readlane_b32 s4, v255, 7
	v_bitop3_b32 v32, v1, v3, v0 bitop3:0xde
	s_add_i32 s93, 0, 0x10000
	v_add_u32_e32 v2, s4, v2
	v_bitop3_b32 v129, v1, v2, v0 bitop3:0xde
	v_mbcnt_lo_u32_b32 v0, -1, 0
	v_mbcnt_hi_u32_b32 v0, -1, v0
	v_readlane_b32 s4, v255, 9
	s_add_i32 s10, 0, 0x14000
	v_add_u32_e32 v142, s93, v129
	v_add_u32_e32 v0, s4, v0
	v_ashrrev_i32_e32 v2, 31, v0
	v_lshrrev_b32_e32 v2, 26, v2
	v_lshlrev_b32_e32 v1, 4, v0
	v_add_u32_e32 v2, v0, v2
	v_bfe_i32 v0, v0, 27, 1
	v_lshrrev_b32_e32 v0, 22, v0
	v_add_u32_e32 v0, v1, v0
	v_and_b32_e32 v0, 0xfffffc00, v0
	v_sub_u32_e32 v0, v1, v0
	v_lshrrev_b32_e32 v1, 4, v0
	v_bitop3_b32 v0, v1, v0, 32 bitop3:0x6c
	v_ashrrev_i32_e32 v3, 31, v0
	v_lshrrev_b32_e32 v3, 26, v3
	v_ashrrev_i32_e32 v2, 6, v2
	v_add_u32_e32 v3, v0, v3
	v_lshlrev_b32_e32 v1, 3, v2
	v_ashrrev_i32_e32 v4, 6, v3
	v_and_b32_e32 v3, 0xc0, v3
	v_and_b32_e32 v1, -16, v1
	v_lshlrev_b32_e32 v2, 5, v2
	v_sub_u32_e32 v0, v0, v3
	v_add_u32_e32 v1, v4, v1
	v_and_b32_e32 v2, 32, v2
	v_ashrrev_i16_sdwa v0, v205, sext(v0) dst_sel:DWORD dst_unused:UNUSED_PAD src0_sel:DWORD src1_sel:BYTE_0
	v_add_u32_sdwa v16, v2, sext(v0) dst_sel:DWORD dst_unused:UNUSED_PAD src0_sel:DWORD src1_sel:WORD_0
	v_lshlrev_b32_e32 v0, 1, v1
	v_lshrrev_b32_e32 v2, 2, v1
	v_and_b32_e32 v3, 3, v4
	s_mov_b32 s4, 0x7fffffe0
	v_and_b32_e32 v0, 24, v0
	v_and_b32_e32 v2, 4, v2
	v_and_or_b32 v3, v1, s4, v3
	v_or3_b32 v0, v3, v2, v0
	v_mul_lo_u32 v17, v1, s46
	v_mul_lo_u32 v0, v0, s47
	v_add_u32_e32 v143, s10, v129
	v_add_lshl_u32 v128, v0, v16, 1
	ds_read_b128 v[0:3], v142
	ds_read_b128 v[4:7], v142 offset:1024
	ds_read_b128 v[8:11], v142 offset:2048
	ds_read_b128 v[12:15], v142 offset:3072
	v_add_lshl_u32 v130, v16, v17, 1
	ds_read_b128 v[16:19], v143
	ds_read_b128 v[20:23], v143 offset:1024
	ds_read_b128 v[24:27], v143 offset:2048
	ds_read_b128 v[28:31], v143 offset:3072
	s_lshl_b32 s22, s47, 7
	s_lshl_b32 s82, s30, 1
	s_lshl_b32 s24, s46, 7
	s_add_u32 s50, s26, s82
	s_addc_u32 s51, s27, 0
	v_lshl_add_u64 v[244:245], s[50:51], 0, v[184:185]
	s_add_i32 s7, s92, 0xc000
	s_mov_b32 s31, s83
	v_add_u32_e32 v144, 0, v32
	v_lshl_add_u64 v[64:65], v[244:245], 0, s[84:85]
	s_mov_b32 m0, s7
	v_lshl_add_u64 v[246:247], v[244:245], 0, s[30:31]
	s_add_i32 s75, s92, 0xe000
	ds_read_b128 v[32:35], v144
	ds_read_b128 v[36:39], v144 offset:1024
	ds_read_b128 v[40:43], v144 offset:2048
	ds_read_b128 v[44:47], v144 offset:3072
	ds_read_b128 v[48:51], v144 offset:4096
	ds_read_b128 v[52:55], v144 offset:5120
	ds_read_b128 v[56:59], v144 offset:6144
	ds_read_b128 v[60:63], v144 offset:7168
	global_load_lds_dwordx4 v[64:65], off
	v_lshl_add_u64 v[64:65], v[246:247], 0, s[84:85]
	s_mov_b32 m0, s75
	s_nop 0
	global_load_lds_dwordx4 v[64:65], off
	s_waitcnt vmcnt(24)
	s_waitcnt lgkmcnt(0)
	s_barrier
	v_mfma_f32_16x16x32_bf16 v[88:91], v[0:3], v[56:59], 0
	v_mfma_f32_16x16x32_bf16 v[64:67], v[0:3], v[32:35], 0
	v_mfma_f32_16x16x32_bf16 v[68:71], v[8:11], v[32:35], 0
	v_mfma_f32_16x16x32_bf16 v[72:75], v[0:3], v[40:43], 0
	v_mfma_f32_16x16x32_bf16 v[76:79], v[8:11], v[40:43], 0
	v_mfma_f32_16x16x32_bf16 v[80:83], v[0:3], v[48:51], 0
	v_mfma_f32_16x16x32_bf16 v[84:87], v[8:11], v[48:51], 0
	v_mfma_f32_16x16x32_bf16 v[96:99], v[4:7], v[60:63], v[88:91]
	v_mfma_f32_16x16x32_bf16 v[88:91], v[8:11], v[56:59], 0
	v_mfma_f32_16x16x32_bf16 v[64:67], v[4:7], v[36:39], v[64:67]
	v_mfma_f32_16x16x32_bf16 v[68:71], v[12:15], v[36:39], v[68:71]
	v_mfma_f32_16x16x32_bf16 v[72:75], v[4:7], v[44:47], v[72:75]
	v_mfma_f32_16x16x32_bf16 v[76:79], v[12:15], v[44:47], v[76:79]
	v_mfma_f32_16x16x32_bf16 v[80:83], v[4:7], v[52:55], v[80:83]
	v_mfma_f32_16x16x32_bf16 v[84:87], v[12:15], v[52:55], v[84:87]
	v_mfma_f32_16x16x32_bf16 v[100:103], v[12:15], v[60:63], v[88:91]
	v_mfma_f32_16x16x32_bf16 v[88:91], v[16:19], v[32:35], 0
	v_mfma_f32_16x16x32_bf16 v[32:35], v[24:27], v[32:35], 0
	v_mfma_f32_16x16x32_bf16 v[112:115], v[20:23], v[36:39], v[88:91]
	v_mfma_f32_16x16x32_bf16 v[32:35], v[28:31], v[36:39], v[32:35]
	v_mfma_f32_16x16x32_bf16 v[36:39], v[16:19], v[40:43], 0
	v_mfma_f32_16x16x32_bf16 v[40:43], v[24:27], v[40:43], 0
	v_mfma_f32_16x16x32_bf16 v[36:39], v[20:23], v[44:47], v[36:39]
	v_mfma_f32_16x16x32_bf16 v[40:43], v[28:31], v[44:47], v[40:43]
	v_mfma_f32_16x16x32_bf16 v[44:47], v[16:19], v[48:51], 0
	v_mfma_f32_16x16x32_bf16 v[48:51], v[24:27], v[48:51], 0
	v_mfma_f32_16x16x32_bf16 v[44:47], v[20:23], v[52:55], v[44:47]
	v_mfma_f32_16x16x32_bf16 v[48:51], v[28:31], v[52:55], v[48:51]
	v_mfma_f32_16x16x32_bf16 v[52:55], v[16:19], v[56:59], 0
	v_mfma_f32_16x16x32_bf16 v[56:59], v[24:27], v[56:59], 0
	v_mfma_f32_16x16x32_bf16 v[52:55], v[20:23], v[60:63], v[52:55]
	v_mfma_f32_16x16x32_bf16 v[56:59], v[28:31], v[60:63], v[56:59]
	s_barrier
	s_add_i32 s93, s93, s74
	v_mov_b32_e32 v133, v185
	s_add_i32 s71, s93, 0x2000
	s_lshl_b32 s44, s28, 1
	v_lshl_add_u64 v[248:249], s[34:35], 0, v[132:133]
	s_mov_b64 s[12:13], 0x100
	s_mov_b32 s29, s83
	s_add_u32 s4, s34, s44
	v_lshl_add_u64 v[134:135], v[248:249], 0, s[12:13]
	s_mov_b32 m0, s93
	v_lshl_add_u64 v[250:251], v[248:249], 0, s[28:29]
	s_addc_u32 s5, s35, 0
	ds_read_b128 v[60:63], v144 offset:16384
	ds_read_b128 v[88:91], v144 offset:17408
	ds_read_b128 v[92:95], v144 offset:18432
	ds_read_b128 v[104:107], v144 offset:19456
	ds_read_b128 v[108:111], v144 offset:20480
	ds_read_b128 v[116:119], v144 offset:21504
	ds_read_b128 v[120:123], v144 offset:22528
	ds_read_b128 v[124:127], v144 offset:23552
	global_load_lds_dwordx4 v[134:135], off
	v_lshl_add_u64 v[134:135], v[250:251], 0, s[12:13]
	s_mov_b32 m0, s71
	v_lshl_add_u64 v[252:253], s[4:5], 0, v[132:133]
	s_add_i32 s10, s10, s74
	global_load_lds_dwordx4 v[134:135], off
	v_lshl_add_u64 v[134:135], v[252:253], 0, s[12:13]
	s_mov_b32 m0, s10
	v_lshl_add_u64 v[210:211], v[252:253], 0, s[28:29]
	s_add_i32 s11, s10, 0x2000
	global_load_lds_dwordx4 v[134:135], off
	v_lshl_add_u64 v[134:135], v[210:211], 0, s[12:13]
	s_mov_b32 m0, s11
	v_lshl_add_u64 v[206:207], s[26:27], 0, v[184:185]
	global_load_lds_dwordx4 v[134:135], off
	v_lshl_add_u64 v[134:135], v[206:207], 0, s[12:13]
	s_mov_b32 m0, s92
	v_lshl_add_u64 v[186:187], v[206:207], 0, s[30:31]
	global_load_lds_dwordx4 v[134:135], off
	v_lshl_add_u64 v[134:135], v[186:187], 0, s[12:13]
	s_mov_b32 m0, s76
	s_mov_b32 s45, s83
	global_load_lds_dwordx4 v[134:135], off
	s_waitcnt vmcnt(24)
	s_waitcnt lgkmcnt(0)
	s_barrier
	v_mfma_f32_16x16x32_bf16 v[134:137], v[0:3], v[60:63], 0
	v_mfma_f32_16x16x32_bf16 v[146:149], v[0:3], v[92:95], 0
	v_mfma_f32_16x16x32_bf16 v[156:159], v[0:3], v[108:111], 0
	v_mfma_f32_16x16x32_bf16 v[0:3], v[0:3], v[120:123], 0
	v_mfma_f32_16x16x32_bf16 v[134:137], v[4:7], v[88:91], v[134:137]
	v_mfma_f32_16x16x32_bf16 v[148:151], v[4:7], v[104:107], v[146:149]
	v_mfma_f32_16x16x32_bf16 v[156:159], v[4:7], v[116:119], v[156:159]
	v_mfma_f32_16x16x32_bf16 v[0:3], v[4:7], v[124:127], v[0:3]
	v_mfma_f32_16x16x32_bf16 v[4:7], v[8:11], v[120:123], 0
	v_mfma_f32_16x16x32_bf16 v[138:141], v[8:11], v[60:63], 0
	v_mfma_f32_16x16x32_bf16 v[152:155], v[8:11], v[92:95], 0
	v_mfma_f32_16x16x32_bf16 v[160:163], v[8:11], v[108:111], 0
	v_mfma_f32_16x16x32_bf16 v[4:7], v[12:15], v[124:127], v[4:7]
	v_mfma_f32_16x16x32_bf16 v[138:141], v[12:15], v[88:91], v[138:141]
	v_mfma_f32_16x16x32_bf16 v[152:155], v[12:15], v[104:107], v[152:155]
	v_mfma_f32_16x16x32_bf16 v[160:163], v[12:15], v[116:119], v[160:163]
	v_mfma_f32_16x16x32_bf16 v[8:11], v[16:19], v[60:63], 0
	v_mfma_f32_16x16x32_bf16 v[164:167], v[20:23], v[88:91], v[8:11]
	v_mfma_f32_16x16x32_bf16 v[8:11], v[24:27], v[60:63], 0
	v_mfma_f32_16x16x32_bf16 v[168:171], v[28:31], v[88:91], v[8:11]
	v_mfma_f32_16x16x32_bf16 v[8:11], v[16:19], v[92:95], 0
	v_mfma_f32_16x16x32_bf16 v[172:175], v[20:23], v[104:107], v[8:11]
	v_mfma_f32_16x16x32_bf16 v[8:11], v[24:27], v[92:95], 0
	v_mfma_f32_16x16x32_bf16 v[176:179], v[28:31], v[104:107], v[8:11]
	v_mfma_f32_16x16x32_bf16 v[8:11], v[16:19], v[108:111], 0
	v_mfma_f32_16x16x32_bf16 v[180:183], v[20:23], v[116:119], v[8:11]
	v_mfma_f32_16x16x32_bf16 v[8:11], v[24:27], v[108:111], 0
	v_mfma_f32_16x16x32_bf16 v[188:191], v[28:31], v[116:119], v[8:11]
	v_mfma_f32_16x16x32_bf16 v[8:11], v[16:19], v[120:123], 0
	v_mfma_f32_16x16x32_bf16 v[192:195], v[20:23], v[124:127], v[8:11]
	v_mfma_f32_16x16x32_bf16 v[8:11], v[24:27], v[120:123], 0
	v_mfma_f32_16x16x32_bf16 v[196:199], v[28:31], v[124:127], v[8:11]
	s_barrier
	s_add_i32 s70, 0, 0x18000
	s_add_i32 s4, 0, 0x1c000
	v_add_u32_e32 v145, s70, v129
	v_add_u32_e32 v146, s4, v129
	s_nop 0
	ds_read_b128 v[8:11], v145
	ds_read_b128 v[12:15], v145 offset:1024
	ds_read_b128 v[16:19], v145 offset:2048
	ds_read_b128 v[20:23], v145 offset:3072
	ds_read_b128 v[200:203], v146
	ds_read_b128 v[212:215], v146 offset:1024
	ds_read_b128 v[216:219], v146 offset:2048
	ds_read_b128 v[220:223], v146 offset:3072
	s_mov_b32 m0, s77
	v_lshl_add_u64 v[88:89], v[244:245], 0, s[12:13]
	ds_read_b128 v[24:27], v144 offset:32768
	ds_read_b128 v[28:31], v144 offset:33792
	ds_read_b128 v[60:63], v144 offset:34816
	ds_read_b128 v[224:227], v144 offset:35840
	ds_read_b128 v[228:231], v144 offset:36864
	ds_read_b128 v[232:235], v144 offset:37888
	ds_read_b128 v[236:239], v144 offset:38912
	ds_read_b128 v[240:243], v144 offset:39936
	global_load_lds_dwordx4 v[88:89], off
	v_lshl_add_u64 v[88:89], v[246:247], 0, s[12:13]
	s_mov_b32 m0, s64
	s_nop 0
	global_load_lds_dwordx4 v[88:89], off
	s_waitcnt vmcnt(8)
	s_waitcnt lgkmcnt(0)
	s_barrier
; #define PG8_WAIT_V(n) asm volatile("s_waitcnt vmcnt(" #n ")" ::: "memory")
; #define PG8_WAIT_VP() asm volatile("s_waitcnt vmcnt(%0)" :: "n"(8 + Epi::NST) : "memory")
; template <class Epi, class Sched>
; __device__ __forceinline__ void gemm_phase(PG8_LAS unsigned char* lds, const Sched& S, const Epi& E, int tid_in) {
;     ...
;         { const int t = 0; PG8_KITER(PG8_WAIT_VP()); }
;         for (int t = 2; t < nt; t += 2) PG8_KITER(PG8_WAIT_V(8));
	v_mfma_f32_16x16x32_bf16 v[64:67], v[8:11], v[24:27], v[64:67]
	v_mfma_f32_16x16x32_bf16 v[124:127], v[12:15], v[28:31], v[64:67]
	v_mfma_f32_16x16x32_bf16 v[64:67], v[16:19], v[24:27], v[68:71]
	v_mfma_f32_16x16x32_bf16 v[120:123], v[20:23], v[28:31], v[64:67]
	v_mfma_f32_16x16x32_bf16 v[64:67], v[8:11], v[60:63], v[72:75]
	v_mfma_f32_16x16x32_bf16 v[108:111], v[12:15], v[224:227], v[64:67]
	v_mfma_f32_16x16x32_bf16 v[64:67], v[16:19], v[60:63], v[76:79]
	v_mfma_f32_16x16x32_bf16 v[104:107], v[20:23], v[224:227], v[64:67]
	v_mfma_f32_16x16x32_bf16 v[64:67], v[8:11], v[228:231], v[80:83]
	v_mfma_f32_16x16x32_bf16 v[92:95], v[12:15], v[232:235], v[64:67]
	v_mfma_f32_16x16x32_bf16 v[64:67], v[16:19], v[228:231], v[84:87]
	v_mfma_f32_16x16x32_bf16 v[88:91], v[20:23], v[232:235], v[64:67]
	v_mfma_f32_16x16x32_bf16 v[64:67], v[8:11], v[236:239], v[96:99]
	v_mfma_f32_16x16x32_bf16 v[76:79], v[12:15], v[240:243], v[64:67]
	v_mfma_f32_16x16x32_bf16 v[64:67], v[16:19], v[236:239], v[100:103]
	v_mfma_f32_16x16x32_bf16 v[72:75], v[20:23], v[240:243], v[64:67]
	v_mfma_f32_16x16x32_bf16 v[64:67], v[200:203], v[24:27], v[112:115]
	v_mfma_f32_16x16x32_bf16 v[24:27], v[216:219], v[24:27], v[32:35]
	v_mfma_f32_16x16x32_bf16 v[112:115], v[220:223], v[28:31], v[24:27]
	v_mfma_f32_16x16x32_bf16 v[24:27], v[200:203], v[60:63], v[36:39]
	v_mfma_f32_16x16x32_bf16 v[100:103], v[212:215], v[224:227], v[24:27]
	v_mfma_f32_16x16x32_bf16 v[24:27], v[216:219], v[60:63], v[40:43]
	v_mfma_f32_16x16x32_bf16 v[96:99], v[220:223], v[224:227], v[24:27]
	v_mfma_f32_16x16x32_bf16 v[24:27], v[200:203], v[228:231], v[44:47]
	v_mfma_f32_16x16x32_bf16 v[84:87], v[212:215], v[232:235], v[24:27]
	v_mfma_f32_16x16x32_bf16 v[24:27], v[216:219], v[228:231], v[48:51]
	v_mfma_f32_16x16x32_bf16 v[80:83], v[220:223], v[232:235], v[24:27]
	v_mfma_f32_16x16x32_bf16 v[24:27], v[200:203], v[236:239], v[52:55]
	v_mfma_f32_16x16x32_bf16 v[68:71], v[212:215], v[240:243], v[24:27]
	v_mfma_f32_16x16x32_bf16 v[24:27], v[216:219], v[236:239], v[56:59]
	v_mfma_f32_16x16x32_bf16 v[116:119], v[212:215], v[28:31], v[64:67]
	v_mfma_f32_16x16x32_bf16 v[64:67], v[220:223], v[240:243], v[24:27]
	s_barrier
	s_mov_b64 s[12:13], 0x180
	s_add_i32 s70, s70, s74
	s_nop 1
	v_lshl_add_u64 v[24:25], v[248:249], 0, s[12:13]
	s_mov_b32 m0, s70
	s_add_i32 s15, s70, 0x2000
	ds_read_b128 v[32:35], v144 offset:49152
	ds_read_b128 v[36:39], v144 offset:50176
	ds_read_b128 v[224:227], v144 offset:51200
	ds_read_b128 v[228:231], v144 offset:52224
	ds_read_b128 v[232:235], v144 offset:53248
	ds_read_b128 v[236:239], v144 offset:54272
	ds_read_b128 v[240:243], v144 offset:55296
	ds_read_b128 v[244:247], v144 offset:56320
	global_load_lds_dwordx4 v[24:25], off
	v_lshl_add_u64 v[24:25], v[250:251], 0, s[12:13]
	s_mov_b32 m0, s15
	s_add_i32 s4, s4, s74
	global_load_lds_dwordx4 v[24:25], off
	v_lshl_add_u64 v[24:25], v[252:253], 0, s[12:13]
	s_mov_b32 m0, s4
	s_add_i32 s5, s4, 0x2000
	global_load_lds_dwordx4 v[24:25], off
	v_lshl_add_u64 v[24:25], v[210:211], 0, s[12:13]
	s_mov_b32 m0, s5
	v_mov_b32_e32 v252, 0x3a27c5ac
	global_load_lds_dwordx4 v[24:25], off
	v_lshl_add_u64 v[24:25], v[206:207], 0, s[12:13]
	s_mov_b32 m0, s67
	s_nop 0
	global_load_lds_dwordx4 v[24:25], off
	v_lshl_add_u64 v[24:25], v[186:187], 0, s[12:13]
	s_mov_b32 m0, s14
	s_nop 0
	global_load_lds_dwordx4 v[24:25], off
	s_waitcnt vmcnt(8)
	s_waitcnt lgkmcnt(0)
	s_barrier
	v_mfma_f32_16x16x32_bf16 v[24:27], v[8:11], v[32:35], v[134:137]
	v_mfma_f32_16x16x32_bf16 v[60:63], v[12:15], v[36:39], v[24:27]
	v_mfma_f32_16x16x32_bf16 v[24:27], v[16:19], v[32:35], v[138:141]
	v_mfma_f32_16x16x32_bf16 v[56:59], v[20:23], v[36:39], v[24:27]
	v_mfma_f32_16x16x32_bf16 v[24:27], v[8:11], v[224:227], v[148:151]
	v_mfma_f32_16x16x32_bf16 v[44:47], v[12:15], v[228:231], v[24:27]
	v_mfma_f32_16x16x32_bf16 v[24:27], v[16:19], v[224:227], v[152:155]
	v_mfma_f32_16x16x32_bf16 v[40:43], v[20:23], v[228:231], v[24:27]
	v_mfma_f32_16x16x32_bf16 v[24:27], v[8:11], v[232:235], v[156:159]
	v_mfma_f32_16x16x32_bf16 v[0:3], v[8:11], v[240:243], v[0:3]
	v_mfma_f32_16x16x32_bf16 v[28:31], v[12:15], v[236:239], v[24:27]
	v_mfma_f32_16x16x32_bf16 v[24:27], v[16:19], v[232:235], v[160:163]
	v_mfma_f32_16x16x32_bf16 v[12:15], v[12:15], v[244:247], v[0:3]
	v_mfma_f32_16x16x32_bf16 v[0:3], v[16:19], v[240:243], v[4:7]
	v_mfma_f32_16x16x32_bf16 v[24:27], v[20:23], v[236:239], v[24:27]
	v_mfma_f32_16x16x32_bf16 v[8:11], v[20:23], v[244:247], v[0:3]
	v_mfma_f32_16x16x32_bf16 v[0:3], v[200:203], v[32:35], v[164:167]
	v_mfma_f32_16x16x32_bf16 v[52:55], v[212:215], v[36:39], v[0:3]
	v_mfma_f32_16x16x32_bf16 v[0:3], v[216:219], v[32:35], v[168:171]
	v_mfma_f32_16x16x32_bf16 v[48:51], v[220:223], v[36:39], v[0:3]
	v_mfma_f32_16x16x32_bf16 v[0:3], v[200:203], v[224:227], v[172:175]
	v_mfma_f32_16x16x32_bf16 v[36:39], v[212:215], v[228:231], v[0:3]
	v_mfma_f32_16x16x32_bf16 v[0:3], v[216:219], v[224:227], v[176:179]
	v_mfma_f32_16x16x32_bf16 v[32:35], v[220:223], v[228:231], v[0:3]
	v_mfma_f32_16x16x32_bf16 v[0:3], v[200:203], v[232:235], v[180:183]
	v_mfma_f32_16x16x32_bf16 v[20:23], v[212:215], v[236:239], v[0:3]
	v_mfma_f32_16x16x32_bf16 v[0:3], v[216:219], v[232:235], v[188:191]
	v_mfma_f32_16x16x32_bf16 v[16:19], v[220:223], v[236:239], v[0:3]
	v_mfma_f32_16x16x32_bf16 v[0:3], v[200:203], v[240:243], v[192:195]
	v_mfma_f32_16x16x32_bf16 v[4:7], v[212:215], v[244:247], v[0:3]
	v_mfma_f32_16x16x32_bf16 v[0:3], v[216:219], v[240:243], v[196:199]
	v_mfma_f32_16x16x32_bf16 v[0:3], v[220:223], v[244:247], v[0:3]
	s_barrier
	s_lshl_b32 s46, s46, 8
	s_lshl_b32 s48, s47, 8
	s_add_u32 s12, s34, 0x200
	s_addc_u32 s13, s35, 0
	s_add_u32 s34, s50, 0x180
	s_addc_u32 s35, s51, 0
	v_lshl_add_u64 v[134:135], s[34:35], 0, v[184:185]
	s_add_u32 s34, s34, s30
	s_addc_u32 s35, s35, 0
	v_mov_b32_e32 v129, v185
	s_mov_b32 s23, s83
	s_mov_b32 s49, s83
	v_mov_b32_e32 v131, v185
	s_mov_b32 s25, s83
	s_mov_b32 s47, s83
	v_lshl_add_u64 v[136:137], s[34:35], 0, v[184:185]
	s_mov_b32 s68, 0
	s_mov_b64 s[34:35], 0
	s_branch .LBB0_916
.LBB0_915:
	ds_read_b128 v[148:151], v142
	ds_read_b128 v[152:155], v142 offset:1024
	ds_read_b128 v[156:159], v142 offset:2048
	ds_read_b128 v[160:163], v142 offset:3072
	ds_read_b128 v[164:167], v143
	ds_read_b128 v[168:171], v143 offset:1024
	ds_read_b128 v[172:175], v143 offset:2048
	ds_read_b128 v[176:179], v143 offset:3072
	s_add_u32 vcc_lo, s26, s34
	s_addc_u32 vcc_hi, s27, s35
	s_add_u32 vcc_lo, vcc_lo, 0x200
	s_addc_u32 vcc_hi, vcc_hi, 0
	s_and_b64 s[54:55], exec, s[54:55]
	s_cselect_b32 s55, s17, vcc_hi
	s_cselect_b32 s54, s16, vcc_lo
	s_mov_b32 m0, s7
	v_lshl_add_u64 v[186:187], v[134:135], 0, s[34:35]
	ds_read_b128 v[180:183], v144
	ds_read_b128 v[188:191], v144 offset:1024
	ds_read_b128 v[192:195], v144 offset:2048
	ds_read_b128 v[196:199], v144 offset:3072
	ds_read_b128 v[200:203], v144 offset:4096
	ds_read_b128 v[212:215], v144 offset:5120
	ds_read_b128 v[216:219], v144 offset:6144
	ds_read_b128 v[220:223], v144 offset:7168
	global_load_lds_dwordx4 v[186:187], off
	v_lshl_add_u64 v[186:187], v[136:137], 0, s[34:35]
	s_mov_b32 m0, s75
	s_nop 0
	global_load_lds_dwordx4 v[186:187], off
	s_waitcnt vmcnt(8)
	s_waitcnt lgkmcnt(0)
	s_barrier
	v_mfma_f32_16x16x32_bf16 v[124:127], v[148:151], v[180:183], v[124:127]
	v_mfma_f32_16x16x32_bf16 v[120:123], v[156:159], v[180:183], v[120:123]
	v_mfma_f32_16x16x32_bf16 v[108:111], v[148:151], v[192:195], v[108:111]
	v_mfma_f32_16x16x32_bf16 v[104:107], v[156:159], v[192:195], v[104:107]
	v_mfma_f32_16x16x32_bf16 v[92:95], v[148:151], v[200:203], v[92:95]
	v_mfma_f32_16x16x32_bf16 v[88:91], v[156:159], v[200:203], v[88:91]
	v_mfma_f32_16x16x32_bf16 v[76:79], v[148:151], v[216:219], v[76:79]
	v_mfma_f32_16x16x32_bf16 v[72:75], v[156:159], v[216:219], v[72:75]
	v_mfma_f32_16x16x32_bf16 v[124:127], v[152:155], v[188:191], v[124:127]
	v_mfma_f32_16x16x32_bf16 v[120:123], v[160:163], v[188:191], v[120:123]
	v_mfma_f32_16x16x32_bf16 v[108:111], v[152:155], v[196:199], v[108:111]
	v_mfma_f32_16x16x32_bf16 v[104:107], v[160:163], v[196:199], v[104:107]
	v_mfma_f32_16x16x32_bf16 v[92:95], v[152:155], v[212:215], v[92:95]
	v_mfma_f32_16x16x32_bf16 v[88:91], v[160:163], v[212:215], v[88:91]
	v_mfma_f32_16x16x32_bf16 v[76:79], v[152:155], v[220:223], v[76:79]
	v_mfma_f32_16x16x32_bf16 v[72:75], v[160:163], v[220:223], v[72:75]
	v_mfma_f32_16x16x32_bf16 v[116:119], v[164:167], v[180:183], v[116:119]
	v_mfma_f32_16x16x32_bf16 v[112:115], v[172:175], v[180:183], v[112:115]
	v_mfma_f32_16x16x32_bf16 v[100:103], v[164:167], v[192:195], v[100:103]
	v_mfma_f32_16x16x32_bf16 v[96:99], v[172:175], v[192:195], v[96:99]
	v_mfma_f32_16x16x32_bf16 v[84:87], v[164:167], v[200:203], v[84:87]
	v_mfma_f32_16x16x32_bf16 v[80:83], v[172:175], v[200:203], v[80:83]
	v_mfma_f32_16x16x32_bf16 v[68:71], v[164:167], v[216:219], v[68:71]
	v_mfma_f32_16x16x32_bf16 v[64:67], v[172:175], v[216:219], v[64:67]
	v_mfma_f32_16x16x32_bf16 v[116:119], v[168:171], v[188:191], v[116:119]
	v_mfma_f32_16x16x32_bf16 v[112:115], v[176:179], v[188:191], v[112:115]
	v_mfma_f32_16x16x32_bf16 v[100:103], v[168:171], v[196:199], v[100:103]
	v_mfma_f32_16x16x32_bf16 v[96:99], v[176:179], v[196:199], v[96:99]
	v_mfma_f32_16x16x32_bf16 v[84:87], v[168:171], v[212:215], v[84:87]
	v_mfma_f32_16x16x32_bf16 v[80:83], v[176:179], v[212:215], v[80:83]
	v_mfma_f32_16x16x32_bf16 v[68:71], v[168:171], v[220:223], v[68:71]
	v_mfma_f32_16x16x32_bf16 v[64:67], v[176:179], v[220:223], v[64:67]
	s_barrier
	s_mov_b32 m0, s93
	v_lshl_add_u64 v[186:187], s[58:59], 0, v[140:141]
	s_add_u32 s58, s58, s60
	ds_read_b128 v[180:183], v144 offset:16384
	ds_read_b128 v[188:191], v144 offset:17408
	ds_read_b128 v[192:195], v144 offset:18432
	ds_read_b128 v[196:199], v144 offset:19456
	ds_read_b128 v[200:203], v144 offset:20480
	ds_read_b128 v[212:215], v144 offset:21504
	ds_read_b128 v[216:219], v144 offset:22528
	ds_read_b128 v[220:223], v144 offset:23552
	global_load_lds_dwordx4 v[186:187], off
	v_lshl_add_u64 v[206:207], v[186:187], 0, s[56:57]
	s_mov_b32 m0, s71
	s_addc_u32 s59, s59, s61
	global_load_lds_dwordx4 v[206:207], off
	v_lshl_add_u64 v[210:211], s[58:59], 0, v[140:141]
	s_mov_b32 m0, s10
	v_lshl_add_u64 v[224:225], v[210:211], 0, s[56:57]
	global_load_lds_dwordx4 v[210:211], off
	s_mov_b32 m0, s11
	v_lshl_add_u64 v[226:227], s[54:55], 0, v[138:139]
	global_load_lds_dwordx4 v[224:225], off
	s_mov_b32 m0, s92
	v_lshl_add_u64 v[228:229], v[226:227], 0, s[50:51]
	global_load_lds_dwordx4 v[226:227], off
	s_mov_b32 m0, s76
	s_nop 0
	global_load_lds_dwordx4 v[228:229], off
	s_waitcnt vmcnt(8)
	s_waitcnt lgkmcnt(0)
	s_barrier
	v_mfma_f32_16x16x32_bf16 v[60:63], v[148:151], v[180:183], v[60:63]
	v_mfma_f32_16x16x32_bf16 v[56:59], v[156:159], v[180:183], v[56:59]
	v_mfma_f32_16x16x32_bf16 v[44:47], v[148:151], v[192:195], v[44:47]
	v_mfma_f32_16x16x32_bf16 v[40:43], v[156:159], v[192:195], v[40:43]
	v_mfma_f32_16x16x32_bf16 v[28:31], v[148:151], v[200:203], v[28:31]
	v_mfma_f32_16x16x32_bf16 v[24:27], v[156:159], v[200:203], v[24:27]
	v_mfma_f32_16x16x32_bf16 v[12:15], v[148:151], v[216:219], v[12:15]
	v_mfma_f32_16x16x32_bf16 v[8:11], v[156:159], v[216:219], v[8:11]
	v_mfma_f32_16x16x32_bf16 v[60:63], v[152:155], v[188:191], v[60:63]
	v_mfma_f32_16x16x32_bf16 v[56:59], v[160:163], v[188:191], v[56:59]
	v_mfma_f32_16x16x32_bf16 v[44:47], v[152:155], v[196:199], v[44:47]
	v_mfma_f32_16x16x32_bf16 v[40:43], v[160:163], v[196:199], v[40:43]
	v_mfma_f32_16x16x32_bf16 v[28:31], v[152:155], v[212:215], v[28:31]
	v_mfma_f32_16x16x32_bf16 v[24:27], v[160:163], v[212:215], v[24:27]
	v_mfma_f32_16x16x32_bf16 v[12:15], v[152:155], v[220:223], v[12:15]
	v_mfma_f32_16x16x32_bf16 v[8:11], v[160:163], v[220:223], v[8:11]
	v_mfma_f32_16x16x32_bf16 v[52:55], v[164:167], v[180:183], v[52:55]
	v_mfma_f32_16x16x32_bf16 v[48:51], v[172:175], v[180:183], v[48:51]
	v_mfma_f32_16x16x32_bf16 v[36:39], v[164:167], v[192:195], v[36:39]
	v_mfma_f32_16x16x32_bf16 v[32:35], v[172:175], v[192:195], v[32:35]
	v_mfma_f32_16x16x32_bf16 v[20:23], v[164:167], v[200:203], v[20:23]
	v_mfma_f32_16x16x32_bf16 v[16:19], v[172:175], v[200:203], v[16:19]
	v_mfma_f32_16x16x32_bf16 v[4:7], v[164:167], v[216:219], v[4:7]
	v_mfma_f32_16x16x32_bf16 v[0:3], v[172:175], v[216:219], v[0:3]
	v_mfma_f32_16x16x32_bf16 v[52:55], v[168:171], v[188:191], v[52:55]
	v_mfma_f32_16x16x32_bf16 v[48:51], v[176:179], v[188:191], v[48:51]
	v_mfma_f32_16x16x32_bf16 v[36:39], v[168:171], v[196:199], v[36:39]
	v_mfma_f32_16x16x32_bf16 v[32:35], v[176:179], v[196:199], v[32:35]
	v_mfma_f32_16x16x32_bf16 v[20:23], v[168:171], v[212:215], v[20:23]
	v_mfma_f32_16x16x32_bf16 v[16:19], v[176:179], v[212:215], v[16:19]
	v_mfma_f32_16x16x32_bf16 v[4:7], v[168:171], v[220:223], v[4:7]
	v_mfma_f32_16x16x32_bf16 v[0:3], v[176:179], v[220:223], v[0:3]
	s_barrier
	ds_read_b128 v[148:151], v145
	ds_read_b128 v[152:155], v145 offset:1024
	ds_read_b128 v[156:159], v145 offset:2048
	ds_read_b128 v[160:163], v145 offset:3072
	ds_read_b128 v[164:167], v146
	ds_read_b128 v[168:171], v146 offset:1024
	ds_read_b128 v[172:175], v146 offset:2048
	ds_read_b128 v[176:179], v146 offset:3072
	s_add_u32 s52, s54, s52
	s_addc_u32 s53, s55, s53
	s_mov_b32 m0, s77
	v_lshl_add_u64 v[138:139], s[52:53], 0, v[138:139]
	ds_read_b128 v[180:183], v144 offset:32768
	ds_read_b128 v[188:191], v144 offset:33792
	ds_read_b128 v[192:195], v144 offset:34816
	ds_read_b128 v[196:199], v144 offset:35840
	ds_read_b128 v[200:203], v144 offset:36864
	ds_read_b128 v[212:215], v144 offset:37888
	ds_read_b128 v[216:219], v144 offset:38912
	ds_read_b128 v[220:223], v144 offset:39936
	global_load_lds_dwordx4 v[138:139], off
	v_lshl_add_u64 v[138:139], v[138:139], 0, s[50:51]
	s_mov_b32 m0, s64
	s_nop 0
	global_load_lds_dwordx4 v[138:139], off
	s_waitcnt vmcnt(8)
	s_waitcnt lgkmcnt(0)
	s_barrier
	v_mfma_f32_16x16x32_bf16 v[124:127], v[148:151], v[180:183], v[124:127]
	v_mfma_f32_16x16x32_bf16 v[120:123], v[156:159], v[180:183], v[120:123]
	v_mfma_f32_16x16x32_bf16 v[108:111], v[148:151], v[192:195], v[108:111]
	v_mfma_f32_16x16x32_bf16 v[104:107], v[156:159], v[192:195], v[104:107]
	v_mfma_f32_16x16x32_bf16 v[92:95], v[148:151], v[200:203], v[92:95]
	v_mfma_f32_16x16x32_bf16 v[88:91], v[156:159], v[200:203], v[88:91]
	v_mfma_f32_16x16x32_bf16 v[76:79], v[148:151], v[216:219], v[76:79]
	v_mfma_f32_16x16x32_bf16 v[72:75], v[156:159], v[216:219], v[72:75]
	v_mfma_f32_16x16x32_bf16 v[124:127], v[152:155], v[188:191], v[124:127]
	v_mfma_f32_16x16x32_bf16 v[120:123], v[160:163], v[188:191], v[120:123]
	v_mfma_f32_16x16x32_bf16 v[108:111], v[152:155], v[196:199], v[108:111]
	v_mfma_f32_16x16x32_bf16 v[104:107], v[160:163], v[196:199], v[104:107]
	v_mfma_f32_16x16x32_bf16 v[92:95], v[152:155], v[212:215], v[92:95]
	v_mfma_f32_16x16x32_bf16 v[88:91], v[160:163], v[212:215], v[88:91]
	v_mfma_f32_16x16x32_bf16 v[76:79], v[152:155], v[220:223], v[76:79]
	v_mfma_f32_16x16x32_bf16 v[72:75], v[160:163], v[220:223], v[72:75]
	v_mfma_f32_16x16x32_bf16 v[116:119], v[164:167], v[180:183], v[116:119]
	v_mfma_f32_16x16x32_bf16 v[112:115], v[172:175], v[180:183], v[112:115]
	v_mfma_f32_16x16x32_bf16 v[100:103], v[164:167], v[192:195], v[100:103]
	v_mfma_f32_16x16x32_bf16 v[96:99], v[172:175], v[192:195], v[96:99]
	v_mfma_f32_16x16x32_bf16 v[84:87], v[164:167], v[200:203], v[84:87]
	v_mfma_f32_16x16x32_bf16 v[80:83], v[172:175], v[200:203], v[80:83]
	v_mfma_f32_16x16x32_bf16 v[68:71], v[164:167], v[216:219], v[68:71]
	v_mfma_f32_16x16x32_bf16 v[64:67], v[172:175], v[216:219], v[64:67]
	v_mfma_f32_16x16x32_bf16 v[116:119], v[168:171], v[188:191], v[116:119]
	v_mfma_f32_16x16x32_bf16 v[112:115], v[176:179], v[188:191], v[112:115]
	v_mfma_f32_16x16x32_bf16 v[100:103], v[168:171], v[196:199], v[100:103]
	v_mfma_f32_16x16x32_bf16 v[96:99], v[176:179], v[196:199], v[96:99]
	v_mfma_f32_16x16x32_bf16 v[84:87], v[168:171], v[212:215], v[84:87]
	v_mfma_f32_16x16x32_bf16 v[80:83], v[176:179], v[212:215], v[80:83]
	v_mfma_f32_16x16x32_bf16 v[68:71], v[168:171], v[220:223], v[68:71]
	v_mfma_f32_16x16x32_bf16 v[64:67], v[176:179], v[220:223], v[64:67]
	s_barrier
; #define PG8_WAIT_V(n) asm volatile("s_waitcnt vmcnt(" #n ")" ::: "memory")
; #define PG8_WAIT_VP() asm volatile("s_waitcnt vmcnt(%0)" :: "n"(8 + Epi::NST) : "memory")
; template <class Epi, class Sched>
; __device__ __forceinline__ void gemm_phase(PG8_LAS unsigned char* lds, const Sched& S, const Epi& E, int tid_in) {
;     ...
;         { const int t = 0; PG8_KITER(PG8_WAIT_VP()); }
;         for (int t = 2; t < nt; t += 2) PG8_KITER(PG8_WAIT_V(8));
	s_mov_b32 m0, s70
	v_lshl_add_u64 v[186:187], v[186:187], 0, s[84:85]
	ds_read_b128 v[138:141], v144 offset:49152
	ds_read_b128 v[180:183], v144 offset:50176
	ds_read_b128 v[188:191], v144 offset:51200
	ds_read_b128 v[192:195], v144 offset:52224
	ds_read_b128 v[196:199], v144 offset:53248
	ds_read_b128 v[200:203], v144 offset:54272
	ds_read_b128 v[212:215], v144 offset:55296
	ds_read_b128 v[216:219], v144 offset:56320
	global_load_lds_dwordx4 v[186:187], off
	v_lshl_add_u64 v[186:187], v[206:207], 0, s[84:85]
	s_mov_b32 m0, s15
	s_nop 0
	global_load_lds_dwordx4 v[186:187], off
	v_lshl_add_u64 v[186:187], v[210:211], 0, s[84:85]
	s_mov_b32 m0, s4
	s_nop 0
	global_load_lds_dwordx4 v[186:187], off
	v_lshl_add_u64 v[186:187], v[224:225], 0, s[84:85]
	s_mov_b32 m0, s5
	s_nop 0
	global_load_lds_dwordx4 v[186:187], off
	v_lshl_add_u64 v[186:187], v[226:227], 0, s[84:85]
	s_mov_b32 m0, s67
	s_nop 0
	global_load_lds_dwordx4 v[186:187], off
	v_lshl_add_u64 v[186:187], v[228:229], 0, s[84:85]
	s_mov_b32 m0, s14
	s_nop 0
	global_load_lds_dwordx4 v[186:187], off
	s_waitcnt vmcnt(8)
	s_waitcnt lgkmcnt(0)
	s_barrier
	v_mfma_f32_16x16x32_bf16 v[60:63], v[148:151], v[138:141], v[60:63]
	v_mfma_f32_16x16x32_bf16 v[56:59], v[156:159], v[138:141], v[56:59]
	v_mfma_f32_16x16x32_bf16 v[44:47], v[148:151], v[188:191], v[44:47]
	v_mfma_f32_16x16x32_bf16 v[40:43], v[156:159], v[188:191], v[40:43]
	v_mfma_f32_16x16x32_bf16 v[28:31], v[148:151], v[196:199], v[28:31]
	v_mfma_f32_16x16x32_bf16 v[24:27], v[156:159], v[196:199], v[24:27]
	v_mfma_f32_16x16x32_bf16 v[12:15], v[148:151], v[212:215], v[12:15]
	v_mfma_f32_16x16x32_bf16 v[8:11], v[156:159], v[212:215], v[8:11]
	v_mfma_f32_16x16x32_bf16 v[60:63], v[152:155], v[180:183], v[60:63]
	v_mfma_f32_16x16x32_bf16 v[56:59], v[160:163], v[180:183], v[56:59]
	v_mfma_f32_16x16x32_bf16 v[44:47], v[152:155], v[192:195], v[44:47]
	v_mfma_f32_16x16x32_bf16 v[40:43], v[160:163], v[192:195], v[40:43]
	v_mfma_f32_16x16x32_bf16 v[28:31], v[152:155], v[200:203], v[28:31]
	v_mfma_f32_16x16x32_bf16 v[24:27], v[160:163], v[200:203], v[24:27]
	v_mfma_f32_16x16x32_bf16 v[12:15], v[152:155], v[216:219], v[12:15]
	v_mfma_f32_16x16x32_bf16 v[8:11], v[160:163], v[216:219], v[8:11]
	v_mfma_f32_16x16x32_bf16 v[52:55], v[164:167], v[138:141], v[52:55]
	v_mfma_f32_16x16x32_bf16 v[48:51], v[172:175], v[138:141], v[48:51]
	v_mfma_f32_16x16x32_bf16 v[36:39], v[164:167], v[188:191], v[36:39]
	v_mfma_f32_16x16x32_bf16 v[32:35], v[172:175], v[188:191], v[32:35]
	v_mfma_f32_16x16x32_bf16 v[20:23], v[164:167], v[196:199], v[20:23]
	v_mfma_f32_16x16x32_bf16 v[16:19], v[172:175], v[196:199], v[16:19]
	v_mfma_f32_16x16x32_bf16 v[4:7], v[164:167], v[212:215], v[4:7]
	v_mfma_f32_16x16x32_bf16 v[0:3], v[172:175], v[212:215], v[0:3]
	v_mfma_f32_16x16x32_bf16 v[52:55], v[168:171], v[180:183], v[52:55]
	v_mfma_f32_16x16x32_bf16 v[48:51], v[176:179], v[180:183], v[48:51]
	v_mfma_f32_16x16x32_bf16 v[36:39], v[168:171], v[192:195], v[36:39]
	v_mfma_f32_16x16x32_bf16 v[32:35], v[176:179], v[192:195], v[32:35]
	v_mfma_f32_16x16x32_bf16 v[20:23], v[168:171], v[200:203], v[20:23]
	v_mfma_f32_16x16x32_bf16 v[16:19], v[176:179], v[200:203], v[16:19]
	v_mfma_f32_16x16x32_bf16 v[4:7], v[168:171], v[216:219], v[4:7]
	v_mfma_f32_16x16x32_bf16 v[0:3], v[176:179], v[216:219], v[0:3]
	s_barrier
	s_add_i32 s68, s68, 2
	s_add_u32 s34, s34, 0x100
	s_addc_u32 s35, s35, 0
	s_cmp_gt_u32 s68, 29
	s_cbranch_scc1 .LBB0_918

; __device__ __forceinline__ int lane_id() { int l; asm volatile("v_mbcnt_lo_u32_b32 %0, -1, 0\n\tv_mbcnt_hi_u32_b32 %0, -1, %0" : "=v"(l)); return l; }
;     __device__ __forceinline__ bool next(int i, UnitG& u) const { if (!P.next(i, u)) return false; u.O = O + ((size_t)u.x0 * 256 * 2048 + (size_t)u.x1 * 256) * 2; u.ldo = 2048; u.kind = 0; return true; }
; template <class Epi, class Sched>
; __device__ __forceinline__ void gemm_phase(PG8_LAS unsigned char* lds, const Sched& S, const Epi& E, int tid_in) {
;     ...
;     for (;;) {
;         int aoff, boff; { const int l3 = lane_id(), fr3 = l3 & 15, fq3 = l3 >> 4; aoff = lds_byte(wr * 64 + fr3, fq3 * 8); boff = lds_byte(wc * 32 + fr3, fq3 * 8); }
;         const bool has_next = S.next(ui + 1, nxt);
;         const char* nA = has_next ? nxt.A : cA; const char* nB = has_next ? nxt.B : cB;
;         const int nlda = has_next ? nxt.lda : cur.lda, nldb = has_next ? nxt.ldb : cur.ldb;
;         unsigned nvA, nvB; { int r2, c2; stage_rc((wid * 64 + lane_id()) * 16, r2, c2); const int rb2 = Epi::PERM ? ((r2 & ~31) + perm32(r2 & 31)) : r2;
;             nvA = (unsigned)(r2 * nlda + c2) * 2u; nvB = (unsigned)(rb2 * nldb + c2) * 2u; }
;         const unsigned nqA = (unsigned)nlda * 128u, nqB = (unsigned)nldb * 128u;
;         const int nt = cur.K / BK;
.LBB0_1078:
	v_and_b32_e32 v1, 15, v0
	v_or_b32_e32 v2, s53, v1
	v_lshlrev_b32_e32 v5, 4, v0
	v_lshlrev_b32_e32 v3, 6, v2
	v_and_b32_e32 v4, 48, v0
	s_movk_i32 s24, 0x3c0
	v_and_b32_e32 v5, 0xfffffc00, v5
	v_lshlrev_b32_e32 v2, 2, v2
	v_and_or_b32 v3, v3, s24, v4
	v_add_u32_e32 v6, s54, v5
	v_and_b32_e32 v2, 32, v2
	v_lshlrev_b32_e32 v0, 2, v0
	v_bitop3_b32 v32, v3, v6, v2 bitop3:0xde
	v_lshl_or_b32 v1, v1, 6, v4
	v_add_u32_e32 v2, s56, v5
	v_and_b32_e32 v0, 32, v0
	v_bitop3_b32 v139, v1, v2, v0 bitop3:0xde
	v_mbcnt_lo_u32_b32 v0, -1, 0
	v_mbcnt_hi_u32_b32 v0, -1, v0
	s_mov_b32 s24, 0xfffe0
	v_add_u32_e32 v0, s57, v0
	v_ashrrev_i32_e32 v2, 31, v0
	v_lshrrev_b32_e32 v2, 26, v2
	v_lshlrev_b32_e32 v1, 4, v0
	v_add_u32_e32 v2, v0, v2
	v_bfe_i32 v0, v0, 27, 1
	v_lshrrev_b32_e32 v0, 22, v0
	v_add_u32_e32 v0, v1, v0
	v_and_b32_e32 v0, 0xfffffc00, v0
	v_sub_u32_e32 v0, v1, v0
	v_lshrrev_b32_e32 v1, 4, v0
	v_bitop3_b32 v0, v1, v0, 32 bitop3:0x6c
	v_ashrrev_i32_e32 v3, 31, v0
	v_ashrrev_i32_e32 v2, 6, v2
	v_lshrrev_b32_e32 v3, 26, v3
	v_lshlrev_b32_e32 v1, 3, v2
	v_add_u32_e32 v3, v0, v3
	v_and_b32_e32 v1, -16, v1
	v_ashrrev_i32_e32 v4, 6, v3
	v_and_b32_e32 v3, 0xc0, v3
	v_add_u32_e32 v1, v4, v1
	v_sub_u32_e32 v0, v0, v3
	v_lshlrev_b32_e32 v2, 5, v2
	v_ashrrev_i16_sdwa v0, v205, sext(v0) dst_sel:DWORD dst_unused:UNUSED_PAD src0_sel:DWORD src1_sel:BYTE_0
	v_lshrrev_b32_e32 v3, 2, v1
	v_and_b32_e32 v2, 32, v2
	v_bfe_i32 v0, v0, 0, 16
	v_lshlrev_b32_e32 v16, 1, v1
	v_and_b32_e32 v17, 4, v3
	v_and_b32_e32 v3, 3, v4
	s_add_i32 s67, 0, 0x10000
	s_add_i32 s71, 0, 0x14000
	v_and_or_b32 v18, v1, s24, v3
	v_add_lshl_u32 v33, v2, v0, 1
	v_add_u32_e32 v136, s67, v139
	v_and_b32_e32 v16, 24, v16
	v_add_u32_e32 v137, s71, v139
	v_lshl_add_u32 v134, v1, 12, v33
	ds_read_b128 v[0:3], v136
	ds_read_b128 v[4:7], v136 offset:1024
	ds_read_b128 v[8:11], v136 offset:2048
	ds_read_b128 v[12:15], v136 offset:3072
	v_or3_b32 v34, v18, v17, v16
	ds_read_b128 v[16:19], v137
	ds_read_b128 v[20:23], v137 offset:1024
	ds_read_b128 v[24:27], v137 offset:2048
	ds_read_b128 v[28:31], v137 offset:3072
	v_lshl_add_u32 v135, v34, 12, v33
	v_mov_b32_e32 v131, v185
	v_lshl_add_u64 v[132:133], s[20:21], 0, v[130:131]
	s_add_i32 s65, s35, 0xc000
	v_add_u32_e32 v138, 0, v32
	v_lshl_add_u64 v[64:65], v[132:133], 0, s[80:81]
	s_mov_b32 m0, s65
	s_add_i32 s66, s35, 0xe000
	ds_read_b128 v[32:35], v138
	ds_read_b128 v[36:39], v138 offset:1024
	ds_read_b128 v[40:43], v138 offset:2048
	ds_read_b128 v[44:47], v138 offset:3072
	ds_read_b128 v[48:51], v138 offset:4096
	ds_read_b128 v[52:55], v138 offset:5120
	ds_read_b128 v[56:59], v138 offset:6144
	ds_read_b128 v[60:63], v138 offset:7168
	global_load_lds_dwordx4 v[64:65], off
	v_lshl_add_u64 v[64:65], v[132:133], 0, s[78:79]
	s_mov_b32 m0, s66
	s_nop 0
	global_load_lds_dwordx4 v[64:65], off
	s_waitcnt vmcnt(24)
	s_waitcnt lgkmcnt(0)
	s_barrier
	v_mfma_f32_16x16x32_bf16 v[64:67], v[0:3], v[32:35], 0
	v_mfma_f32_16x16x32_bf16 v[68:71], v[8:11], v[32:35], 0
	v_mfma_f32_16x16x32_bf16 v[72:75], v[0:3], v[40:43], 0
	v_mfma_f32_16x16x32_bf16 v[76:79], v[8:11], v[40:43], 0
	v_mfma_f32_16x16x32_bf16 v[80:83], v[0:3], v[48:51], 0
	v_mfma_f32_16x16x32_bf16 v[84:87], v[8:11], v[48:51], 0
	v_mfma_f32_16x16x32_bf16 v[88:91], v[0:3], v[56:59], 0
	v_mfma_f32_16x16x32_bf16 v[92:95], v[8:11], v[56:59], 0
	v_mfma_f32_16x16x32_bf16 v[64:67], v[4:7], v[36:39], v[64:67]
	v_mfma_f32_16x16x32_bf16 v[68:71], v[12:15], v[36:39], v[68:71]
	v_mfma_f32_16x16x32_bf16 v[72:75], v[4:7], v[44:47], v[72:75]
	v_mfma_f32_16x16x32_bf16 v[76:79], v[12:15], v[44:47], v[76:79]
	v_mfma_f32_16x16x32_bf16 v[80:83], v[4:7], v[52:55], v[80:83]
	v_mfma_f32_16x16x32_bf16 v[84:87], v[12:15], v[52:55], v[84:87]
	v_mfma_f32_16x16x32_bf16 v[88:91], v[4:7], v[60:63], v[88:91]
	v_mfma_f32_16x16x32_bf16 v[92:95], v[12:15], v[60:63], v[92:95]
	v_mfma_f32_16x16x32_bf16 v[96:99], v[16:19], v[32:35], 0
	v_mfma_f32_16x16x32_bf16 v[32:35], v[24:27], v[32:35], 0
	v_mfma_f32_16x16x32_bf16 v[108:111], v[28:31], v[36:39], v[32:35]
	v_mfma_f32_16x16x32_bf16 v[32:35], v[16:19], v[40:43], 0
	v_mfma_f32_16x16x32_bf16 v[140:143], v[20:23], v[44:47], v[32:35]
	v_mfma_f32_16x16x32_bf16 v[32:35], v[24:27], v[40:43], 0
	v_mfma_f32_16x16x32_bf16 v[40:43], v[28:31], v[44:47], v[32:35]
	v_mfma_f32_16x16x32_bf16 v[32:35], v[16:19], v[48:51], 0
	v_mfma_f32_16x16x32_bf16 v[44:47], v[20:23], v[52:55], v[32:35]
	v_mfma_f32_16x16x32_bf16 v[32:35], v[24:27], v[48:51], 0
	v_mfma_f32_16x16x32_bf16 v[48:51], v[28:31], v[52:55], v[32:35]
	v_mfma_f32_16x16x32_bf16 v[32:35], v[16:19], v[56:59], 0
	v_mfma_f32_16x16x32_bf16 v[52:55], v[20:23], v[60:63], v[32:35]
	v_mfma_f32_16x16x32_bf16 v[32:35], v[24:27], v[56:59], 0
	v_mfma_f32_16x16x32_bf16 v[104:107], v[20:23], v[36:39], v[96:99]
	v_mfma_f32_16x16x32_bf16 v[56:59], v[28:31], v[60:63], v[32:35]
	s_barrier
	v_mov_b32_e32 v129, v185
	v_lshl_add_u64 v[186:187], s[22:23], 0, v[128:129]
	s_mov_b64 s[24:25], 0x100
	s_add_i32 s67, s67, s34
	v_lshl_add_u64 v[124:125], v[186:187], 0, s[24:25]
	s_mov_b32 m0, s67
	s_mov_b64 s[74:75], 0x40100
	s_add_i32 s70, s67, 0x2000
	ds_read_b128 v[32:35], v138 offset:16384
	ds_read_b128 v[36:39], v138 offset:17408
	ds_read_b128 v[60:63], v138 offset:18432
	ds_read_b128 v[96:99], v138 offset:19456
	ds_read_b128 v[100:103], v138 offset:20480
	ds_read_b128 v[112:115], v138 offset:21504
	ds_read_b128 v[116:119], v138 offset:22528
	ds_read_b128 v[120:123], v138 offset:23552
	global_load_lds_dwordx4 v[124:125], off
	v_lshl_add_u64 v[124:125], v[186:187], 0, s[74:75]
	s_mov_b32 m0, s70
	s_mov_b64 s[76:77], 0x80100
	s_add_i32 s71, s71, s34
	global_load_lds_dwordx4 v[124:125], off
	v_lshl_add_u64 v[124:125], v[186:187], 0, s[76:77]
	s_mov_b32 m0, s71
	s_mov_b64 s[86:87], 0xc0100
	s_add_i32 s72, s71, 0x2000
	global_load_lds_dwordx4 v[124:125], off
	v_lshl_add_u64 v[124:125], v[186:187], 0, s[86:87]
	s_mov_b32 m0, s72
	s_nop 0
	global_load_lds_dwordx4 v[124:125], off
	v_lshl_add_u64 v[124:125], v[132:133], 0, s[24:25]
	s_mov_b32 m0, s35
	s_nop 0
	global_load_lds_dwordx4 v[124:125], off
	v_lshl_add_u64 v[124:125], v[132:133], 0, s[74:75]
	s_mov_b32 m0, s44
	s_nop 0
	global_load_lds_dwordx4 v[124:125], off
	s_waitcnt vmcnt(24)
	s_waitcnt lgkmcnt(0)
	s_barrier
	v_mfma_f32_16x16x32_bf16 v[124:127], v[0:3], v[32:35], 0
	v_mfma_f32_16x16x32_bf16 v[144:147], v[4:7], v[36:39], v[124:127]
	v_mfma_f32_16x16x32_bf16 v[124:127], v[8:11], v[32:35], 0
	v_mfma_f32_16x16x32_bf16 v[148:151], v[12:15], v[36:39], v[124:127]
	v_mfma_f32_16x16x32_bf16 v[124:127], v[0:3], v[60:63], 0
	v_mfma_f32_16x16x32_bf16 v[152:155], v[4:7], v[96:99], v[124:127]
	v_mfma_f32_16x16x32_bf16 v[124:127], v[8:11], v[60:63], 0
	v_mfma_f32_16x16x32_bf16 v[156:159], v[12:15], v[96:99], v[124:127]
	v_mfma_f32_16x16x32_bf16 v[124:127], v[0:3], v[100:103], 0
	v_mfma_f32_16x16x32_bf16 v[0:3], v[0:3], v[116:119], 0
	v_mfma_f32_16x16x32_bf16 v[160:163], v[4:7], v[112:115], v[124:127]
	v_mfma_f32_16x16x32_bf16 v[0:3], v[4:7], v[120:123], v[0:3]
	v_mfma_f32_16x16x32_bf16 v[4:7], v[8:11], v[116:119], 0
	v_mfma_f32_16x16x32_bf16 v[124:127], v[8:11], v[100:103], 0
	v_mfma_f32_16x16x32_bf16 v[8:11], v[12:15], v[120:123], v[4:7]
	v_mfma_f32_16x16x32_bf16 v[164:167], v[12:15], v[112:115], v[124:127]
	v_mfma_f32_16x16x32_bf16 v[4:7], v[16:19], v[32:35], 0
	v_mfma_f32_16x16x32_bf16 v[12:15], v[20:23], v[36:39], v[4:7]
	v_mfma_f32_16x16x32_bf16 v[4:7], v[24:27], v[32:35], 0
	v_mfma_f32_16x16x32_bf16 v[168:171], v[28:31], v[36:39], v[4:7]
	v_mfma_f32_16x16x32_bf16 v[4:7], v[16:19], v[60:63], 0
	v_mfma_f32_16x16x32_bf16 v[172:175], v[20:23], v[96:99], v[4:7]
	v_mfma_f32_16x16x32_bf16 v[4:7], v[24:27], v[60:63], 0
	v_mfma_f32_16x16x32_bf16 v[176:179], v[28:31], v[96:99], v[4:7]
	v_mfma_f32_16x16x32_bf16 v[4:7], v[16:19], v[100:103], 0
	v_mfma_f32_16x16x32_bf16 v[180:183], v[20:23], v[112:115], v[4:7]
	v_mfma_f32_16x16x32_bf16 v[4:7], v[24:27], v[100:103], 0
	v_mfma_f32_16x16x32_bf16 v[188:191], v[28:31], v[112:115], v[4:7]
	v_mfma_f32_16x16x32_bf16 v[4:7], v[16:19], v[116:119], 0
	v_mfma_f32_16x16x32_bf16 v[192:195], v[20:23], v[120:123], v[4:7]
	v_mfma_f32_16x16x32_bf16 v[4:7], v[24:27], v[116:119], 0
	v_mfma_f32_16x16x32_bf16 v[196:199], v[28:31], v[120:123], v[4:7]
	s_barrier
	s_add_i32 s73, 0, 0x18000
	s_add_i32 s75, 0, 0x1c000
	v_add_u32_e32 v129, s73, v139
	v_add_u32_e32 v131, s75, v139
	s_nop 0
	ds_read_b128 v[4:7], v129
	ds_read_b128 v[24:27], v129 offset:1024
	ds_read_b128 v[28:31], v129 offset:2048
	ds_read_b128 v[60:63], v129 offset:3072
	ds_read_b128 v[200:203], v131
	ds_read_b128 v[212:215], v131 offset:1024
	ds_read_b128 v[216:219], v131 offset:2048
	ds_read_b128 v[220:223], v131 offset:3072
	s_mov_b32 m0, s45
	v_lshl_add_u64 v[32:33], v[132:133], 0, s[76:77]
	ds_read_b128 v[16:19], v138 offset:32768
	ds_read_b128 v[20:23], v138 offset:33792
	ds_read_b128 v[224:227], v138 offset:34816
	ds_read_b128 v[228:231], v138 offset:35840
	ds_read_b128 v[232:235], v138 offset:36864
	ds_read_b128 v[236:239], v138 offset:37888
	ds_read_b128 v[240:243], v138 offset:38912
	ds_read_b128 v[244:247], v138 offset:39936
	global_load_lds_dwordx4 v[32:33], off
	v_lshl_add_u64 v[32:33], v[132:133], 0, s[86:87]
	s_mov_b32 m0, s46
	s_nop 0
	global_load_lds_dwordx4 v[32:33], off
	s_waitcnt vmcnt(8)
	s_waitcnt lgkmcnt(0)
	s_barrier
	v_mfma_f32_16x16x32_bf16 v[32:35], v[4:7], v[16:19], v[64:67]
	v_mfma_f32_16x16x32_bf16 v[116:119], v[24:27], v[20:23], v[32:35]
	v_mfma_f32_16x16x32_bf16 v[32:35], v[28:31], v[16:19], v[68:71]
	v_mfma_f32_16x16x32_bf16 v[112:115], v[60:63], v[20:23], v[32:35]
	v_mfma_f32_16x16x32_bf16 v[32:35], v[4:7], v[224:227], v[72:75]
	v_mfma_f32_16x16x32_bf16 v[100:103], v[24:27], v[228:231], v[32:35]
	v_mfma_f32_16x16x32_bf16 v[32:35], v[28:31], v[224:227], v[76:79]
	v_mfma_f32_16x16x32_bf16 v[96:99], v[60:63], v[228:231], v[32:35]
	v_mfma_f32_16x16x32_bf16 v[32:35], v[4:7], v[232:235], v[80:83]
	v_mfma_f32_16x16x32_bf16 v[68:71], v[24:27], v[236:239], v[32:35]
	v_mfma_f32_16x16x32_bf16 v[32:35], v[28:31], v[232:235], v[84:87]
	v_mfma_f32_16x16x32_bf16 v[64:67], v[60:63], v[236:239], v[32:35]
	v_mfma_f32_16x16x32_bf16 v[32:35], v[4:7], v[240:243], v[88:91]
	v_mfma_f32_16x16x32_bf16 v[36:39], v[24:27], v[244:247], v[32:35]
	v_mfma_f32_16x16x32_bf16 v[32:35], v[28:31], v[240:243], v[92:95]
	v_mfma_f32_16x16x32_bf16 v[32:35], v[60:63], v[244:247], v[32:35]
	v_mfma_f32_16x16x32_bf16 v[72:75], v[200:203], v[16:19], v[104:107]
	v_mfma_f32_16x16x32_bf16 v[16:19], v[216:219], v[16:19], v[108:111]
	v_mfma_f32_16x16x32_bf16 v[120:123], v[220:223], v[20:23], v[16:19]
	v_mfma_f32_16x16x32_bf16 v[16:19], v[200:203], v[224:227], v[140:143]
	v_mfma_f32_16x16x32_bf16 v[108:111], v[212:215], v[228:231], v[16:19]
	v_mfma_f32_16x16x32_bf16 v[16:19], v[216:219], v[224:227], v[40:43]
	v_mfma_f32_16x16x32_bf16 v[104:107], v[220:223], v[228:231], v[16:19]
	v_mfma_f32_16x16x32_bf16 v[16:19], v[200:203], v[232:235], v[44:47]
	v_mfma_f32_16x16x32_bf16 v[84:87], v[212:215], v[236:239], v[16:19]
	v_mfma_f32_16x16x32_bf16 v[16:19], v[216:219], v[232:235], v[48:51]
	v_mfma_f32_16x16x32_bf16 v[80:83], v[220:223], v[236:239], v[16:19]
	v_mfma_f32_16x16x32_bf16 v[16:19], v[200:203], v[240:243], v[52:55]
	v_mfma_f32_16x16x32_bf16 v[52:55], v[212:215], v[244:247], v[16:19]
	v_mfma_f32_16x16x32_bf16 v[16:19], v[216:219], v[240:243], v[56:59]
	v_mfma_f32_16x16x32_bf16 v[124:127], v[212:215], v[20:23], v[72:75]
	v_mfma_f32_16x16x32_bf16 v[48:51], v[220:223], v[244:247], v[16:19]
	s_barrier
	s_mov_b64 s[24:25], 0x180
	s_add_i32 s73, s73, s34
	s_nop 1
	v_lshl_add_u64 v[16:17], v[186:187], 0, s[24:25]
	s_mov_b32 m0, s73
	s_mov_b64 s[86:87], 0x40180
	s_add_i32 s74, s73, 0x2000
	ds_read_b128 v[56:59], v138 offset:49152
	ds_read_b128 v[88:91], v138 offset:50176
	ds_read_b128 v[140:143], v138 offset:51200
	ds_read_b128 v[224:227], v138 offset:52224
	ds_read_b128 v[228:231], v138 offset:53248
	ds_read_b128 v[232:235], v138 offset:54272
	ds_read_b128 v[236:239], v138 offset:55296
	ds_read_b128 v[240:243], v138 offset:56320
	global_load_lds_dwordx4 v[16:17], off
	v_lshl_add_u64 v[16:17], v[186:187], 0, s[86:87]
	s_mov_b32 m0, s74
	s_mov_b64 s[62:63], 0x80180
	s_add_i32 s75, s75, s34
	global_load_lds_dwordx4 v[16:17], off
	v_lshl_add_u64 v[16:17], v[186:187], 0, s[62:63]
	s_mov_b32 m0, s75
	s_mov_b64 s[4:5], 0xc0180
	s_add_i32 s76, s75, 0x2000
	global_load_lds_dwordx4 v[16:17], off
	v_lshl_add_u64 v[16:17], v[186:187], 0, s[4:5]
	s_mov_b32 m0, s76
	s_nop 0
	global_load_lds_dwordx4 v[16:17], off
	v_lshl_add_u64 v[16:17], v[132:133], 0, s[24:25]
	s_mov_b32 m0, s48
	s_nop 0
	global_load_lds_dwordx4 v[16:17], off
	v_lshl_add_u64 v[16:17], v[132:133], 0, s[86:87]
	s_mov_b32 m0, s51
	s_nop 0
	global_load_lds_dwordx4 v[16:17], off
	s_waitcnt vmcnt(8)
	s_waitcnt lgkmcnt(0)
	s_barrier
	v_mfma_f32_16x16x32_bf16 v[16:19], v[4:7], v[56:59], v[144:147]
	v_mfma_f32_16x16x32_bf16 v[76:79], v[24:27], v[88:91], v[16:19]
	v_mfma_f32_16x16x32_bf16 v[16:19], v[28:31], v[56:59], v[148:151]
	v_mfma_f32_16x16x32_bf16 v[72:75], v[60:63], v[88:91], v[16:19]
	v_mfma_f32_16x16x32_bf16 v[16:19], v[4:7], v[140:143], v[152:155]
	v_mfma_f32_16x16x32_bf16 v[44:47], v[24:27], v[224:227], v[16:19]
	v_mfma_f32_16x16x32_bf16 v[16:19], v[28:31], v[140:143], v[156:159]
	v_mfma_f32_16x16x32_bf16 v[40:43], v[60:63], v[224:227], v[16:19]
	v_mfma_f32_16x16x32_bf16 v[16:19], v[4:7], v[228:231], v[160:163]
	v_mfma_f32_16x16x32_bf16 v[0:3], v[4:7], v[236:239], v[0:3]
	v_mfma_f32_16x16x32_bf16 v[20:23], v[24:27], v[232:235], v[16:19]
	v_mfma_f32_16x16x32_bf16 v[16:19], v[28:31], v[228:231], v[164:167]
	v_mfma_f32_16x16x32_bf16 v[4:7], v[24:27], v[240:243], v[0:3]
	v_mfma_f32_16x16x32_bf16 v[0:3], v[28:31], v[236:239], v[8:11]
	v_mfma_f32_16x16x32_bf16 v[16:19], v[60:63], v[232:235], v[16:19]
	v_mfma_f32_16x16x32_bf16 v[0:3], v[60:63], v[240:243], v[0:3]
	v_mfma_f32_16x16x32_bf16 v[8:11], v[200:203], v[56:59], v[12:15]
	v_mfma_f32_16x16x32_bf16 v[92:95], v[212:215], v[88:91], v[8:11]
	v_mfma_f32_16x16x32_bf16 v[8:11], v[216:219], v[56:59], v[168:171]
	v_mfma_f32_16x16x32_bf16 v[88:91], v[220:223], v[88:91], v[8:11]
	v_mfma_f32_16x16x32_bf16 v[8:11], v[200:203], v[140:143], v[172:175]
	v_mfma_f32_16x16x32_bf16 v[60:63], v[212:215], v[224:227], v[8:11]
	v_mfma_f32_16x16x32_bf16 v[8:11], v[216:219], v[140:143], v[176:179]
	v_mfma_f32_16x16x32_bf16 v[56:59], v[220:223], v[224:227], v[8:11]
	v_mfma_f32_16x16x32_bf16 v[8:11], v[200:203], v[228:231], v[180:183]
	v_mfma_f32_16x16x32_bf16 v[28:31], v[212:215], v[232:235], v[8:11]
	v_mfma_f32_16x16x32_bf16 v[8:11], v[216:219], v[228:231], v[188:191]
	v_mfma_f32_16x16x32_bf16 v[24:27], v[220:223], v[232:235], v[8:11]
	v_mfma_f32_16x16x32_bf16 v[8:11], v[200:203], v[236:239], v[192:195]
	v_mfma_f32_16x16x32_bf16 v[12:15], v[212:215], v[240:243], v[8:11]
	v_mfma_f32_16x16x32_bf16 v[8:11], v[216:219], v[236:239], v[196:199]
	v_mfma_f32_16x16x32_bf16 v[8:11], v[220:223], v[240:243], v[8:11]
	s_barrier
	s_add_u32 s68, s22, 0x200
	s_addc_u32 s77, s23, 0
	s_mov_b32 s82, 0
	s_mov_b64 s[22:23], 0
.LBB0_1079:
	ds_read_b128 v[140:143], v136
	ds_read_b128 v[144:147], v136 offset:1024
	ds_read_b128 v[148:151], v136 offset:2048
	ds_read_b128 v[152:155], v136 offset:3072
	ds_read_b128 v[156:159], v137
	ds_read_b128 v[160:163], v137 offset:1024
	ds_read_b128 v[164:167], v137 offset:2048
	ds_read_b128 v[168:171], v137 offset:3072
	s_add_u32 s24, s20, s22
	s_addc_u32 s25, s21, s23
	s_add_u32 s86, s24, 0x200
	s_addc_u32 s87, s25, 0
	s_add_u32 s92, s68, s22
	s_addc_u32 s93, s77, s23
	s_cmpk_eq_i32 s22, 0xe00
	s_cselect_b64 vcc, -1, 0
	s_and_b64 s[24:25], vcc, exec
	v_cndmask_b32_e32 v186, v130, v134, vcc
	s_cselect_b32 s25, s15, s87
	s_cselect_b32 s24, s14, s86
	s_cselect_b32 s87, s17, s93
	s_cselect_b32 s86, s16, s92
	v_cndmask_b32_e32 v184, v128, v135, vcc
	v_lshl_add_u64 v[206:207], v[132:133], 0, s[22:23]
	s_mov_b32 m0, s65
	v_lshl_add_u64 v[210:211], v[206:207], 0, s[62:63]
	ds_read_b128 v[172:175], v138
	ds_read_b128 v[176:179], v138 offset:1024
	ds_read_b128 v[180:183], v138 offset:2048
	ds_read_b128 v[188:191], v138 offset:3072
	ds_read_b128 v[192:195], v138 offset:4096
	ds_read_b128 v[196:199], v138 offset:5120
	ds_read_b128 v[200:203], v138 offset:6144
	ds_read_b128 v[212:215], v138 offset:7168
	global_load_lds_dwordx4 v[210:211], off
	v_lshl_add_u64 v[206:207], v[206:207], 0, s[4:5]
	s_mov_b32 m0, s66
	s_nop 0
	global_load_lds_dwordx4 v[206:207], off
	s_waitcnt vmcnt(8)
	s_waitcnt lgkmcnt(0)
	s_barrier
	v_mfma_f32_16x16x32_bf16 v[116:119], v[140:143], v[172:175], v[116:119]
	v_mfma_f32_16x16x32_bf16 v[112:115], v[148:151], v[172:175], v[112:115]
	v_mfma_f32_16x16x32_bf16 v[100:103], v[140:143], v[180:183], v[100:103]
	v_mfma_f32_16x16x32_bf16 v[96:99], v[148:151], v[180:183], v[96:99]
	v_mfma_f32_16x16x32_bf16 v[68:71], v[140:143], v[192:195], v[68:71]
	v_mfma_f32_16x16x32_bf16 v[64:67], v[148:151], v[192:195], v[64:67]
	v_mfma_f32_16x16x32_bf16 v[36:39], v[140:143], v[200:203], v[36:39]
	v_mfma_f32_16x16x32_bf16 v[32:35], v[148:151], v[200:203], v[32:35]
	v_mfma_f32_16x16x32_bf16 v[116:119], v[144:147], v[176:179], v[116:119]
	v_mfma_f32_16x16x32_bf16 v[112:115], v[152:155], v[176:179], v[112:115]
	v_mfma_f32_16x16x32_bf16 v[100:103], v[144:147], v[188:191], v[100:103]
	v_mfma_f32_16x16x32_bf16 v[96:99], v[152:155], v[188:191], v[96:99]
	v_mfma_f32_16x16x32_bf16 v[68:71], v[144:147], v[196:199], v[68:71]
	v_mfma_f32_16x16x32_bf16 v[64:67], v[152:155], v[196:199], v[64:67]
	v_mfma_f32_16x16x32_bf16 v[36:39], v[144:147], v[212:215], v[36:39]
	v_mfma_f32_16x16x32_bf16 v[32:35], v[152:155], v[212:215], v[32:35]
	v_mfma_f32_16x16x32_bf16 v[124:127], v[156:159], v[172:175], v[124:127]
	v_mfma_f32_16x16x32_bf16 v[120:123], v[164:167], v[172:175], v[120:123]
	v_mfma_f32_16x16x32_bf16 v[108:111], v[156:159], v[180:183], v[108:111]
	v_mfma_f32_16x16x32_bf16 v[104:107], v[164:167], v[180:183], v[104:107]
	v_mfma_f32_16x16x32_bf16 v[84:87], v[156:159], v[192:195], v[84:87]
	v_mfma_f32_16x16x32_bf16 v[80:83], v[164:167], v[192:195], v[80:83]
	v_mfma_f32_16x16x32_bf16 v[52:55], v[156:159], v[200:203], v[52:55]
	v_mfma_f32_16x16x32_bf16 v[48:51], v[164:167], v[200:203], v[48:51]
	v_mfma_f32_16x16x32_bf16 v[124:127], v[160:163], v[176:179], v[124:127]
	v_mfma_f32_16x16x32_bf16 v[120:123], v[168:171], v[176:179], v[120:123]
	v_mfma_f32_16x16x32_bf16 v[108:111], v[160:163], v[188:191], v[108:111]
	v_mfma_f32_16x16x32_bf16 v[104:107], v[168:171], v[188:191], v[104:107]
	v_mfma_f32_16x16x32_bf16 v[84:87], v[160:163], v[196:199], v[84:87]
	v_mfma_f32_16x16x32_bf16 v[80:83], v[168:171], v[196:199], v[80:83]
	v_mfma_f32_16x16x32_bf16 v[52:55], v[160:163], v[212:215], v[52:55]
	v_mfma_f32_16x16x32_bf16 v[48:51], v[168:171], v[212:215], v[48:51]
	s_barrier
	s_mov_b32 m0, s67
	v_lshl_add_u64 v[206:207], s[86:87], 0, v[184:185]
	ds_read_b128 v[172:175], v138 offset:16384
	ds_read_b128 v[176:179], v138 offset:17408
	ds_read_b128 v[180:183], v138 offset:18432
	ds_read_b128 v[188:191], v138 offset:19456
	ds_read_b128 v[192:195], v138 offset:20480
	ds_read_b128 v[196:199], v138 offset:21504
	ds_read_b128 v[200:203], v138 offset:22528
	ds_read_b128 v[212:215], v138 offset:23552
	global_load_lds_dwordx4 v184, s[86:87]
	v_lshl_add_u64 v[210:211], v[206:207], 0, s[88:89]
	s_mov_b32 m0, s70
	v_mov_b32_e32 v187, v185
	global_load_lds_dwordx4 v[210:211], off
	v_lshl_add_u64 v[210:211], v[206:207], 0, s[90:91]
	s_mov_b32 m0, s71
	s_nop 0
	global_load_lds_dwordx4 v[210:211], off
	v_lshl_add_u64 v[210:211], v[206:207], 0, s[96:97]
	s_mov_b32 m0, s72
	s_nop 0
	global_load_lds_dwordx4 v[210:211], off
	v_lshl_add_u64 v[210:211], s[24:25], 0, v[186:187]
	s_mov_b32 m0, s35
	s_nop 0
	global_load_lds_dwordx4 v186, s[24:25]
	v_lshl_add_u64 v[186:187], v[210:211], 0, s[88:89]
	s_mov_b32 m0, s44
	s_nop 0
	global_load_lds_dwordx4 v[186:187], off
	s_waitcnt vmcnt(8)
	s_waitcnt lgkmcnt(0)
	s_barrier
	v_mfma_f32_16x16x32_bf16 v[76:79], v[140:143], v[172:175], v[76:79]
	v_mfma_f32_16x16x32_bf16 v[72:75], v[148:151], v[172:175], v[72:75]
	v_mfma_f32_16x16x32_bf16 v[44:47], v[140:143], v[180:183], v[44:47]
	v_mfma_f32_16x16x32_bf16 v[40:43], v[148:151], v[180:183], v[40:43]
	v_mfma_f32_16x16x32_bf16 v[20:23], v[140:143], v[192:195], v[20:23]
	v_mfma_f32_16x16x32_bf16 v[16:19], v[148:151], v[192:195], v[16:19]
	v_mfma_f32_16x16x32_bf16 v[4:7], v[140:143], v[200:203], v[4:7]
	v_mfma_f32_16x16x32_bf16 v[0:3], v[148:151], v[200:203], v[0:3]
	v_mfma_f32_16x16x32_bf16 v[76:79], v[144:147], v[176:179], v[76:79]
	v_mfma_f32_16x16x32_bf16 v[72:75], v[152:155], v[176:179], v[72:75]
	v_mfma_f32_16x16x32_bf16 v[44:47], v[144:147], v[188:191], v[44:47]
	v_mfma_f32_16x16x32_bf16 v[40:43], v[152:155], v[188:191], v[40:43]
	v_mfma_f32_16x16x32_bf16 v[20:23], v[144:147], v[196:199], v[20:23]
	v_mfma_f32_16x16x32_bf16 v[16:19], v[152:155], v[196:199], v[16:19]
	v_mfma_f32_16x16x32_bf16 v[4:7], v[144:147], v[212:215], v[4:7]
	v_mfma_f32_16x16x32_bf16 v[0:3], v[152:155], v[212:215], v[0:3]
	v_mfma_f32_16x16x32_bf16 v[92:95], v[156:159], v[172:175], v[92:95]
	v_mfma_f32_16x16x32_bf16 v[88:91], v[164:167], v[172:175], v[88:91]
	v_mfma_f32_16x16x32_bf16 v[60:63], v[156:159], v[180:183], v[60:63]
	v_mfma_f32_16x16x32_bf16 v[56:59], v[164:167], v[180:183], v[56:59]
	v_mfma_f32_16x16x32_bf16 v[28:31], v[156:159], v[192:195], v[28:31]
	v_mfma_f32_16x16x32_bf16 v[24:27], v[164:167], v[192:195], v[24:27]
	v_mfma_f32_16x16x32_bf16 v[12:15], v[156:159], v[200:203], v[12:15]
	v_mfma_f32_16x16x32_bf16 v[8:11], v[164:167], v[200:203], v[8:11]
	v_mfma_f32_16x16x32_bf16 v[92:95], v[160:163], v[176:179], v[92:95]
	v_mfma_f32_16x16x32_bf16 v[88:91], v[168:171], v[176:179], v[88:91]
	v_mfma_f32_16x16x32_bf16 v[60:63], v[160:163], v[188:191], v[60:63]
	v_mfma_f32_16x16x32_bf16 v[56:59], v[168:171], v[188:191], v[56:59]
	v_mfma_f32_16x16x32_bf16 v[28:31], v[160:163], v[196:199], v[28:31]
	v_mfma_f32_16x16x32_bf16 v[24:27], v[168:171], v[196:199], v[24:27]
	v_mfma_f32_16x16x32_bf16 v[12:15], v[160:163], v[212:215], v[12:15]
	v_mfma_f32_16x16x32_bf16 v[8:11], v[168:171], v[212:215], v[8:11]
	s_barrier
; #define PG8_WAIT_V(n) asm volatile("s_waitcnt vmcnt(" #n ")" ::: "memory")
; #define PG8_WAIT_VP() asm volatile("s_waitcnt vmcnt(%0)" :: "n"(8 + Epi::NST) : "memory")
; #define PG8_BAR __builtin_amdgcn_s_barrier()
; template <class Epi, class Sched>
; __device__ __forceinline__ void gemm_phase(PG8_LAS unsigned char* lds, const Sched& S, const Epi& E, int tid_in) {
;     ...
;         { const int t = 0; PG8_KITER(PG8_WAIT_VP()); }
;         for (int t = 2; t < nt; t += 2) PG8_KITER(PG8_WAIT_V(8));
;     ...
;         if (wr == 0) PG8_BAR;
	ds_read_b128 v[140:143], v129
	ds_read_b128 v[144:147], v129 offset:1024
	ds_read_b128 v[148:151], v129 offset:2048
	ds_read_b128 v[152:155], v129 offset:3072
	ds_read_b128 v[156:159], v131
	ds_read_b128 v[160:163], v131 offset:1024
	ds_read_b128 v[164:167], v131 offset:2048
	ds_read_b128 v[168:171], v131 offset:3072
	s_mov_b32 m0, s45
	v_lshl_add_u64 v[186:187], v[210:211], 0, s[90:91]
	ds_read_b128 v[172:175], v138 offset:32768
	ds_read_b128 v[176:179], v138 offset:33792
	ds_read_b128 v[180:183], v138 offset:34816
	ds_read_b128 v[188:191], v138 offset:35840
	ds_read_b128 v[192:195], v138 offset:36864
	ds_read_b128 v[196:199], v138 offset:37888
	ds_read_b128 v[200:203], v138 offset:38912
	ds_read_b128 v[212:215], v138 offset:39936
	global_load_lds_dwordx4 v[186:187], off
	v_lshl_add_u64 v[186:187], v[210:211], 0, s[96:97]
	s_mov_b32 m0, s46
	s_nop 0
	global_load_lds_dwordx4 v[186:187], off
	s_waitcnt vmcnt(8)
	s_waitcnt lgkmcnt(0)
	s_barrier
	v_mfma_f32_16x16x32_bf16 v[116:119], v[140:143], v[172:175], v[116:119]
	v_mfma_f32_16x16x32_bf16 v[112:115], v[148:151], v[172:175], v[112:115]
	v_mfma_f32_16x16x32_bf16 v[100:103], v[140:143], v[180:183], v[100:103]
	v_mfma_f32_16x16x32_bf16 v[96:99], v[148:151], v[180:183], v[96:99]
	v_mfma_f32_16x16x32_bf16 v[68:71], v[140:143], v[192:195], v[68:71]
	v_mfma_f32_16x16x32_bf16 v[64:67], v[148:151], v[192:195], v[64:67]
	v_mfma_f32_16x16x32_bf16 v[36:39], v[140:143], v[200:203], v[36:39]
	v_mfma_f32_16x16x32_bf16 v[32:35], v[148:151], v[200:203], v[32:35]
	v_mfma_f32_16x16x32_bf16 v[116:119], v[144:147], v[176:179], v[116:119]
	v_mfma_f32_16x16x32_bf16 v[112:115], v[152:155], v[176:179], v[112:115]
	v_mfma_f32_16x16x32_bf16 v[100:103], v[144:147], v[188:191], v[100:103]
	v_mfma_f32_16x16x32_bf16 v[96:99], v[152:155], v[188:191], v[96:99]
	v_mfma_f32_16x16x32_bf16 v[68:71], v[144:147], v[196:199], v[68:71]
	v_mfma_f32_16x16x32_bf16 v[64:67], v[152:155], v[196:199], v[64:67]
	v_mfma_f32_16x16x32_bf16 v[36:39], v[144:147], v[212:215], v[36:39]
	v_mfma_f32_16x16x32_bf16 v[32:35], v[152:155], v[212:215], v[32:35]
	v_mfma_f32_16x16x32_bf16 v[124:127], v[156:159], v[172:175], v[124:127]
	v_mfma_f32_16x16x32_bf16 v[120:123], v[164:167], v[172:175], v[120:123]
	v_mfma_f32_16x16x32_bf16 v[108:111], v[156:159], v[180:183], v[108:111]
	v_mfma_f32_16x16x32_bf16 v[104:107], v[164:167], v[180:183], v[104:107]
	v_mfma_f32_16x16x32_bf16 v[84:87], v[156:159], v[192:195], v[84:87]
	v_mfma_f32_16x16x32_bf16 v[80:83], v[164:167], v[192:195], v[80:83]
	v_mfma_f32_16x16x32_bf16 v[52:55], v[156:159], v[200:203], v[52:55]
	v_mfma_f32_16x16x32_bf16 v[48:51], v[164:167], v[200:203], v[48:51]
	v_mfma_f32_16x16x32_bf16 v[124:127], v[160:163], v[176:179], v[124:127]
	v_mfma_f32_16x16x32_bf16 v[120:123], v[168:171], v[176:179], v[120:123]
	v_mfma_f32_16x16x32_bf16 v[108:111], v[160:163], v[188:191], v[108:111]
	v_mfma_f32_16x16x32_bf16 v[104:107], v[168:171], v[188:191], v[104:107]
	v_mfma_f32_16x16x32_bf16 v[84:87], v[160:163], v[196:199], v[84:87]
	v_mfma_f32_16x16x32_bf16 v[80:83], v[168:171], v[196:199], v[80:83]
	v_mfma_f32_16x16x32_bf16 v[52:55], v[160:163], v[212:215], v[52:55]
	v_mfma_f32_16x16x32_bf16 v[48:51], v[168:171], v[212:215], v[48:51]
	s_barrier
	s_mov_b32 m0, s73
	v_lshl_add_u64 v[186:187], v[206:207], 0, s[84:85]
	ds_read_b128 v[172:175], v138 offset:49152
	ds_read_b128 v[176:179], v138 offset:50176
	ds_read_b128 v[180:183], v138 offset:51200
	ds_read_b128 v[188:191], v138 offset:52224
	ds_read_b128 v[192:195], v138 offset:53248
	ds_read_b128 v[196:199], v138 offset:54272
	ds_read_b128 v[200:203], v138 offset:55296
	ds_read_b128 v[212:215], v138 offset:56320
	global_load_lds_dwordx4 v[186:187], off
	v_lshl_add_u64 v[186:187], v[206:207], 0, s[94:95]
	s_mov_b32 m0, s74
	s_nop 0
	global_load_lds_dwordx4 v[186:187], off
	v_lshl_add_u64 v[186:187], v[206:207], 0, s[80:81]
	s_mov_b32 m0, s75
	s_nop 0
	global_load_lds_dwordx4 v[186:187], off
	v_lshl_add_u64 v[186:187], v[206:207], 0, s[78:79]
	s_mov_b32 m0, s76
	s_nop 0
	global_load_lds_dwordx4 v[186:187], off
	v_lshl_add_u64 v[186:187], v[210:211], 0, s[84:85]
	s_mov_b32 m0, s48
	s_nop 0
	global_load_lds_dwordx4 v[186:187], off
	v_lshl_add_u64 v[186:187], v[210:211], 0, s[94:95]
	s_mov_b32 m0, s51
	s_nop 0
	global_load_lds_dwordx4 v[186:187], off
	s_waitcnt vmcnt(8)
	s_waitcnt lgkmcnt(0)
	s_barrier
	v_mfma_f32_16x16x32_bf16 v[76:79], v[140:143], v[172:175], v[76:79]
	v_mfma_f32_16x16x32_bf16 v[72:75], v[148:151], v[172:175], v[72:75]
	v_mfma_f32_16x16x32_bf16 v[44:47], v[140:143], v[180:183], v[44:47]
	v_mfma_f32_16x16x32_bf16 v[40:43], v[148:151], v[180:183], v[40:43]
	v_mfma_f32_16x16x32_bf16 v[20:23], v[140:143], v[192:195], v[20:23]
	v_mfma_f32_16x16x32_bf16 v[16:19], v[148:151], v[192:195], v[16:19]
	v_mfma_f32_16x16x32_bf16 v[4:7], v[140:143], v[200:203], v[4:7]
	v_mfma_f32_16x16x32_bf16 v[0:3], v[148:151], v[200:203], v[0:3]
	v_mfma_f32_16x16x32_bf16 v[76:79], v[144:147], v[176:179], v[76:79]
	v_mfma_f32_16x16x32_bf16 v[72:75], v[152:155], v[176:179], v[72:75]
	v_mfma_f32_16x16x32_bf16 v[44:47], v[144:147], v[188:191], v[44:47]
	v_mfma_f32_16x16x32_bf16 v[40:43], v[152:155], v[188:191], v[40:43]
	v_mfma_f32_16x16x32_bf16 v[20:23], v[144:147], v[196:199], v[20:23]
	v_mfma_f32_16x16x32_bf16 v[16:19], v[152:155], v[196:199], v[16:19]
	v_mfma_f32_16x16x32_bf16 v[4:7], v[144:147], v[212:215], v[4:7]
	v_mfma_f32_16x16x32_bf16 v[0:3], v[152:155], v[212:215], v[0:3]
	v_mfma_f32_16x16x32_bf16 v[92:95], v[156:159], v[172:175], v[92:95]
	v_mfma_f32_16x16x32_bf16 v[88:91], v[164:167], v[172:175], v[88:91]
	v_mfma_f32_16x16x32_bf16 v[60:63], v[156:159], v[180:183], v[60:63]
	v_mfma_f32_16x16x32_bf16 v[56:59], v[164:167], v[180:183], v[56:59]
	v_mfma_f32_16x16x32_bf16 v[28:31], v[156:159], v[192:195], v[28:31]
	v_mfma_f32_16x16x32_bf16 v[24:27], v[164:167], v[192:195], v[24:27]
	v_mfma_f32_16x16x32_bf16 v[12:15], v[156:159], v[200:203], v[12:15]
	v_mfma_f32_16x16x32_bf16 v[8:11], v[164:167], v[200:203], v[8:11]
	v_mfma_f32_16x16x32_bf16 v[92:95], v[160:163], v[176:179], v[92:95]
	v_mfma_f32_16x16x32_bf16 v[88:91], v[168:171], v[176:179], v[88:91]
	v_mfma_f32_16x16x32_bf16 v[60:63], v[160:163], v[188:191], v[60:63]
	v_mfma_f32_16x16x32_bf16 v[56:59], v[168:171], v[188:191], v[56:59]
	v_mfma_f32_16x16x32_bf16 v[28:31], v[160:163], v[196:199], v[28:31]
	v_mfma_f32_16x16x32_bf16 v[24:27], v[168:171], v[196:199], v[24:27]
	v_mfma_f32_16x16x32_bf16 v[12:15], v[160:163], v[212:215], v[12:15]
	v_mfma_f32_16x16x32_bf16 v[8:11], v[168:171], v[212:215], v[8:11]
	s_barrier
	s_add_i32 s82, s82, 2
	s_add_u32 s22, s22, 0x100
	s_addc_u32 s23, s23, 0
	s_cmp_gt_u32 s82, 29
	s_cbranch_scc0 .LBB0_1079
	s_and_b64 vcc, exec, s[10:11]
	s_cbranch_vccz .LBB0_1082
	s_barrier

; __device__ __forceinline__ int lane_id() { int l; asm volatile("v_mbcnt_lo_u32_b32 %0, -1, 0\n\tv_mbcnt_hi_u32_b32 %0, -1, %0" : "=v"(l)); return l; }
;     __device__ __forceinline__ bool next(int i, UnitG& u) const { if (!P.next(i, u)) return false; u.O = O + ((size_t)u.x0 * 256 * 2048 + (size_t)u.x1 * 256) * 2; u.ldo = 2048; u.kind = 0; return true; }
; template <class Epi, class Sched>
; __device__ __forceinline__ void gemm_phase(PG8_LAS unsigned char* lds, const Sched& S, const Epi& E, int tid_in) {
;     ...
;     for (;;) {
;         int aoff, boff; { const int l3 = lane_id(), fr3 = l3 & 15, fq3 = l3 >> 4; aoff = lds_byte(wr * 64 + fr3, fq3 * 8); boff = lds_byte(wc * 32 + fr3, fq3 * 8); }
;         const bool has_next = S.next(ui + 1, nxt);
;         const char* nA = has_next ? nxt.A : cA; const char* nB = has_next ? nxt.B : cB;
;         const int nlda = has_next ? nxt.lda : cur.lda, nldb = has_next ? nxt.ldb : cur.ldb;
;         unsigned nvA, nvB; { int r2, c2; stage_rc((wid * 64 + lane_id()) * 16, r2, c2); const int rb2 = Epi::PERM ? ((r2 & ~31) + perm32(r2 & 31)) : r2;
;             nvA = (unsigned)(r2 * nlda + c2) * 2u; nvB = (unsigned)(rb2 * nldb + c2) * 2u; }
;         const unsigned nqA = (unsigned)nlda * 128u, nqB = (unsigned)nldb * 128u;
;         const int nt = cur.K / BK;
.LBB0_1273:
	v_and_b32_e32 v1, 15, v0
	v_or_b32_e32 v2, s77, v1
	v_lshlrev_b32_e32 v3, 6, v2
	v_and_b32_e32 v4, 48, v0
	s_movk_i32 s5, 0x3c0
	v_lshlrev_b32_e32 v5, 4, v0
	v_and_or_b32 v3, v3, s5, v4
	v_and_b32_e32 v5, 0xfffffc00, v5
	v_readlane_b32 s5, v255, 5
	v_lshlrev_b32_e32 v2, 2, v2
	v_and_b32_e32 v2, 32, v2
	v_add_u32_e32 v6, s5, v5
	v_readlane_b32 s5, v255, 7
	v_lshlrev_b32_e32 v0, 2, v0
	s_nop 0
	v_bitop3_b32 v32, v3, v6, v2 bitop3:0xde
	v_lshl_or_b32 v1, v1, 6, v4
	v_add_u32_e32 v2, s5, v5
	v_and_b32_e32 v0, 32, v0
	v_bitop3_b32 v137, v1, v2, v0 bitop3:0xde
	v_mbcnt_lo_u32_b32 v0, -1, 0
	v_mbcnt_hi_u32_b32 v0, -1, v0
	v_readlane_b32 s5, v255, 9
	s_add_i32 s93, 0, 0x10000
	s_add_i32 s8, 0, 0x14000
	v_add_u32_e32 v0, s5, v0
	v_ashrrev_i32_e32 v2, 31, v0
	v_lshrrev_b32_e32 v2, 26, v2
	v_lshlrev_b32_e32 v1, 4, v0
	v_add_u32_e32 v2, v0, v2
	v_bfe_i32 v0, v0, 27, 1
	v_lshrrev_b32_e32 v0, 22, v0
	v_add_u32_e32 v0, v1, v0
	v_and_b32_e32 v0, 0xfffffc00, v0
	v_sub_u32_e32 v0, v1, v0
	v_lshrrev_b32_e32 v1, 4, v0
	v_bitop3_b32 v0, v1, v0, 32 bitop3:0x6c
	v_ashrrev_i32_e32 v3, 31, v0
	v_lshrrev_b32_e32 v3, 26, v3
	v_ashrrev_i32_e32 v2, 6, v2
	v_add_u32_e32 v3, v0, v3
	v_lshlrev_b32_e32 v1, 3, v2
	v_ashrrev_i32_e32 v4, 6, v3
	v_and_b32_e32 v3, 0xc0, v3
	v_and_b32_e32 v1, -16, v1
	v_lshlrev_b32_e32 v2, 5, v2
	v_sub_u32_e32 v0, v0, v3
	v_add_u32_e32 v1, v4, v1
	v_and_b32_e32 v2, 32, v2
	v_ashrrev_i16_sdwa v0, v205, sext(v0) dst_sel:DWORD dst_unused:UNUSED_PAD src0_sel:DWORD src1_sel:BYTE_0
	v_add_u32_sdwa v33, v2, sext(v0) dst_sel:DWORD dst_unused:UNUSED_PAD src0_sel:DWORD src1_sel:WORD_0
	v_lshlrev_b32_e32 v0, 1, v1
	v_lshrrev_b32_e32 v2, 2, v1
	v_and_b32_e32 v3, 3, v4
	s_mov_b32 s5, 0x7fffffe0
	v_and_b32_e32 v0, 24, v0
	v_and_b32_e32 v2, 4, v2
	v_and_or_b32 v3, v1, s5, v3
	v_or3_b32 v0, v3, v2, v0
	v_mul_lo_u32 v1, v1, s54
	v_add_u32_e32 v142, s93, v137
	v_add_u32_e32 v143, s8, v137
	v_add_lshl_u32 v136, v33, v1, 1
	v_mul_lo_u32 v34, v0, s54
	ds_read_b128 v[0:3], v142
	ds_read_b128 v[4:7], v142 offset:1024
	ds_read_b128 v[8:11], v142 offset:2048
	ds_read_b128 v[12:15], v142 offset:3072
	ds_read_b128 v[16:19], v143
	ds_read_b128 v[20:23], v143 offset:1024
	ds_read_b128 v[24:27], v143 offset:2048
	ds_read_b128 v[28:31], v143 offset:3072
	s_mov_b32 s86, 4
	s_lshl_b32 s34, s54, 7
	s_lshr_b32 s87, s71, 6
	s_lshl_b32 s82, s6, 1
	s_lshl_b32 s44, s54, 7
	v_add_lshl_u32 v138, v34, v33, 1
	s_add_u32 s10, s46, s82
	s_addc_u32 s11, s47, 0
	v_lshl_add_u64 v[124:125], s[10:11], 0, v[184:185]
	s_add_i32 s72, s14, 0xc000
	s_mov_b32 s7, s83
	v_add_u32_e32 v144, 0, v32
	v_lshl_add_u64 v[64:65], v[124:125], 0, s[84:85]
	s_mov_b32 m0, s72
	v_lshl_add_u64 v[126:127], v[124:125], 0, s[6:7]
	s_add_i32 s92, s14, 0xe000
	ds_read_b128 v[32:35], v144
	ds_read_b128 v[36:39], v144 offset:1024
	ds_read_b128 v[40:43], v144 offset:2048
	ds_read_b128 v[44:47], v144 offset:3072
	ds_read_b128 v[48:51], v144 offset:4096
	ds_read_b128 v[52:55], v144 offset:5120
	ds_read_b128 v[56:59], v144 offset:6144
	ds_read_b128 v[60:63], v144 offset:7168
	global_load_lds_dwordx4 v[64:65], off
	v_lshl_add_u64 v[64:65], v[126:127], 0, s[84:85]
	s_mov_b32 m0, s92
	s_nop 0
	global_load_lds_dwordx4 v[64:65], off
	s_waitcnt vmcnt(24)
	s_waitcnt lgkmcnt(0)
	s_barrier
	v_mfma_f32_16x16x32_bf16 v[64:67], v[0:3], v[32:35], 0
	v_mfma_f32_16x16x32_bf16 v[68:71], v[8:11], v[32:35], 0
	v_mfma_f32_16x16x32_bf16 v[72:75], v[0:3], v[40:43], 0
	v_mfma_f32_16x16x32_bf16 v[76:79], v[8:11], v[40:43], 0
	v_mfma_f32_16x16x32_bf16 v[80:83], v[0:3], v[48:51], 0
	v_mfma_f32_16x16x32_bf16 v[84:87], v[8:11], v[48:51], 0
	v_mfma_f32_16x16x32_bf16 v[88:91], v[0:3], v[56:59], 0
	v_mfma_f32_16x16x32_bf16 v[92:95], v[8:11], v[56:59], 0
	v_mfma_f32_16x16x32_bf16 v[64:67], v[4:7], v[36:39], v[64:67]
	v_mfma_f32_16x16x32_bf16 v[68:71], v[12:15], v[36:39], v[68:71]
	v_mfma_f32_16x16x32_bf16 v[72:75], v[4:7], v[44:47], v[72:75]
	v_mfma_f32_16x16x32_bf16 v[76:79], v[12:15], v[44:47], v[76:79]
	v_mfma_f32_16x16x32_bf16 v[80:83], v[4:7], v[52:55], v[80:83]
	v_mfma_f32_16x16x32_bf16 v[84:87], v[12:15], v[52:55], v[84:87]
	v_mfma_f32_16x16x32_bf16 v[88:91], v[4:7], v[60:63], v[88:91]
	v_mfma_f32_16x16x32_bf16 v[92:95], v[12:15], v[60:63], v[92:95]
	v_mfma_f32_16x16x32_bf16 v[96:99], v[16:19], v[32:35], 0
	v_mfma_f32_16x16x32_bf16 v[32:35], v[24:27], v[32:35], 0
	v_mfma_f32_16x16x32_bf16 v[130:133], v[20:23], v[36:39], v[96:99]
	v_mfma_f32_16x16x32_bf16 v[32:35], v[28:31], v[36:39], v[32:35]
	v_mfma_f32_16x16x32_bf16 v[36:39], v[16:19], v[40:43], 0
	v_mfma_f32_16x16x32_bf16 v[40:43], v[24:27], v[40:43], 0
	v_mfma_f32_16x16x32_bf16 v[36:39], v[20:23], v[44:47], v[36:39]
	v_mfma_f32_16x16x32_bf16 v[40:43], v[28:31], v[44:47], v[40:43]
	v_mfma_f32_16x16x32_bf16 v[44:47], v[16:19], v[48:51], 0
	v_mfma_f32_16x16x32_bf16 v[48:51], v[24:27], v[48:51], 0
	v_mfma_f32_16x16x32_bf16 v[44:47], v[20:23], v[52:55], v[44:47]
	v_mfma_f32_16x16x32_bf16 v[52:55], v[28:31], v[52:55], v[48:51]
	v_mfma_f32_16x16x32_bf16 v[48:51], v[16:19], v[56:59], 0
	v_mfma_f32_16x16x32_bf16 v[148:151], v[20:23], v[60:63], v[48:51]
	v_mfma_f32_16x16x32_bf16 v[48:51], v[24:27], v[56:59], 0
	v_mfma_f32_16x16x32_bf16 v[56:59], v[28:31], v[60:63], v[48:51]
	s_barrier
	s_add_i32 s93, s93, s15
	v_mov_b32_e32 v129, v185
	s_add_i32 s10, s93, 0x2000
	s_lshl_b32 s50, s4, 1
	v_lshl_add_u64 v[134:135], s[48:49], 0, v[128:129]
	s_mov_b64 s[52:53], 0x100
	s_mov_b32 s5, s83
	s_add_u32 s16, s48, s50
	v_lshl_add_u64 v[120:121], v[134:135], 0, s[52:53]
	s_mov_b32 m0, s93
	v_lshl_add_u64 v[140:141], v[134:135], 0, s[4:5]
	s_addc_u32 s17, s49, 0
	ds_read_b128 v[48:51], v144 offset:16384
	ds_read_b128 v[60:63], v144 offset:17408
	ds_read_b128 v[96:99], v144 offset:18432
	ds_read_b128 v[100:103], v144 offset:19456
	ds_read_b128 v[104:107], v144 offset:20480
	ds_read_b128 v[108:111], v144 offset:21504
	ds_read_b128 v[112:115], v144 offset:22528
	ds_read_b128 v[116:119], v144 offset:23552
	global_load_lds_dwordx4 v[120:121], off
	v_lshl_add_u64 v[120:121], v[140:141], 0, s[52:53]
	s_mov_b32 m0, s10
	v_lshl_add_u64 v[186:187], s[16:17], 0, v[128:129]
	s_add_i32 s11, s8, s15
	global_load_lds_dwordx4 v[120:121], off
	v_lshl_add_u64 v[120:121], v[186:187], 0, s[52:53]
	s_mov_b32 m0, s11
	v_lshl_add_u64 v[206:207], v[186:187], 0, s[4:5]
	s_add_i32 s8, s11, 0x2000
	global_load_lds_dwordx4 v[120:121], off
	v_lshl_add_u64 v[120:121], v[206:207], 0, s[52:53]
	s_mov_b32 m0, s8
	v_lshl_add_u64 v[210:211], s[46:47], 0, v[184:185]
	global_load_lds_dwordx4 v[120:121], off
	v_lshl_add_u64 v[120:121], v[210:211], 0, s[52:53]
	s_mov_b32 m0, s14
	v_lshl_add_u64 v[252:253], v[210:211], 0, s[6:7]
	global_load_lds_dwordx4 v[120:121], off
	v_lshl_add_u64 v[120:121], v[252:253], 0, s[52:53]
	s_mov_b32 m0, s73
	s_mov_b32 s51, s83
	global_load_lds_dwordx4 v[120:121], off
	s_waitcnt vmcnt(24)
	s_waitcnt lgkmcnt(0)
	s_barrier
	v_mfma_f32_16x16x32_bf16 v[120:123], v[0:3], v[48:51], 0
	v_mfma_f32_16x16x32_bf16 v[152:155], v[4:7], v[60:63], v[120:123]
	v_mfma_f32_16x16x32_bf16 v[120:123], v[8:11], v[48:51], 0
	v_mfma_f32_16x16x32_bf16 v[156:159], v[12:15], v[60:63], v[120:123]
	v_mfma_f32_16x16x32_bf16 v[120:123], v[0:3], v[96:99], 0
	v_mfma_f32_16x16x32_bf16 v[160:163], v[4:7], v[100:103], v[120:123]
	v_mfma_f32_16x16x32_bf16 v[120:123], v[8:11], v[96:99], 0
	v_mfma_f32_16x16x32_bf16 v[164:167], v[12:15], v[100:103], v[120:123]
	v_mfma_f32_16x16x32_bf16 v[120:123], v[0:3], v[104:107], 0
	v_mfma_f32_16x16x32_bf16 v[0:3], v[0:3], v[112:115], 0
	v_mfma_f32_16x16x32_bf16 v[168:171], v[4:7], v[108:111], v[120:123]
	v_mfma_f32_16x16x32_bf16 v[0:3], v[4:7], v[116:119], v[0:3]
	v_mfma_f32_16x16x32_bf16 v[4:7], v[8:11], v[112:115], 0
	v_mfma_f32_16x16x32_bf16 v[120:123], v[8:11], v[104:107], 0
	v_mfma_f32_16x16x32_bf16 v[4:7], v[12:15], v[116:119], v[4:7]
	v_mfma_f32_16x16x32_bf16 v[172:175], v[12:15], v[108:111], v[120:123]
	v_mfma_f32_16x16x32_bf16 v[8:11], v[16:19], v[48:51], 0
	v_mfma_f32_16x16x32_bf16 v[12:15], v[24:27], v[48:51], 0
	v_mfma_f32_16x16x32_bf16 v[48:51], v[16:19], v[96:99], 0
	v_mfma_f32_16x16x32_bf16 v[176:179], v[20:23], v[100:103], v[48:51]
	v_mfma_f32_16x16x32_bf16 v[48:51], v[24:27], v[96:99], 0
	v_mfma_f32_16x16x32_bf16 v[180:183], v[28:31], v[100:103], v[48:51]
	v_mfma_f32_16x16x32_bf16 v[48:51], v[16:19], v[104:107], 0
	v_mfma_f32_16x16x32_bf16 v[16:19], v[16:19], v[112:115], 0
	v_mfma_f32_16x16x32_bf16 v[8:11], v[20:23], v[60:63], v[8:11]
	v_mfma_f32_16x16x32_bf16 v[12:15], v[28:31], v[60:63], v[12:15]
	v_mfma_f32_16x16x32_bf16 v[188:191], v[20:23], v[108:111], v[48:51]
	v_mfma_f32_16x16x32_bf16 v[48:51], v[24:27], v[104:107], 0
	v_mfma_f32_16x16x32_bf16 v[196:199], v[20:23], v[116:119], v[16:19]
	v_mfma_f32_16x16x32_bf16 v[16:19], v[24:27], v[112:115], 0
	v_mfma_f32_16x16x32_bf16 v[192:195], v[28:31], v[108:111], v[48:51]
	v_mfma_f32_16x16x32_bf16 v[200:203], v[28:31], v[116:119], v[16:19]
	s_barrier
	s_add_i32 s16, 0, 0x18000
	s_add_i32 s24, 0, 0x1c000
	v_add_u32_e32 v145, s16, v137
	v_add_u32_e32 v146, s24, v137
	ds_read_b128 v[16:19], v145
	ds_read_b128 v[20:23], v145 offset:1024
	ds_read_b128 v[24:27], v145 offset:2048
	ds_read_b128 v[28:31], v145 offset:3072
	ds_read_b128 v[212:215], v146
	ds_read_b128 v[216:219], v146 offset:1024
	ds_read_b128 v[220:223], v146 offset:2048
	ds_read_b128 v[224:227], v146 offset:3072
	s_mov_b32 m0, s74
	v_lshl_add_u64 v[96:97], v[124:125], 0, s[52:53]
	ds_read_b128 v[48:51], v144 offset:32768
	ds_read_b128 v[60:63], v144 offset:33792
	ds_read_b128 v[228:231], v144 offset:34816
	ds_read_b128 v[232:235], v144 offset:35840
	ds_read_b128 v[236:239], v144 offset:36864
	ds_read_b128 v[240:243], v144 offset:37888
	ds_read_b128 v[244:247], v144 offset:38912
	ds_read_b128 v[248:251], v144 offset:39936
	global_load_lds_dwordx4 v[96:97], off
	v_lshl_add_u64 v[96:97], v[126:127], 0, s[52:53]
	s_mov_b32 m0, s75
	s_nop 0
	global_load_lds_dwordx4 v[96:97], off
	s_waitcnt vmcnt(8)
	s_waitcnt lgkmcnt(0)
	s_barrier
; #define PG8_WAIT_V(n) asm volatile("s_waitcnt vmcnt(" #n ")" ::: "memory")
; #define PG8_WAIT_VP() asm volatile("s_waitcnt vmcnt(%0)" :: "n"(8 + Epi::NST) : "memory")
; template <class Epi, class Sched>
; __device__ __forceinline__ void gemm_phase(PG8_LAS unsigned char* lds, const Sched& S, const Epi& E, int tid_in) {
;     ...
;         { const int t = 0; PG8_KITER(PG8_WAIT_VP()); }
;         for (int t = 2; t < nt; t += 2) PG8_KITER(PG8_WAIT_V(8));
	v_mfma_f32_16x16x32_bf16 v[64:67], v[16:19], v[48:51], v[64:67]
	v_mfma_f32_16x16x32_bf16 v[120:123], v[20:23], v[60:63], v[64:67]
	v_mfma_f32_16x16x32_bf16 v[64:67], v[24:27], v[48:51], v[68:71]
	v_mfma_f32_16x16x32_bf16 v[124:127], v[28:31], v[60:63], v[64:67]
	v_mfma_f32_16x16x32_bf16 v[64:67], v[16:19], v[228:231], v[72:75]
	v_mfma_f32_16x16x32_bf16 v[112:115], v[20:23], v[232:235], v[64:67]
	v_mfma_f32_16x16x32_bf16 v[64:67], v[24:27], v[228:231], v[76:79]
	v_mfma_f32_16x16x32_bf16 v[116:119], v[28:31], v[232:235], v[64:67]
	v_mfma_f32_16x16x32_bf16 v[64:67], v[16:19], v[236:239], v[80:83]
	v_mfma_f32_16x16x32_bf16 v[104:107], v[20:23], v[240:243], v[64:67]
	v_mfma_f32_16x16x32_bf16 v[64:67], v[24:27], v[236:239], v[84:87]
	v_mfma_f32_16x16x32_bf16 v[108:111], v[28:31], v[240:243], v[64:67]
	v_mfma_f32_16x16x32_bf16 v[64:67], v[16:19], v[244:247], v[88:91]
	v_mfma_f32_16x16x32_bf16 v[96:99], v[20:23], v[248:251], v[64:67]
	v_mfma_f32_16x16x32_bf16 v[64:67], v[24:27], v[244:247], v[92:95]
	v_mfma_f32_16x16x32_bf16 v[100:103], v[28:31], v[248:251], v[64:67]
	v_mfma_f32_16x16x32_bf16 v[32:35], v[220:223], v[48:51], v[32:35]
	v_mfma_f32_16x16x32_bf16 v[64:67], v[212:215], v[48:51], v[130:133]
	v_mfma_f32_16x16x32_bf16 v[84:87], v[224:227], v[60:63], v[32:35]
	v_mfma_f32_16x16x32_bf16 v[32:35], v[212:215], v[228:231], v[36:39]
	v_mfma_f32_16x16x32_bf16 v[80:83], v[216:219], v[60:63], v[64:67]
	v_mfma_f32_16x16x32_bf16 v[64:67], v[216:219], v[232:235], v[32:35]
	v_mfma_f32_16x16x32_bf16 v[32:35], v[220:223], v[228:231], v[40:43]
	v_mfma_f32_16x16x32_bf16 v[68:71], v[224:227], v[232:235], v[32:35]
	v_mfma_f32_16x16x32_bf16 v[32:35], v[212:215], v[236:239], v[44:47]
	v_mfma_f32_16x16x32_bf16 v[48:51], v[216:219], v[240:243], v[32:35]
	v_mfma_f32_16x16x32_bf16 v[32:35], v[220:223], v[236:239], v[52:55]
	v_mfma_f32_16x16x32_bf16 v[52:55], v[224:227], v[240:243], v[32:35]
	v_mfma_f32_16x16x32_bf16 v[32:35], v[212:215], v[244:247], v[148:151]
	v_mfma_f32_16x16x32_bf16 v[36:39], v[220:223], v[244:247], v[56:59]
	v_mfma_f32_16x16x32_bf16 v[32:35], v[216:219], v[248:251], v[32:35]
	v_mfma_f32_16x16x32_bf16 v[36:39], v[224:227], v[248:251], v[36:39]
	s_barrier
	s_mov_b64 s[52:53], 0x180
	s_add_i32 s16, s16, s15
	v_lshl_add_u64 v[40:41], v[134:135], 0, s[52:53]
	s_mov_b32 m0, s16
	s_add_i32 s17, s16, 0x2000
	ds_read_b128 v[130:133], v144 offset:49152
	ds_read_b128 v[148:151], v144 offset:50176
	ds_read_b128 v[228:231], v144 offset:51200
	ds_read_b128 v[232:235], v144 offset:52224
	ds_read_b128 v[236:239], v144 offset:53248
	ds_read_b128 v[240:243], v144 offset:54272
	ds_read_b128 v[244:247], v144 offset:55296
	ds_read_b128 v[248:251], v144 offset:56320
	global_load_lds_dwordx4 v[40:41], off
	v_lshl_add_u64 v[40:41], v[140:141], 0, s[52:53]
	s_mov_b32 m0, s17
	s_add_i32 s24, s24, s15
	global_load_lds_dwordx4 v[40:41], off
	v_lshl_add_u64 v[40:41], v[186:187], 0, s[52:53]
	s_mov_b32 m0, s24
	s_add_i32 s25, s24, 0x2000
	global_load_lds_dwordx4 v[40:41], off
	v_lshl_add_u64 v[40:41], v[206:207], 0, s[52:53]
	s_mov_b32 m0, s25
	s_nop 0
	global_load_lds_dwordx4 v[40:41], off
	v_lshl_add_u64 v[40:41], v[210:211], 0, s[52:53]
	s_mov_b32 m0, s13
	s_nop 0
	global_load_lds_dwordx4 v[40:41], off
	v_lshl_add_u64 v[40:41], v[252:253], 0, s[52:53]
	s_mov_b32 m0, s76
	v_mov_b32_e32 v252, 0x3a27c5ac
	global_load_lds_dwordx4 v[40:41], off
	s_waitcnt vmcnt(8)
	s_waitcnt lgkmcnt(0)
	s_barrier
	v_mfma_f32_16x16x32_bf16 v[40:43], v[16:19], v[130:133], v[152:155]
	v_mfma_f32_16x16x32_bf16 v[88:91], v[20:23], v[148:151], v[40:43]
	v_mfma_f32_16x16x32_bf16 v[40:43], v[24:27], v[130:133], v[156:159]
	v_mfma_f32_16x16x32_bf16 v[92:95], v[28:31], v[148:151], v[40:43]
	v_mfma_f32_16x16x32_bf16 v[40:43], v[16:19], v[228:231], v[160:163]
	v_mfma_f32_16x16x32_bf16 v[72:75], v[20:23], v[232:235], v[40:43]
	v_mfma_f32_16x16x32_bf16 v[40:43], v[24:27], v[228:231], v[164:167]
	v_mfma_f32_16x16x32_bf16 v[76:79], v[28:31], v[232:235], v[40:43]
	v_mfma_f32_16x16x32_bf16 v[40:43], v[16:19], v[236:239], v[168:171]
	v_mfma_f32_16x16x32_bf16 v[56:59], v[20:23], v[240:243], v[40:43]
	v_mfma_f32_16x16x32_bf16 v[40:43], v[24:27], v[236:239], v[172:175]
	v_mfma_f32_16x16x32_bf16 v[0:3], v[16:19], v[244:247], v[0:3]
	v_mfma_f32_16x16x32_bf16 v[60:63], v[28:31], v[240:243], v[40:43]
	v_mfma_f32_16x16x32_bf16 v[40:43], v[20:23], v[248:251], v[0:3]
	v_mfma_f32_16x16x32_bf16 v[0:3], v[24:27], v[244:247], v[4:7]
	v_mfma_f32_16x16x32_bf16 v[44:47], v[28:31], v[248:251], v[0:3]
	v_mfma_f32_16x16x32_bf16 v[0:3], v[212:215], v[130:133], v[8:11]
	v_mfma_f32_16x16x32_bf16 v[24:27], v[216:219], v[148:151], v[0:3]
	v_mfma_f32_16x16x32_bf16 v[0:3], v[220:223], v[130:133], v[12:15]
	v_mfma_f32_16x16x32_bf16 v[28:31], v[224:227], v[148:151], v[0:3]
	v_mfma_f32_16x16x32_bf16 v[0:3], v[212:215], v[228:231], v[176:179]
	v_mfma_f32_16x16x32_bf16 v[16:19], v[216:219], v[232:235], v[0:3]
	v_mfma_f32_16x16x32_bf16 v[0:3], v[220:223], v[228:231], v[180:183]
	v_mfma_f32_16x16x32_bf16 v[20:23], v[224:227], v[232:235], v[0:3]
	v_mfma_f32_16x16x32_bf16 v[0:3], v[212:215], v[236:239], v[188:191]
	v_mfma_f32_16x16x32_bf16 v[8:11], v[216:219], v[240:243], v[0:3]
	v_mfma_f32_16x16x32_bf16 v[0:3], v[220:223], v[236:239], v[192:195]
	v_mfma_f32_16x16x32_bf16 v[12:15], v[224:227], v[240:243], v[0:3]
	v_mfma_f32_16x16x32_bf16 v[0:3], v[212:215], v[244:247], v[196:199]
	v_mfma_f32_16x16x32_bf16 v[4:7], v[220:223], v[244:247], v[200:203]
	v_mfma_f32_16x16x32_bf16 v[0:3], v[216:219], v[248:251], v[0:3]
	v_mfma_f32_16x16x32_bf16 v[4:7], v[224:227], v[248:251], v[4:7]
	s_barrier
	s_lshl_b32 s52, s54, 8
	s_lshl_b32 s54, s54, 8
	s_add_u32 s46, s46, 0x180
	s_addc_u32 s47, s47, 0
	s_add_u32 s48, s48, 0x200
	v_mov_b32_e32 v137, v185
	s_mov_b32 s35, s83
	s_mov_b32 s53, s83
	v_mov_b32_e32 v139, v185
	s_mov_b32 s45, s83
	s_mov_b32 s55, s83
	s_addc_u32 s49, s49, 0
	v_lshl_add_u64 v[130:131], s[82:83], 0, v[184:185]
	v_mad_u64_u32 v[132:133], s[56:57], s6, 3, v[184:185]

.LBB0_1276:
	ds_read_b128 v[148:151], v142
	ds_read_b128 v[152:155], v142 offset:1024
	ds_read_b128 v[156:159], v142 offset:2048
	ds_read_b128 v[160:163], v142 offset:3072
	ds_read_b128 v[164:167], v143
	ds_read_b128 v[168:171], v143 offset:1024
	ds_read_b128 v[172:175], v143 offset:2048
	ds_read_b128 v[176:179], v143 offset:3072
	s_add_u32 s68, s46, 0x80
	s_addc_u32 vcc_lo, s47, 0
	s_and_b64 s[60:61], exec, s[60:61]
	s_cselect_b32 s61, s27, vcc_lo
	s_cselect_b32 s60, s26, s68
	s_mov_b32 m0, s72
	v_lshl_add_u64 v[186:187], s[46:47], 0, v[130:131]
	ds_read_b128 v[180:183], v144
	ds_read_b128 v[188:191], v144 offset:1024
	ds_read_b128 v[192:195], v144 offset:2048
	ds_read_b128 v[196:199], v144 offset:3072
	ds_read_b128 v[200:203], v144 offset:4096
	ds_read_b128 v[212:215], v144 offset:5120
	ds_read_b128 v[216:219], v144 offset:6144
	ds_read_b128 v[220:223], v144 offset:7168
	global_load_lds_dwordx4 v[186:187], off
	v_lshl_add_u64 v[186:187], s[46:47], 0, v[132:133]
	s_mov_b32 m0, s92
	s_nop 0
	global_load_lds_dwordx4 v[186:187], off
	s_waitcnt vmcnt(8)
	s_waitcnt lgkmcnt(0)
	s_barrier
	v_mfma_f32_16x16x32_bf16 v[120:123], v[148:151], v[180:183], v[120:123]
	v_mfma_f32_16x16x32_bf16 v[124:127], v[156:159], v[180:183], v[124:127]
	v_mfma_f32_16x16x32_bf16 v[112:115], v[148:151], v[192:195], v[112:115]
	v_mfma_f32_16x16x32_bf16 v[116:119], v[156:159], v[192:195], v[116:119]
	v_mfma_f32_16x16x32_bf16 v[104:107], v[148:151], v[200:203], v[104:107]
	v_mfma_f32_16x16x32_bf16 v[108:111], v[156:159], v[200:203], v[108:111]
	v_mfma_f32_16x16x32_bf16 v[96:99], v[148:151], v[216:219], v[96:99]
	v_mfma_f32_16x16x32_bf16 v[100:103], v[156:159], v[216:219], v[100:103]
	v_mfma_f32_16x16x32_bf16 v[120:123], v[152:155], v[188:191], v[120:123]
	v_mfma_f32_16x16x32_bf16 v[124:127], v[160:163], v[188:191], v[124:127]
	v_mfma_f32_16x16x32_bf16 v[112:115], v[152:155], v[196:199], v[112:115]
	v_mfma_f32_16x16x32_bf16 v[116:119], v[160:163], v[196:199], v[116:119]
	v_mfma_f32_16x16x32_bf16 v[104:107], v[152:155], v[212:215], v[104:107]
	v_mfma_f32_16x16x32_bf16 v[108:111], v[160:163], v[212:215], v[108:111]
	v_mfma_f32_16x16x32_bf16 v[96:99], v[152:155], v[220:223], v[96:99]
	v_mfma_f32_16x16x32_bf16 v[100:103], v[160:163], v[220:223], v[100:103]
	v_mfma_f32_16x16x32_bf16 v[80:83], v[164:167], v[180:183], v[80:83]
	v_mfma_f32_16x16x32_bf16 v[84:87], v[172:175], v[180:183], v[84:87]
	v_mfma_f32_16x16x32_bf16 v[64:67], v[164:167], v[192:195], v[64:67]
	v_mfma_f32_16x16x32_bf16 v[68:71], v[172:175], v[192:195], v[68:71]
	v_mfma_f32_16x16x32_bf16 v[48:51], v[164:167], v[200:203], v[48:51]
	v_mfma_f32_16x16x32_bf16 v[52:55], v[172:175], v[200:203], v[52:55]
	v_mfma_f32_16x16x32_bf16 v[32:35], v[164:167], v[216:219], v[32:35]
	v_mfma_f32_16x16x32_bf16 v[36:39], v[172:175], v[216:219], v[36:39]
	v_mfma_f32_16x16x32_bf16 v[80:83], v[168:171], v[188:191], v[80:83]
	v_mfma_f32_16x16x32_bf16 v[84:87], v[176:179], v[188:191], v[84:87]
	v_mfma_f32_16x16x32_bf16 v[64:67], v[168:171], v[196:199], v[64:67]
	v_mfma_f32_16x16x32_bf16 v[68:71], v[176:179], v[196:199], v[68:71]
	v_mfma_f32_16x16x32_bf16 v[48:51], v[168:171], v[212:215], v[48:51]
	v_mfma_f32_16x16x32_bf16 v[52:55], v[176:179], v[212:215], v[52:55]
	v_mfma_f32_16x16x32_bf16 v[32:35], v[168:171], v[220:223], v[32:35]
	v_mfma_f32_16x16x32_bf16 v[36:39], v[176:179], v[220:223], v[36:39]
	s_barrier
	s_mov_b32 m0, s93
	v_lshl_add_u64 v[186:187], s[66:67], 0, v[140:141]
	s_add_u32 s64, s66, s64
	ds_read_b128 v[180:183], v144 offset:16384
	ds_read_b128 v[188:191], v144 offset:17408
	ds_read_b128 v[192:195], v144 offset:18432
	ds_read_b128 v[196:199], v144 offset:19456
	ds_read_b128 v[200:203], v144 offset:20480
	ds_read_b128 v[212:215], v144 offset:21504
	ds_read_b128 v[216:219], v144 offset:22528
	ds_read_b128 v[220:223], v144 offset:23552
	global_load_lds_dwordx4 v[186:187], off
	v_lshl_add_u64 v[206:207], v[186:187], 0, s[62:63]
	s_mov_b32 m0, s10
	s_addc_u32 s65, s67, s65
	global_load_lds_dwordx4 v[206:207], off
	v_lshl_add_u64 v[140:141], s[64:65], 0, v[140:141]
	s_mov_b32 m0, s11
	v_lshl_add_u64 v[210:211], v[140:141], 0, s[62:63]
	global_load_lds_dwordx4 v[140:141], off
	s_mov_b32 m0, s8
	v_lshl_add_u64 v[224:225], s[60:61], 0, v[134:135]
	global_load_lds_dwordx4 v[210:211], off
	s_mov_b32 m0, s14
	v_lshl_add_u64 v[226:227], v[224:225], 0, s[56:57]
	global_load_lds_dwordx4 v[224:225], off
	s_mov_b32 m0, s73
	s_nop 0
	global_load_lds_dwordx4 v[226:227], off
	s_waitcnt vmcnt(8)
	s_waitcnt lgkmcnt(0)
	s_barrier
	v_mfma_f32_16x16x32_bf16 v[88:91], v[148:151], v[180:183], v[88:91]
	v_mfma_f32_16x16x32_bf16 v[92:95], v[156:159], v[180:183], v[92:95]
	v_mfma_f32_16x16x32_bf16 v[72:75], v[148:151], v[192:195], v[72:75]
	v_mfma_f32_16x16x32_bf16 v[76:79], v[156:159], v[192:195], v[76:79]
	v_mfma_f32_16x16x32_bf16 v[56:59], v[148:151], v[200:203], v[56:59]
	v_mfma_f32_16x16x32_bf16 v[60:63], v[156:159], v[200:203], v[60:63]
	v_mfma_f32_16x16x32_bf16 v[40:43], v[148:151], v[216:219], v[40:43]
	v_mfma_f32_16x16x32_bf16 v[44:47], v[156:159], v[216:219], v[44:47]
	v_mfma_f32_16x16x32_bf16 v[88:91], v[152:155], v[188:191], v[88:91]
	v_mfma_f32_16x16x32_bf16 v[92:95], v[160:163], v[188:191], v[92:95]
	v_mfma_f32_16x16x32_bf16 v[72:75], v[152:155], v[196:199], v[72:75]
	v_mfma_f32_16x16x32_bf16 v[76:79], v[160:163], v[196:199], v[76:79]
	v_mfma_f32_16x16x32_bf16 v[56:59], v[152:155], v[212:215], v[56:59]
	v_mfma_f32_16x16x32_bf16 v[60:63], v[160:163], v[212:215], v[60:63]
	v_mfma_f32_16x16x32_bf16 v[40:43], v[152:155], v[220:223], v[40:43]
	v_mfma_f32_16x16x32_bf16 v[44:47], v[160:163], v[220:223], v[44:47]
	v_mfma_f32_16x16x32_bf16 v[24:27], v[164:167], v[180:183], v[24:27]
	v_mfma_f32_16x16x32_bf16 v[28:31], v[172:175], v[180:183], v[28:31]
	v_mfma_f32_16x16x32_bf16 v[16:19], v[164:167], v[192:195], v[16:19]
	v_mfma_f32_16x16x32_bf16 v[20:23], v[172:175], v[192:195], v[20:23]
	v_mfma_f32_16x16x32_bf16 v[8:11], v[164:167], v[200:203], v[8:11]
	v_mfma_f32_16x16x32_bf16 v[12:15], v[172:175], v[200:203], v[12:15]
	v_mfma_f32_16x16x32_bf16 v[0:3], v[164:167], v[216:219], v[0:3]
	v_mfma_f32_16x16x32_bf16 v[4:7], v[172:175], v[216:219], v[4:7]
	v_mfma_f32_16x16x32_bf16 v[24:27], v[168:171], v[188:191], v[24:27]
	v_mfma_f32_16x16x32_bf16 v[28:31], v[176:179], v[188:191], v[28:31]
	v_mfma_f32_16x16x32_bf16 v[16:19], v[168:171], v[196:199], v[16:19]
	v_mfma_f32_16x16x32_bf16 v[20:23], v[176:179], v[196:199], v[20:23]
	v_mfma_f32_16x16x32_bf16 v[8:11], v[168:171], v[212:215], v[8:11]
	v_mfma_f32_16x16x32_bf16 v[12:15], v[176:179], v[212:215], v[12:15]
	v_mfma_f32_16x16x32_bf16 v[0:3], v[168:171], v[220:223], v[0:3]
	v_mfma_f32_16x16x32_bf16 v[4:7], v[176:179], v[220:223], v[4:7]
	s_barrier
; #define PG8_WAIT_V(n) asm volatile("s_waitcnt vmcnt(" #n ")" ::: "memory")
; #define PG8_WAIT_VP() asm volatile("s_waitcnt vmcnt(%0)" :: "n"(8 + Epi::NST) : "memory")
; template <class Epi, class Sched>
; __device__ __forceinline__ void gemm_phase(PG8_LAS unsigned char* lds, const Sched& S, const Epi& E, int tid_in) {
;     ...
;         { const int t = 0; PG8_KITER(PG8_WAIT_VP()); }
;         for (int t = 2; t < nt; t += 2) PG8_KITER(PG8_WAIT_V(8));
	ds_read_b128 v[148:151], v145
	ds_read_b128 v[152:155], v145 offset:1024
	ds_read_b128 v[156:159], v145 offset:2048
	ds_read_b128 v[160:163], v145 offset:3072
	ds_read_b128 v[164:167], v146
	ds_read_b128 v[168:171], v146 offset:1024
	ds_read_b128 v[172:175], v146 offset:2048
	ds_read_b128 v[176:179], v146 offset:3072
	s_add_u32 s58, s60, s58
	s_addc_u32 s59, s61, s59
	s_mov_b32 m0, s74
	v_lshl_add_u64 v[134:135], s[58:59], 0, v[134:135]
	ds_read_b128 v[180:183], v144 offset:32768
	ds_read_b128 v[188:191], v144 offset:33792
	ds_read_b128 v[192:195], v144 offset:34816
	ds_read_b128 v[196:199], v144 offset:35840
	ds_read_b128 v[200:203], v144 offset:36864
	ds_read_b128 v[212:215], v144 offset:37888
	ds_read_b128 v[216:219], v144 offset:38912
	ds_read_b128 v[220:223], v144 offset:39936
	global_load_lds_dwordx4 v[134:135], off
	v_lshl_add_u64 v[134:135], v[134:135], 0, s[56:57]
	s_mov_b32 m0, s75
	s_nop 0
	global_load_lds_dwordx4 v[134:135], off
	s_waitcnt vmcnt(8)
	s_waitcnt lgkmcnt(0)
	s_barrier
	v_mfma_f32_16x16x32_bf16 v[120:123], v[148:151], v[180:183], v[120:123]
	v_mfma_f32_16x16x32_bf16 v[124:127], v[156:159], v[180:183], v[124:127]
	v_mfma_f32_16x16x32_bf16 v[112:115], v[148:151], v[192:195], v[112:115]
	v_mfma_f32_16x16x32_bf16 v[116:119], v[156:159], v[192:195], v[116:119]
	v_mfma_f32_16x16x32_bf16 v[104:107], v[148:151], v[200:203], v[104:107]
	v_mfma_f32_16x16x32_bf16 v[108:111], v[156:159], v[200:203], v[108:111]
	v_mfma_f32_16x16x32_bf16 v[96:99], v[148:151], v[216:219], v[96:99]
	v_mfma_f32_16x16x32_bf16 v[100:103], v[156:159], v[216:219], v[100:103]
	v_mfma_f32_16x16x32_bf16 v[120:123], v[152:155], v[188:191], v[120:123]
	v_mfma_f32_16x16x32_bf16 v[124:127], v[160:163], v[188:191], v[124:127]
	v_mfma_f32_16x16x32_bf16 v[112:115], v[152:155], v[196:199], v[112:115]
	v_mfma_f32_16x16x32_bf16 v[116:119], v[160:163], v[196:199], v[116:119]
	v_mfma_f32_16x16x32_bf16 v[104:107], v[152:155], v[212:215], v[104:107]
	v_mfma_f32_16x16x32_bf16 v[108:111], v[160:163], v[212:215], v[108:111]
	v_mfma_f32_16x16x32_bf16 v[96:99], v[152:155], v[220:223], v[96:99]
	v_mfma_f32_16x16x32_bf16 v[100:103], v[160:163], v[220:223], v[100:103]
	v_mfma_f32_16x16x32_bf16 v[80:83], v[164:167], v[180:183], v[80:83]
	v_mfma_f32_16x16x32_bf16 v[84:87], v[172:175], v[180:183], v[84:87]
	v_mfma_f32_16x16x32_bf16 v[64:67], v[164:167], v[192:195], v[64:67]
	v_mfma_f32_16x16x32_bf16 v[68:71], v[172:175], v[192:195], v[68:71]
	v_mfma_f32_16x16x32_bf16 v[48:51], v[164:167], v[200:203], v[48:51]
	v_mfma_f32_16x16x32_bf16 v[52:55], v[172:175], v[200:203], v[52:55]
	v_mfma_f32_16x16x32_bf16 v[32:35], v[164:167], v[216:219], v[32:35]
	v_mfma_f32_16x16x32_bf16 v[36:39], v[172:175], v[216:219], v[36:39]
	v_mfma_f32_16x16x32_bf16 v[80:83], v[168:171], v[188:191], v[80:83]
	v_mfma_f32_16x16x32_bf16 v[84:87], v[176:179], v[188:191], v[84:87]
	v_mfma_f32_16x16x32_bf16 v[64:67], v[168:171], v[196:199], v[64:67]
	v_mfma_f32_16x16x32_bf16 v[68:71], v[176:179], v[196:199], v[68:71]
	v_mfma_f32_16x16x32_bf16 v[48:51], v[168:171], v[212:215], v[48:51]
	v_mfma_f32_16x16x32_bf16 v[52:55], v[176:179], v[212:215], v[52:55]
	v_mfma_f32_16x16x32_bf16 v[32:35], v[168:171], v[220:223], v[32:35]
	v_mfma_f32_16x16x32_bf16 v[36:39], v[176:179], v[220:223], v[36:39]
	s_barrier
	s_mov_b32 m0, s16
	v_lshl_add_u64 v[134:135], v[186:187], 0, s[84:85]
	ds_read_b128 v[180:183], v144 offset:49152
	ds_read_b128 v[188:191], v144 offset:50176
	ds_read_b128 v[192:195], v144 offset:51200
	ds_read_b128 v[196:199], v144 offset:52224
	ds_read_b128 v[200:203], v144 offset:53248
	ds_read_b128 v[212:215], v144 offset:54272
	ds_read_b128 v[216:219], v144 offset:55296
	ds_read_b128 v[220:223], v144 offset:56320
	global_load_lds_dwordx4 v[134:135], off
	v_lshl_add_u64 v[134:135], v[206:207], 0, s[84:85]
	s_mov_b32 m0, s17
	s_nop 0
	global_load_lds_dwordx4 v[134:135], off
	v_lshl_add_u64 v[134:135], v[140:141], 0, s[84:85]
	s_mov_b32 m0, s24
	s_nop 0
	global_load_lds_dwordx4 v[134:135], off
	v_lshl_add_u64 v[134:135], v[210:211], 0, s[84:85]
	s_mov_b32 m0, s25
	s_nop 0
	global_load_lds_dwordx4 v[134:135], off
	v_lshl_add_u64 v[134:135], v[224:225], 0, s[84:85]
	s_mov_b32 m0, s13
	s_nop 0
	global_load_lds_dwordx4 v[134:135], off
	v_lshl_add_u64 v[134:135], v[226:227], 0, s[84:85]
	s_mov_b32 m0, s76
	s_nop 0
	global_load_lds_dwordx4 v[134:135], off
	s_waitcnt vmcnt(8)
	s_waitcnt lgkmcnt(0)
	s_barrier
	v_mfma_f32_16x16x32_bf16 v[88:91], v[148:151], v[180:183], v[88:91]
	v_mfma_f32_16x16x32_bf16 v[92:95], v[156:159], v[180:183], v[92:95]
	v_mfma_f32_16x16x32_bf16 v[72:75], v[148:151], v[192:195], v[72:75]
	v_mfma_f32_16x16x32_bf16 v[76:79], v[156:159], v[192:195], v[76:79]
	v_mfma_f32_16x16x32_bf16 v[56:59], v[148:151], v[200:203], v[56:59]
	v_mfma_f32_16x16x32_bf16 v[60:63], v[156:159], v[200:203], v[60:63]
	v_mfma_f32_16x16x32_bf16 v[40:43], v[148:151], v[216:219], v[40:43]
	v_mfma_f32_16x16x32_bf16 v[44:47], v[156:159], v[216:219], v[44:47]
	v_mfma_f32_16x16x32_bf16 v[88:91], v[152:155], v[188:191], v[88:91]
	v_mfma_f32_16x16x32_bf16 v[92:95], v[160:163], v[188:191], v[92:95]
	v_mfma_f32_16x16x32_bf16 v[72:75], v[152:155], v[196:199], v[72:75]
	v_mfma_f32_16x16x32_bf16 v[76:79], v[160:163], v[196:199], v[76:79]
	v_mfma_f32_16x16x32_bf16 v[56:59], v[152:155], v[212:215], v[56:59]
	v_mfma_f32_16x16x32_bf16 v[60:63], v[160:163], v[212:215], v[60:63]
	v_mfma_f32_16x16x32_bf16 v[40:43], v[152:155], v[220:223], v[40:43]
	v_mfma_f32_16x16x32_bf16 v[44:47], v[160:163], v[220:223], v[44:47]
	v_mfma_f32_16x16x32_bf16 v[24:27], v[164:167], v[180:183], v[24:27]
	v_mfma_f32_16x16x32_bf16 v[28:31], v[172:175], v[180:183], v[28:31]
	v_mfma_f32_16x16x32_bf16 v[16:19], v[164:167], v[192:195], v[16:19]
	v_mfma_f32_16x16x32_bf16 v[20:23], v[172:175], v[192:195], v[20:23]
	v_mfma_f32_16x16x32_bf16 v[8:11], v[164:167], v[200:203], v[8:11]
	v_mfma_f32_16x16x32_bf16 v[12:15], v[172:175], v[200:203], v[12:15]
	v_mfma_f32_16x16x32_bf16 v[0:3], v[164:167], v[216:219], v[0:3]
	v_mfma_f32_16x16x32_bf16 v[4:7], v[172:175], v[216:219], v[4:7]
	v_mfma_f32_16x16x32_bf16 v[24:27], v[168:171], v[188:191], v[24:27]
	v_mfma_f32_16x16x32_bf16 v[28:31], v[176:179], v[188:191], v[28:31]
	v_mfma_f32_16x16x32_bf16 v[16:19], v[168:171], v[196:199], v[16:19]
	v_mfma_f32_16x16x32_bf16 v[20:23], v[176:179], v[196:199], v[20:23]
	v_mfma_f32_16x16x32_bf16 v[8:11], v[168:171], v[212:215], v[8:11]
	v_mfma_f32_16x16x32_bf16 v[12:15], v[176:179], v[212:215], v[12:15]
	v_mfma_f32_16x16x32_bf16 v[0:3], v[168:171], v[220:223], v[0:3]
	v_mfma_f32_16x16x32_bf16 v[4:7], v[176:179], v[220:223], v[4:7]
	s_barrier
	s_add_i32 s56, s86, 2
	s_add_u32 s46, s46, 0x100
	s_addc_u32 s47, s47, 0
	s_add_u32 s48, s48, 0x100
	s_addc_u32 s49, s49, 0
	s_cmp_ge_u32 s86, s87
	s_cbranch_scc1 .LBB0_1278
	s_mov_b32 s86, s56
	s_branch .LBB0_1274

; __device__ __forceinline__ int lane_id() { int l; asm volatile("v_mbcnt_lo_u32_b32 %0, -1, 0\n\tv_mbcnt_hi_u32_b32 %0, -1, %0" : "=v"(l)); return l; }
;     __device__ __forceinline__ bool next(int i, UnitG& u) const { if (!P.next(i, u)) return false; u.O = O + ((size_t)u.x0 * 256 * 2048 + (size_t)u.x1 * 256) * 2; u.ldo = 2048; u.kind = 0; return true; }
; template <class Epi, class Sched>
; __device__ __forceinline__ void gemm_phase(PG8_LAS unsigned char* lds, const Sched& S, const Epi& E, int tid_in) {
;     ...
;         int aoff, boff; { const int l3 = lane_id(), fr3 = l3 & 15, fq3 = l3 >> 4; aoff = lds_byte(wr * 64 + fr3, fq3 * 8); boff = lds_byte(wc * 32 + fr3, fq3 * 8); }
;         const bool has_next = S.next(ui + 1, nxt);
;         const char* nA = has_next ? nxt.A : cA; const char* nB = has_next ? nxt.B : cB;
;         const int nlda = has_next ? nxt.lda : cur.lda, nldb = has_next ? nxt.ldb : cur.ldb;
;         unsigned nvA, nvB; { int r2, c2; stage_rc((wid * 64 + lane_id()) * 16, r2, c2); const int rb2 = Epi::PERM ? ((r2 & ~31) + perm32(r2 & 31)) : r2;
;             nvA = (unsigned)(r2 * nlda + c2) * 2u; nvB = (unsigned)(rb2 * nldb + c2) * 2u; }
;         const unsigned nqA = (unsigned)nlda * 128u, nqB = (unsigned)nldb * 128u;
;         const int nt = cur.K / BK;
.LBB0_1445:
	v_and_b32_e32 v1, 15, v0
	v_or_b32_e32 v2, s46, v1
	v_ashrrev_i32_e32 v3, 6, v0
	v_lshlrev_b32_e32 v4, 6, v2
	v_and_b32_e32 v5, 48, v0
	s_movk_i32 s53, 0x3c0
	v_lshlrev_b32_e32 v2, 2, v2
	v_and_or_b32 v4, v4, s53, v5
	v_lshl_add_u32 v6, v3, 10, s47
	v_and_b32_e32 v2, 32, v2
	v_lshlrev_b32_e32 v0, 2, v0
	s_nop 0
	v_bitop3_b32 v32, v4, v6, v2 bitop3:0xde
	v_lshl_or_b32 v1, v1, 6, v5
	v_add_lshl_u32 v2, v3, s49, 10
	v_and_b32_e32 v0, 32, v0
	v_bitop3_b32 v119, v1, v2, v0 bitop3:0xde
	v_mbcnt_lo_u32_b32 v0, -1, 0
	v_mbcnt_hi_u32_b32 v0, -1, v0
	s_mov_b32 s53, 0xfffe0
	v_add_u32_e32 v0, s50, v0
	v_ashrrev_i32_e32 v2, 31, v0
	v_lshrrev_b32_e32 v2, 26, v2
	v_lshlrev_b32_e32 v1, 4, v0
	v_add_u32_e32 v2, v0, v2
	v_bfe_i32 v0, v0, 27, 1
	v_lshrrev_b32_e32 v0, 22, v0
	v_add_u32_e32 v0, v1, v0
	v_and_b32_e32 v0, 0xfffffc00, v0
	v_sub_u32_e32 v0, v1, v0
	v_lshrrev_b32_e32 v1, 4, v0
	v_bitop3_b32 v0, v1, v0, 32 bitop3:0x6c
	v_ashrrev_i32_e32 v3, 31, v0
	v_lshrrev_b32_e32 v3, 26, v3
	v_ashrrev_i32_e32 v2, 6, v2
	v_add_u32_e32 v3, v0, v3
	v_lshlrev_b32_e32 v1, 3, v2
	v_ashrrev_i32_e32 v4, 6, v3
	v_and_b32_e32 v3, 0xc0, v3
	v_and_b32_e32 v1, -16, v1
	v_sub_u32_e32 v0, v0, v3
	v_add_u32_e32 v1, v4, v1
	v_lshlrev_b32_e32 v2, 5, v2
	v_ashrrev_i16_sdwa v0, v205, sext(v0) dst_sel:DWORD dst_unused:UNUSED_PAD src0_sel:DWORD src1_sel:BYTE_0
	v_and_b32_e32 v2, 32, v2
	v_bfe_i32 v0, v0, 0, 16
	v_lshlrev_b32_e32 v3, 1, v1
	v_lshrrev_b32_e32 v5, 2, v1
	v_and_b32_e32 v4, 3, v4
	s_add_i32 s55, 0, 0x10000
	s_add_i32 s57, 0, 0x14000
	v_and_b32_e32 v3, 24, v3
	v_and_b32_e32 v5, 4, v5
	v_and_or_b32 v4, v1, s53, v4
	v_add_lshl_u32 v34, v2, v0, 1
	v_add_u32_e32 v116, s55, v119
	v_add_u32_e32 v117, s57, v119
	v_or3_b32 v33, v4, v5, v3
	v_lshl_add_u32 v186, v1, 12, v34
	ds_read_b128 v[0:3], v116
	ds_read_b128 v[4:7], v116 offset:1024
	ds_read_b128 v[8:11], v116 offset:2048
	ds_read_b128 v[12:15], v116 offset:3072
	ds_read_b128 v[16:19], v117
	ds_read_b128 v[20:23], v117 offset:1024
	ds_read_b128 v[24:27], v117 offset:2048
	ds_read_b128 v[28:31], v117 offset:3072
	v_lshl_add_u32 v211, v33, 12, v34
	v_mov_b32_e32 v115, v185
	v_lshl_add_u64 v[206:207], s[20:21], 0, v[114:115]
	s_add_i32 s53, s7, 0xc000
	v_add_u32_e32 v118, 0, v32
	v_lshl_add_u64 v[64:65], v[206:207], 0, s[80:81]
	s_mov_b32 m0, s53
	s_add_i32 s54, s7, 0xe000
	ds_read_b128 v[32:35], v118
	ds_read_b128 v[36:39], v118 offset:1024
	ds_read_b128 v[40:43], v118 offset:2048
	ds_read_b128 v[44:47], v118 offset:3072
	ds_read_b128 v[48:51], v118 offset:4096
	ds_read_b128 v[52:55], v118 offset:5120
	ds_read_b128 v[56:59], v118 offset:6144
	ds_read_b128 v[60:63], v118 offset:7168
	global_load_lds_dwordx4 v[64:65], off
	v_lshl_add_u64 v[64:65], v[206:207], 0, s[78:79]
	s_mov_b32 m0, s54
	s_nop 0
	global_load_lds_dwordx4 v[64:65], off
	s_waitcnt vmcnt(24)
	s_waitcnt lgkmcnt(0)
	s_barrier
	v_mfma_f32_16x16x32_bf16 v[88:91], v[0:3], v[56:59], 0
	v_mfma_f32_16x16x32_bf16 v[64:67], v[0:3], v[32:35], 0
	v_mfma_f32_16x16x32_bf16 v[68:71], v[8:11], v[32:35], 0
	v_mfma_f32_16x16x32_bf16 v[72:75], v[0:3], v[40:43], 0
	v_mfma_f32_16x16x32_bf16 v[76:79], v[8:11], v[40:43], 0
	v_mfma_f32_16x16x32_bf16 v[80:83], v[0:3], v[48:51], 0
	v_mfma_f32_16x16x32_bf16 v[84:87], v[8:11], v[48:51], 0
	v_mfma_f32_16x16x32_bf16 v[96:99], v[4:7], v[60:63], v[88:91]
	v_mfma_f32_16x16x32_bf16 v[88:91], v[8:11], v[56:59], 0
	v_mfma_f32_16x16x32_bf16 v[64:67], v[4:7], v[36:39], v[64:67]
	v_mfma_f32_16x16x32_bf16 v[68:71], v[12:15], v[36:39], v[68:71]
	v_mfma_f32_16x16x32_bf16 v[72:75], v[4:7], v[44:47], v[72:75]
	v_mfma_f32_16x16x32_bf16 v[76:79], v[12:15], v[44:47], v[76:79]
	v_mfma_f32_16x16x32_bf16 v[80:83], v[4:7], v[52:55], v[80:83]
	v_mfma_f32_16x16x32_bf16 v[84:87], v[12:15], v[52:55], v[84:87]
	v_mfma_f32_16x16x32_bf16 v[100:103], v[12:15], v[60:63], v[88:91]
	v_mfma_f32_16x16x32_bf16 v[88:91], v[16:19], v[32:35], 0
	v_mfma_f32_16x16x32_bf16 v[32:35], v[24:27], v[32:35], 0
	v_mfma_f32_16x16x32_bf16 v[120:123], v[20:23], v[36:39], v[88:91]
	v_mfma_f32_16x16x32_bf16 v[32:35], v[28:31], v[36:39], v[32:35]
	v_mfma_f32_16x16x32_bf16 v[36:39], v[16:19], v[40:43], 0
	v_mfma_f32_16x16x32_bf16 v[40:43], v[24:27], v[40:43], 0
	v_mfma_f32_16x16x32_bf16 v[36:39], v[20:23], v[44:47], v[36:39]
	v_mfma_f32_16x16x32_bf16 v[40:43], v[28:31], v[44:47], v[40:43]
	v_mfma_f32_16x16x32_bf16 v[44:47], v[16:19], v[48:51], 0
	v_mfma_f32_16x16x32_bf16 v[48:51], v[24:27], v[48:51], 0
	v_mfma_f32_16x16x32_bf16 v[44:47], v[20:23], v[52:55], v[44:47]
	v_mfma_f32_16x16x32_bf16 v[48:51], v[28:31], v[52:55], v[48:51]
	v_mfma_f32_16x16x32_bf16 v[52:55], v[16:19], v[56:59], 0
	v_mfma_f32_16x16x32_bf16 v[56:59], v[24:27], v[56:59], 0
	v_mfma_f32_16x16x32_bf16 v[52:55], v[20:23], v[60:63], v[52:55]
	v_mfma_f32_16x16x32_bf16 v[56:59], v[28:31], v[60:63], v[56:59]
	s_barrier
	v_mov_b32_e32 v113, v185
	v_lshl_add_u64 v[244:245], s[22:23], 0, v[112:113]
	s_mov_b64 s[60:61], 0x100
	s_add_i32 s55, s55, s30
	v_lshl_add_u64 v[136:137], v[244:245], 0, s[60:61]
	s_mov_b32 m0, s55
	s_mov_b64 s[62:63], 0x40100
	s_add_i32 s56, s55, 0x2000
	ds_read_b128 v[60:63], v118 offset:16384
	ds_read_b128 v[88:91], v118 offset:17408
	ds_read_b128 v[92:95], v118 offset:18432
	ds_read_b128 v[104:107], v118 offset:19456
	ds_read_b128 v[108:111], v118 offset:20480
	ds_read_b128 v[124:127], v118 offset:21504
	ds_read_b128 v[128:131], v118 offset:22528
	ds_read_b128 v[132:135], v118 offset:23552
	global_load_lds_dwordx4 v[136:137], off
	v_lshl_add_u64 v[136:137], v[244:245], 0, s[62:63]
	s_mov_b32 m0, s56
	s_mov_b64 s[64:65], 0x80100
	s_add_i32 s57, s57, s30
	global_load_lds_dwordx4 v[136:137], off
	v_lshl_add_u64 v[136:137], v[244:245], 0, s[64:65]
	s_mov_b32 m0, s57
	s_mov_b64 s[66:67], 0xc0100
	s_add_i32 s58, s57, 0x2000
	global_load_lds_dwordx4 v[136:137], off
	v_lshl_add_u64 v[136:137], v[244:245], 0, s[66:67]
	s_mov_b32 m0, s58
	s_nop 0
	global_load_lds_dwordx4 v[136:137], off
	v_lshl_add_u64 v[136:137], v[206:207], 0, s[60:61]
	s_mov_b32 m0, s7
	s_nop 0
	global_load_lds_dwordx4 v[136:137], off
	v_lshl_add_u64 v[136:137], v[206:207], 0, s[62:63]
	s_mov_b32 m0, s31
	s_nop 0
	global_load_lds_dwordx4 v[136:137], off
	s_waitcnt vmcnt(24)
	s_waitcnt lgkmcnt(0)
	s_barrier
	v_mfma_f32_16x16x32_bf16 v[136:139], v[0:3], v[60:63], 0
	v_mfma_f32_16x16x32_bf16 v[144:147], v[0:3], v[92:95], 0
	v_mfma_f32_16x16x32_bf16 v[152:155], v[0:3], v[108:111], 0
	v_mfma_f32_16x16x32_bf16 v[0:3], v[0:3], v[128:131], 0
	v_mfma_f32_16x16x32_bf16 v[136:139], v[4:7], v[88:91], v[136:139]
	v_mfma_f32_16x16x32_bf16 v[144:147], v[4:7], v[104:107], v[144:147]
	v_mfma_f32_16x16x32_bf16 v[152:155], v[4:7], v[124:127], v[152:155]
	v_mfma_f32_16x16x32_bf16 v[0:3], v[4:7], v[132:135], v[0:3]
	v_mfma_f32_16x16x32_bf16 v[4:7], v[8:11], v[128:131], 0
	v_mfma_f32_16x16x32_bf16 v[140:143], v[8:11], v[60:63], 0
	v_mfma_f32_16x16x32_bf16 v[148:151], v[8:11], v[92:95], 0
	v_mfma_f32_16x16x32_bf16 v[156:159], v[8:11], v[108:111], 0
	v_mfma_f32_16x16x32_bf16 v[4:7], v[12:15], v[132:135], v[4:7]
	v_mfma_f32_16x16x32_bf16 v[140:143], v[12:15], v[88:91], v[140:143]
	v_mfma_f32_16x16x32_bf16 v[148:151], v[12:15], v[104:107], v[148:151]
	v_mfma_f32_16x16x32_bf16 v[156:159], v[12:15], v[124:127], v[156:159]
	v_mfma_f32_16x16x32_bf16 v[8:11], v[16:19], v[60:63], 0
	v_mfma_f32_16x16x32_bf16 v[160:163], v[20:23], v[88:91], v[8:11]
	v_mfma_f32_16x16x32_bf16 v[8:11], v[24:27], v[60:63], 0
	v_mfma_f32_16x16x32_bf16 v[180:183], v[28:31], v[88:91], v[8:11]
	v_mfma_f32_16x16x32_bf16 v[8:11], v[16:19], v[92:95], 0
	v_mfma_f32_16x16x32_bf16 v[188:191], v[20:23], v[104:107], v[8:11]
	v_mfma_f32_16x16x32_bf16 v[8:11], v[24:27], v[92:95], 0
	v_mfma_f32_16x16x32_bf16 v[192:195], v[28:31], v[104:107], v[8:11]
	v_mfma_f32_16x16x32_bf16 v[8:11], v[16:19], v[108:111], 0
	v_mfma_f32_16x16x32_bf16 v[196:199], v[20:23], v[124:127], v[8:11]
	v_mfma_f32_16x16x32_bf16 v[8:11], v[24:27], v[108:111], 0
	v_mfma_f32_16x16x32_bf16 v[124:127], v[28:31], v[124:127], v[8:11]
	v_mfma_f32_16x16x32_bf16 v[8:11], v[16:19], v[128:131], 0
	v_mfma_f32_16x16x32_bf16 v[200:203], v[20:23], v[132:135], v[8:11]
	v_mfma_f32_16x16x32_bf16 v[8:11], v[24:27], v[128:131], 0
	v_mfma_f32_16x16x32_bf16 v[128:131], v[28:31], v[132:135], v[8:11]
	s_barrier
	s_add_i32 s59, 0, 0x18000
	s_add_i32 s61, 0, 0x1c000
	v_add_u32_e32 v113, s59, v119
	v_add_u32_e32 v119, s61, v119
	s_nop 0
	ds_read_b128 v[8:11], v113
	ds_read_b128 v[12:15], v113 offset:1024
	ds_read_b128 v[16:19], v113 offset:2048
	ds_read_b128 v[20:23], v113 offset:3072
	ds_read_b128 v[132:135], v119
	ds_read_b128 v[212:215], v119 offset:1024
	ds_read_b128 v[216:219], v119 offset:2048
	ds_read_b128 v[220:223], v119 offset:3072
	s_mov_b32 m0, s34
	v_lshl_add_u64 v[88:89], v[206:207], 0, s[64:65]
	ds_read_b128 v[24:27], v118 offset:32768
	ds_read_b128 v[28:31], v118 offset:33792
	ds_read_b128 v[60:63], v118 offset:34816
	ds_read_b128 v[224:227], v118 offset:35840
	ds_read_b128 v[228:231], v118 offset:36864
	ds_read_b128 v[232:235], v118 offset:37888
	ds_read_b128 v[236:239], v118 offset:38912
	ds_read_b128 v[240:243], v118 offset:39936
	global_load_lds_dwordx4 v[88:89], off
	v_lshl_add_u64 v[88:89], v[206:207], 0, s[66:67]
	s_mov_b32 m0, s35
	s_nop 0
	global_load_lds_dwordx4 v[88:89], off
	s_waitcnt vmcnt(8)
	s_waitcnt lgkmcnt(0)
	s_barrier
	v_mfma_f32_16x16x32_bf16 v[64:67], v[8:11], v[24:27], v[64:67]
	v_mfma_f32_16x16x32_bf16 v[172:175], v[12:15], v[28:31], v[64:67]
	v_mfma_f32_16x16x32_bf16 v[64:67], v[16:19], v[24:27], v[68:71]
	v_mfma_f32_16x16x32_bf16 v[164:167], v[20:23], v[28:31], v[64:67]
	v_mfma_f32_16x16x32_bf16 v[64:67], v[8:11], v[60:63], v[72:75]
	v_mfma_f32_16x16x32_bf16 v[108:111], v[12:15], v[224:227], v[64:67]
	v_mfma_f32_16x16x32_bf16 v[64:67], v[16:19], v[60:63], v[76:79]
	v_mfma_f32_16x16x32_bf16 v[104:107], v[20:23], v[224:227], v[64:67]
	v_mfma_f32_16x16x32_bf16 v[64:67], v[8:11], v[228:231], v[80:83]
	v_mfma_f32_16x16x32_bf16 v[92:95], v[12:15], v[232:235], v[64:67]
	v_mfma_f32_16x16x32_bf16 v[64:67], v[16:19], v[228:231], v[84:87]
	v_mfma_f32_16x16x32_bf16 v[88:91], v[20:23], v[232:235], v[64:67]
	v_mfma_f32_16x16x32_bf16 v[64:67], v[8:11], v[236:239], v[96:99]
	v_mfma_f32_16x16x32_bf16 v[76:79], v[12:15], v[240:243], v[64:67]
	v_mfma_f32_16x16x32_bf16 v[64:67], v[16:19], v[236:239], v[100:103]
	v_mfma_f32_16x16x32_bf16 v[68:71], v[20:23], v[240:243], v[64:67]
	v_mfma_f32_16x16x32_bf16 v[64:67], v[132:135], v[24:27], v[120:123]
	v_mfma_f32_16x16x32_bf16 v[24:27], v[216:219], v[24:27], v[32:35]
	v_mfma_f32_16x16x32_bf16 v[168:171], v[220:223], v[28:31], v[24:27]
	v_mfma_f32_16x16x32_bf16 v[24:27], v[132:135], v[60:63], v[36:39]
	v_mfma_f32_16x16x32_bf16 v[100:103], v[212:215], v[224:227], v[24:27]
	v_mfma_f32_16x16x32_bf16 v[24:27], v[216:219], v[60:63], v[40:43]
	v_mfma_f32_16x16x32_bf16 v[96:99], v[220:223], v[224:227], v[24:27]
	v_mfma_f32_16x16x32_bf16 v[24:27], v[132:135], v[228:231], v[44:47]
	v_mfma_f32_16x16x32_bf16 v[84:87], v[212:215], v[232:235], v[24:27]
	v_mfma_f32_16x16x32_bf16 v[24:27], v[216:219], v[228:231], v[48:51]
	v_mfma_f32_16x16x32_bf16 v[80:83], v[220:223], v[232:235], v[24:27]
	v_mfma_f32_16x16x32_bf16 v[24:27], v[132:135], v[236:239], v[52:55]
	v_mfma_f32_16x16x32_bf16 v[176:179], v[212:215], v[28:31], v[64:67]
	v_mfma_f32_16x16x32_bf16 v[64:67], v[212:215], v[240:243], v[24:27]
	v_mfma_f32_16x16x32_bf16 v[24:27], v[216:219], v[236:239], v[56:59]
	v_mfma_f32_16x16x32_bf16 v[52:55], v[220:223], v[240:243], v[24:27]
	s_barrier
; #define PG8_WAIT_V(n) asm volatile("s_waitcnt vmcnt(" #n ")" ::: "memory")
; #define PG8_WAIT_VP() asm volatile("s_waitcnt vmcnt(%0)" :: "n"(8 + Epi::NST) : "memory")
; template <class Epi, class Sched>
; __device__ __forceinline__ void gemm_phase(PG8_LAS unsigned char* lds, const Sched& S, const Epi& E, int tid_in) {
;     ...
;         { const int t = 0; PG8_KITER(PG8_WAIT_VP()); }
;         for (int t = 2; t < nt; t += 2) PG8_KITER(PG8_WAIT_V(8));
	s_mov_b64 s[64:65], 0x180
	s_add_i32 s59, s59, s30
	s_nop 2
	v_lshl_add_u64 v[24:25], v[244:245], 0, s[64:65]
	s_mov_b32 m0, s59
	s_mov_b64 s[66:67], 0x40180
	s_add_i32 s60, s59, 0x2000
	ds_read_b128 v[32:35], v118 offset:49152
	ds_read_b128 v[36:39], v118 offset:50176
	ds_read_b128 v[120:123], v118 offset:51200
	ds_read_b128 v[224:227], v118 offset:52224
	ds_read_b128 v[228:231], v118 offset:53248
	ds_read_b128 v[232:235], v118 offset:54272
	ds_read_b128 v[236:239], v118 offset:55296
	ds_read_b128 v[240:243], v118 offset:56320
	global_load_lds_dwordx4 v[24:25], off
	v_lshl_add_u64 v[24:25], v[244:245], 0, s[66:67]
	s_mov_b32 m0, s60
	s_add_i32 s61, s61, s30
	global_load_lds_dwordx4 v[24:25], off
	v_lshl_add_u64 v[24:25], v[244:245], 0, s[70:71]
	s_mov_b32 m0, s61
	s_add_i32 s62, s61, 0x2000
	global_load_lds_dwordx4 v[24:25], off
	v_lshl_add_u64 v[24:25], v[244:245], 0, s[72:73]
	s_mov_b32 m0, s62
	s_nop 0
	global_load_lds_dwordx4 v[24:25], off
	v_lshl_add_u64 v[24:25], v[206:207], 0, s[64:65]
	s_mov_b32 m0, s44
	s_nop 0
	global_load_lds_dwordx4 v[24:25], off
	v_lshl_add_u64 v[24:25], v[206:207], 0, s[66:67]
	s_mov_b32 m0, s45
	s_nop 0
	global_load_lds_dwordx4 v[24:25], off
	s_waitcnt vmcnt(8)
	s_waitcnt lgkmcnt(0)
	s_barrier
	v_mfma_f32_16x16x32_bf16 v[24:27], v[8:11], v[32:35], v[136:139]
	v_mfma_f32_16x16x32_bf16 v[72:75], v[12:15], v[36:39], v[24:27]
	v_mfma_f32_16x16x32_bf16 v[24:27], v[16:19], v[32:35], v[140:143]
	v_mfma_f32_16x16x32_bf16 v[60:63], v[20:23], v[36:39], v[24:27]
	v_mfma_f32_16x16x32_bf16 v[24:27], v[8:11], v[120:123], v[144:147]
	v_mfma_f32_16x16x32_bf16 v[44:47], v[12:15], v[224:227], v[24:27]
	v_mfma_f32_16x16x32_bf16 v[24:27], v[16:19], v[120:123], v[148:151]
	v_mfma_f32_16x16x32_bf16 v[40:43], v[20:23], v[224:227], v[24:27]
	v_mfma_f32_16x16x32_bf16 v[24:27], v[8:11], v[228:231], v[152:155]
	v_mfma_f32_16x16x32_bf16 v[0:3], v[8:11], v[236:239], v[0:3]
	v_mfma_f32_16x16x32_bf16 v[28:31], v[12:15], v[232:235], v[24:27]
	v_mfma_f32_16x16x32_bf16 v[24:27], v[16:19], v[228:231], v[156:159]
	v_mfma_f32_16x16x32_bf16 v[12:15], v[12:15], v[240:243], v[0:3]
	v_mfma_f32_16x16x32_bf16 v[0:3], v[16:19], v[236:239], v[4:7]
	v_mfma_f32_16x16x32_bf16 v[24:27], v[20:23], v[232:235], v[24:27]
	v_mfma_f32_16x16x32_bf16 v[8:11], v[20:23], v[240:243], v[0:3]
	v_mfma_f32_16x16x32_bf16 v[0:3], v[132:135], v[32:35], v[160:163]
	v_mfma_f32_16x16x32_bf16 v[56:59], v[212:215], v[36:39], v[0:3]
	v_mfma_f32_16x16x32_bf16 v[0:3], v[216:219], v[32:35], v[180:183]
	v_mfma_f32_16x16x32_bf16 v[48:51], v[220:223], v[36:39], v[0:3]
	v_mfma_f32_16x16x32_bf16 v[0:3], v[132:135], v[120:123], v[188:191]
	v_mfma_f32_16x16x32_bf16 v[36:39], v[212:215], v[224:227], v[0:3]
	v_mfma_f32_16x16x32_bf16 v[0:3], v[216:219], v[120:123], v[192:195]
	v_mfma_f32_16x16x32_bf16 v[32:35], v[220:223], v[224:227], v[0:3]
	v_mfma_f32_16x16x32_bf16 v[0:3], v[132:135], v[228:231], v[196:199]
	v_mfma_f32_16x16x32_bf16 v[20:23], v[212:215], v[232:235], v[0:3]
	v_mfma_f32_16x16x32_bf16 v[0:3], v[216:219], v[228:231], v[124:127]
	v_mfma_f32_16x16x32_bf16 v[16:19], v[220:223], v[232:235], v[0:3]
	v_mfma_f32_16x16x32_bf16 v[0:3], v[132:135], v[236:239], v[200:203]
	v_mfma_f32_16x16x32_bf16 v[4:7], v[212:215], v[240:243], v[0:3]
	v_mfma_f32_16x16x32_bf16 v[0:3], v[216:219], v[236:239], v[128:131]
	v_mfma_f32_16x16x32_bf16 v[0:3], v[220:223], v[240:243], v[0:3]
	s_barrier
	s_add_u32 s20, s20, 0x80180
	s_addc_u32 s21, s21, 0
	s_add_u32 s63, s22, 0x200
	s_addc_u32 s64, s23, 0
	s_mov_b32 s65, 0
.LBB0_1446:
	ds_read_b128 v[120:123], v116
	ds_read_b128 v[124:127], v116 offset:1024
	ds_read_b128 v[128:131], v116 offset:2048
	ds_read_b128 v[132:135], v116 offset:3072
	ds_read_b128 v[136:139], v117
	ds_read_b128 v[140:143], v117 offset:1024
	ds_read_b128 v[144:147], v117 offset:2048
	ds_read_b128 v[148:151], v117 offset:3072
	s_add_u32 s66, s20, 0xfff80080
	s_addc_u32 s67, s21, -1
	s_cmp_eq_u32 s65, 28
	s_cselect_b64 vcc, -1, 0
	s_and_b64 s[22:23], vcc, exec
	v_cndmask_b32_e32 v184, v114, v186, vcc
	s_cselect_b32 s23, s15, s67
	s_cselect_b32 s22, s14, s66
	v_cndmask_b32_e32 v206, v112, v211, vcc
	s_cselect_b32 s67, s17, s64
	s_cselect_b32 s66, s16, s63
	s_mov_b32 m0, s53
	v_lshl_add_u64 v[212:213], s[20:21], 0, v[114:115]
	ds_read_b128 v[152:155], v118
	ds_read_b128 v[156:159], v118 offset:1024
	ds_read_b128 v[160:163], v118 offset:2048
	ds_read_b128 v[180:183], v118 offset:3072
	ds_read_b128 v[188:191], v118 offset:4096
	ds_read_b128 v[192:195], v118 offset:5120
	ds_read_b128 v[196:199], v118 offset:6144
	ds_read_b128 v[200:203], v118 offset:7168
	global_load_lds_dwordx4 v[212:213], off
	v_lshl_add_u64 v[212:213], v[212:213], 0, s[88:89]
	s_mov_b32 m0, s54
	s_nop 0
	global_load_lds_dwordx4 v[212:213], off
	s_waitcnt vmcnt(8)
	s_waitcnt lgkmcnt(0)
	s_barrier
	v_mfma_f32_16x16x32_bf16 v[172:175], v[120:123], v[152:155], v[172:175]
	v_mfma_f32_16x16x32_bf16 v[164:167], v[128:131], v[152:155], v[164:167]
	v_mfma_f32_16x16x32_bf16 v[108:111], v[120:123], v[160:163], v[108:111]
	v_mfma_f32_16x16x32_bf16 v[104:107], v[128:131], v[160:163], v[104:107]
	v_mfma_f32_16x16x32_bf16 v[92:95], v[120:123], v[188:191], v[92:95]
	v_mfma_f32_16x16x32_bf16 v[88:91], v[128:131], v[188:191], v[88:91]
	v_mfma_f32_16x16x32_bf16 v[76:79], v[120:123], v[196:199], v[76:79]
	v_mfma_f32_16x16x32_bf16 v[68:71], v[128:131], v[196:199], v[68:71]
	v_mfma_f32_16x16x32_bf16 v[172:175], v[124:127], v[156:159], v[172:175]
	v_mfma_f32_16x16x32_bf16 v[164:167], v[132:135], v[156:159], v[164:167]
	v_mfma_f32_16x16x32_bf16 v[108:111], v[124:127], v[180:183], v[108:111]
	v_mfma_f32_16x16x32_bf16 v[104:107], v[132:135], v[180:183], v[104:107]
	v_mfma_f32_16x16x32_bf16 v[92:95], v[124:127], v[192:195], v[92:95]
	v_mfma_f32_16x16x32_bf16 v[88:91], v[132:135], v[192:195], v[88:91]
	v_mfma_f32_16x16x32_bf16 v[76:79], v[124:127], v[200:203], v[76:79]
	v_mfma_f32_16x16x32_bf16 v[68:71], v[132:135], v[200:203], v[68:71]
	v_mfma_f32_16x16x32_bf16 v[176:179], v[136:139], v[152:155], v[176:179]
	v_mfma_f32_16x16x32_bf16 v[100:103], v[136:139], v[160:163], v[100:103]
	v_mfma_f32_16x16x32_bf16 v[96:99], v[144:147], v[160:163], v[96:99]
	v_mfma_f32_16x16x32_bf16 v[84:87], v[136:139], v[188:191], v[84:87]
	v_mfma_f32_16x16x32_bf16 v[80:83], v[144:147], v[188:191], v[80:83]
	v_mfma_f32_16x16x32_bf16 v[64:67], v[136:139], v[196:199], v[64:67]
	v_mfma_f32_16x16x32_bf16 v[52:55], v[144:147], v[196:199], v[52:55]
	v_mfma_f32_16x16x32_bf16 v[176:179], v[140:143], v[156:159], v[176:179]
	v_mfma_f32_16x16x32_bf16 v[152:155], v[144:147], v[152:155], v[168:171]
	v_mfma_f32_16x16x32_bf16 v[100:103], v[140:143], v[180:183], v[100:103]
	v_mfma_f32_16x16x32_bf16 v[96:99], v[148:151], v[180:183], v[96:99]
	v_mfma_f32_16x16x32_bf16 v[84:87], v[140:143], v[192:195], v[84:87]
	v_mfma_f32_16x16x32_bf16 v[80:83], v[148:151], v[192:195], v[80:83]
	v_mfma_f32_16x16x32_bf16 v[64:67], v[140:143], v[200:203], v[64:67]
	v_mfma_f32_16x16x32_bf16 v[52:55], v[148:151], v[200:203], v[52:55]
	v_mfma_f32_16x16x32_bf16 v[152:155], v[148:151], v[156:159], v[152:155]
	s_barrier
	v_mov_b32_e32 v207, v185
	s_mov_b32 m0, s55
	v_lshl_add_u64 v[216:217], s[66:67], 0, v[206:207]
	ds_read_b128 v[156:159], v118 offset:16384
	ds_read_b128 v[160:163], v118 offset:17408
	ds_read_b128 v[168:171], v118 offset:18432
	ds_read_b128 v[180:183], v118 offset:19456
	ds_read_b128 v[188:191], v118 offset:20480
	ds_read_b128 v[192:195], v118 offset:21504
	ds_read_b128 v[196:199], v118 offset:22528
	ds_read_b128 v[200:203], v118 offset:23552
	global_load_lds_dwordx4 v206, s[66:67]
	v_lshl_add_u64 v[206:207], v[216:217], 0, s[88:89]
	s_mov_b32 m0, s56
	s_nop 0
	global_load_lds_dwordx4 v[206:207], off
	v_lshl_add_u64 v[206:207], v[216:217], 0, s[90:91]
	s_mov_b32 m0, s57
	s_nop 0
	global_load_lds_dwordx4 v[206:207], off
	v_lshl_add_u64 v[206:207], v[216:217], 0, s[96:97]
	s_mov_b32 m0, s58
	s_nop 0
	global_load_lds_dwordx4 v[206:207], off
	v_lshl_add_u64 v[206:207], s[22:23], 0, v[184:185]
	s_mov_b32 m0, s7
	v_lshl_add_u64 v[212:213], v[206:207], 0, s[88:89]
	global_load_lds_dwordx4 v[206:207], off
	s_mov_b32 m0, s31
	s_nop 0
	global_load_lds_dwordx4 v[212:213], off
	s_waitcnt vmcnt(8)
	s_waitcnt lgkmcnt(0)
	s_barrier
	v_mfma_f32_16x16x32_bf16 v[72:75], v[120:123], v[156:159], v[72:75]
	v_mfma_f32_16x16x32_bf16 v[60:63], v[128:131], v[156:159], v[60:63]
	v_mfma_f32_16x16x32_bf16 v[44:47], v[120:123], v[168:171], v[44:47]
	v_mfma_f32_16x16x32_bf16 v[40:43], v[128:131], v[168:171], v[40:43]
	v_mfma_f32_16x16x32_bf16 v[28:31], v[120:123], v[188:191], v[28:31]
	v_mfma_f32_16x16x32_bf16 v[24:27], v[128:131], v[188:191], v[24:27]
	v_mfma_f32_16x16x32_bf16 v[12:15], v[120:123], v[196:199], v[12:15]
	v_mfma_f32_16x16x32_bf16 v[8:11], v[128:131], v[196:199], v[8:11]
	v_mfma_f32_16x16x32_bf16 v[72:75], v[124:127], v[160:163], v[72:75]
	v_mfma_f32_16x16x32_bf16 v[60:63], v[132:135], v[160:163], v[60:63]
	v_mfma_f32_16x16x32_bf16 v[44:47], v[124:127], v[180:183], v[44:47]
	v_mfma_f32_16x16x32_bf16 v[40:43], v[132:135], v[180:183], v[40:43]
	v_mfma_f32_16x16x32_bf16 v[28:31], v[124:127], v[192:195], v[28:31]
	v_mfma_f32_16x16x32_bf16 v[24:27], v[132:135], v[192:195], v[24:27]
	v_mfma_f32_16x16x32_bf16 v[12:15], v[124:127], v[200:203], v[12:15]
	v_mfma_f32_16x16x32_bf16 v[8:11], v[132:135], v[200:203], v[8:11]
	v_mfma_f32_16x16x32_bf16 v[56:59], v[136:139], v[156:159], v[56:59]
	v_mfma_f32_16x16x32_bf16 v[48:51], v[144:147], v[156:159], v[48:51]
	v_mfma_f32_16x16x32_bf16 v[36:39], v[136:139], v[168:171], v[36:39]
	v_mfma_f32_16x16x32_bf16 v[32:35], v[144:147], v[168:171], v[32:35]
	v_mfma_f32_16x16x32_bf16 v[20:23], v[136:139], v[188:191], v[20:23]
	v_mfma_f32_16x16x32_bf16 v[16:19], v[144:147], v[188:191], v[16:19]
	v_mfma_f32_16x16x32_bf16 v[4:7], v[136:139], v[196:199], v[4:7]
	v_mfma_f32_16x16x32_bf16 v[0:3], v[144:147], v[196:199], v[0:3]
	v_mfma_f32_16x16x32_bf16 v[56:59], v[140:143], v[160:163], v[56:59]
	v_mfma_f32_16x16x32_bf16 v[48:51], v[148:151], v[160:163], v[48:51]
	v_mfma_f32_16x16x32_bf16 v[36:39], v[140:143], v[180:183], v[36:39]
	v_mfma_f32_16x16x32_bf16 v[32:35], v[148:151], v[180:183], v[32:35]
	v_mfma_f32_16x16x32_bf16 v[20:23], v[140:143], v[192:195], v[20:23]
	v_mfma_f32_16x16x32_bf16 v[16:19], v[148:151], v[192:195], v[16:19]
	v_mfma_f32_16x16x32_bf16 v[4:7], v[140:143], v[200:203], v[4:7]
	v_mfma_f32_16x16x32_bf16 v[0:3], v[148:151], v[200:203], v[0:3]
	s_barrier
; #define PG8_WAIT_V(n) asm volatile("s_waitcnt vmcnt(" #n ")" ::: "memory")
; #define PG8_WAIT_VP() asm volatile("s_waitcnt vmcnt(%0)" :: "n"(8 + Epi::NST) : "memory")
; #define PG8_BAR __builtin_amdgcn_s_barrier()
; template <class Epi, class Sched>
; __device__ __forceinline__ void gemm_phase(PG8_LAS unsigned char* lds, const Sched& S, const Epi& E, int tid_in) {
;     ...
;         { const int t = 0; PG8_KITER(PG8_WAIT_VP()); }
;         for (int t = 2; t < nt; t += 2) PG8_KITER(PG8_WAIT_V(8));
;     ...
;         if (wr == 0) PG8_BAR;
	ds_read_b128 v[120:123], v113
	ds_read_b128 v[124:127], v113 offset:1024
	ds_read_b128 v[128:131], v113 offset:2048
	ds_read_b128 v[132:135], v113 offset:3072
	ds_read_b128 v[136:139], v119
	ds_read_b128 v[140:143], v119 offset:1024
	ds_read_b128 v[144:147], v119 offset:2048
	ds_read_b128 v[148:151], v119 offset:3072
	s_mov_b32 m0, s34
	v_lshl_add_u64 v[168:169], v[206:207], 0, s[90:91]
	ds_read_b128 v[156:159], v118 offset:32768
	ds_read_b128 v[160:163], v118 offset:33792
	ds_read_b128 v[180:183], v118 offset:34816
	ds_read_b128 v[188:191], v118 offset:35840
	ds_read_b128 v[192:195], v118 offset:36864
	ds_read_b128 v[196:199], v118 offset:37888
	ds_read_b128 v[200:203], v118 offset:38912
	ds_read_b128 v[212:215], v118 offset:39936
	global_load_lds_dwordx4 v[168:169], off
	v_lshl_add_u64 v[168:169], v[206:207], 0, s[96:97]
	s_mov_b32 m0, s35
	s_nop 0
	global_load_lds_dwordx4 v[168:169], off
	s_waitcnt vmcnt(8)
	s_waitcnt lgkmcnt(0)
	s_barrier
	v_mfma_f32_16x16x32_bf16 v[168:171], v[120:123], v[156:159], v[172:175]
	v_mfma_f32_16x16x32_bf16 v[164:167], v[128:131], v[156:159], v[164:167]
	v_mfma_f32_16x16x32_bf16 v[108:111], v[120:123], v[180:183], v[108:111]
	v_mfma_f32_16x16x32_bf16 v[104:107], v[128:131], v[180:183], v[104:107]
	v_mfma_f32_16x16x32_bf16 v[92:95], v[120:123], v[192:195], v[92:95]
	v_mfma_f32_16x16x32_bf16 v[88:91], v[128:131], v[192:195], v[88:91]
	v_mfma_f32_16x16x32_bf16 v[76:79], v[120:123], v[200:203], v[76:79]
	v_mfma_f32_16x16x32_bf16 v[68:71], v[128:131], v[200:203], v[68:71]
	v_mfma_f32_16x16x32_bf16 v[172:175], v[124:127], v[160:163], v[168:171]
	v_mfma_f32_16x16x32_bf16 v[164:167], v[132:135], v[160:163], v[164:167]
	v_mfma_f32_16x16x32_bf16 v[108:111], v[124:127], v[188:191], v[108:111]
	v_mfma_f32_16x16x32_bf16 v[104:107], v[132:135], v[188:191], v[104:107]
	v_mfma_f32_16x16x32_bf16 v[92:95], v[124:127], v[196:199], v[92:95]
	v_mfma_f32_16x16x32_bf16 v[88:91], v[132:135], v[196:199], v[88:91]
	v_mfma_f32_16x16x32_bf16 v[76:79], v[124:127], v[212:215], v[76:79]
	v_mfma_f32_16x16x32_bf16 v[68:71], v[132:135], v[212:215], v[68:71]
	v_mfma_f32_16x16x32_bf16 v[168:171], v[136:139], v[156:159], v[176:179]
	v_mfma_f32_16x16x32_bf16 v[152:155], v[144:147], v[156:159], v[152:155]
	v_mfma_f32_16x16x32_bf16 v[100:103], v[136:139], v[180:183], v[100:103]
	v_mfma_f32_16x16x32_bf16 v[96:99], v[144:147], v[180:183], v[96:99]
	v_mfma_f32_16x16x32_bf16 v[84:87], v[136:139], v[192:195], v[84:87]
	v_mfma_f32_16x16x32_bf16 v[80:83], v[144:147], v[192:195], v[80:83]
	v_mfma_f32_16x16x32_bf16 v[64:67], v[136:139], v[200:203], v[64:67]
	v_mfma_f32_16x16x32_bf16 v[52:55], v[144:147], v[200:203], v[52:55]
	v_mfma_f32_16x16x32_bf16 v[176:179], v[140:143], v[160:163], v[168:171]
	v_mfma_f32_16x16x32_bf16 v[168:171], v[148:151], v[160:163], v[152:155]
	v_mfma_f32_16x16x32_bf16 v[100:103], v[140:143], v[188:191], v[100:103]
	v_mfma_f32_16x16x32_bf16 v[96:99], v[148:151], v[188:191], v[96:99]
	v_mfma_f32_16x16x32_bf16 v[84:87], v[140:143], v[196:199], v[84:87]
	v_mfma_f32_16x16x32_bf16 v[80:83], v[148:151], v[196:199], v[80:83]
	v_mfma_f32_16x16x32_bf16 v[64:67], v[140:143], v[212:215], v[64:67]
	v_mfma_f32_16x16x32_bf16 v[52:55], v[148:151], v[212:215], v[52:55]
	s_barrier
	s_mov_b32 m0, s59
	v_lshl_add_u64 v[212:213], v[216:217], 0, s[84:85]
	ds_read_b128 v[152:155], v118 offset:49152
	ds_read_b128 v[156:159], v118 offset:50176
	ds_read_b128 v[160:163], v118 offset:51200
	ds_read_b128 v[180:183], v118 offset:52224
	ds_read_b128 v[188:191], v118 offset:53248
	ds_read_b128 v[192:195], v118 offset:54272
	ds_read_b128 v[196:199], v118 offset:55296
	ds_read_b128 v[200:203], v118 offset:56320
	global_load_lds_dwordx4 v[212:213], off
	v_lshl_add_u64 v[212:213], v[216:217], 0, s[94:95]
	s_mov_b32 m0, s60
	s_nop 0
	global_load_lds_dwordx4 v[212:213], off
	v_lshl_add_u64 v[212:213], v[216:217], 0, s[80:81]
	s_mov_b32 m0, s61
	s_nop 0
	global_load_lds_dwordx4 v[212:213], off
	v_lshl_add_u64 v[212:213], v[216:217], 0, s[78:79]
	s_mov_b32 m0, s62
	s_nop 0
	global_load_lds_dwordx4 v[212:213], off
	v_lshl_add_u64 v[212:213], v[206:207], 0, s[84:85]
	s_mov_b32 m0, s44
	v_lshl_add_u64 v[206:207], v[206:207], 0, s[94:95]
	global_load_lds_dwordx4 v[212:213], off
	s_mov_b32 m0, s45
	s_nop 0
	global_load_lds_dwordx4 v[206:207], off
	s_waitcnt vmcnt(8)
	s_waitcnt lgkmcnt(0)
	s_barrier
	v_mfma_f32_16x16x32_bf16 v[72:75], v[120:123], v[152:155], v[72:75]
	v_mfma_f32_16x16x32_bf16 v[60:63], v[128:131], v[152:155], v[60:63]
	v_mfma_f32_16x16x32_bf16 v[44:47], v[120:123], v[160:163], v[44:47]
	v_mfma_f32_16x16x32_bf16 v[40:43], v[128:131], v[160:163], v[40:43]
	v_mfma_f32_16x16x32_bf16 v[28:31], v[120:123], v[188:191], v[28:31]
	v_mfma_f32_16x16x32_bf16 v[24:27], v[128:131], v[188:191], v[24:27]
	v_mfma_f32_16x16x32_bf16 v[12:15], v[120:123], v[196:199], v[12:15]
	v_mfma_f32_16x16x32_bf16 v[8:11], v[128:131], v[196:199], v[8:11]
	v_mfma_f32_16x16x32_bf16 v[72:75], v[124:127], v[156:159], v[72:75]
	v_mfma_f32_16x16x32_bf16 v[60:63], v[132:135], v[156:159], v[60:63]
	v_mfma_f32_16x16x32_bf16 v[44:47], v[124:127], v[180:183], v[44:47]
	v_mfma_f32_16x16x32_bf16 v[40:43], v[132:135], v[180:183], v[40:43]
	v_mfma_f32_16x16x32_bf16 v[28:31], v[124:127], v[192:195], v[28:31]
	v_mfma_f32_16x16x32_bf16 v[24:27], v[132:135], v[192:195], v[24:27]
	v_mfma_f32_16x16x32_bf16 v[12:15], v[124:127], v[200:203], v[12:15]
	v_mfma_f32_16x16x32_bf16 v[8:11], v[132:135], v[200:203], v[8:11]
	v_mfma_f32_16x16x32_bf16 v[56:59], v[136:139], v[152:155], v[56:59]
	v_mfma_f32_16x16x32_bf16 v[48:51], v[144:147], v[152:155], v[48:51]
	v_mfma_f32_16x16x32_bf16 v[36:39], v[136:139], v[160:163], v[36:39]
	v_mfma_f32_16x16x32_bf16 v[32:35], v[144:147], v[160:163], v[32:35]
	v_mfma_f32_16x16x32_bf16 v[20:23], v[136:139], v[188:191], v[20:23]
	v_mfma_f32_16x16x32_bf16 v[16:19], v[144:147], v[188:191], v[16:19]
	v_mfma_f32_16x16x32_bf16 v[4:7], v[136:139], v[196:199], v[4:7]
	v_mfma_f32_16x16x32_bf16 v[0:3], v[144:147], v[196:199], v[0:3]
	v_mfma_f32_16x16x32_bf16 v[56:59], v[140:143], v[156:159], v[56:59]
	v_mfma_f32_16x16x32_bf16 v[48:51], v[148:151], v[156:159], v[48:51]
	v_mfma_f32_16x16x32_bf16 v[36:39], v[140:143], v[180:183], v[36:39]
	v_mfma_f32_16x16x32_bf16 v[32:35], v[148:151], v[180:183], v[32:35]
	v_mfma_f32_16x16x32_bf16 v[20:23], v[140:143], v[192:195], v[20:23]
	v_mfma_f32_16x16x32_bf16 v[16:19], v[148:151], v[192:195], v[16:19]
	v_mfma_f32_16x16x32_bf16 v[4:7], v[140:143], v[200:203], v[4:7]
	v_mfma_f32_16x16x32_bf16 v[0:3], v[148:151], v[200:203], v[0:3]
	s_barrier
	s_add_i32 s65, s65, 2
	s_add_u32 s20, s20, 0x100
	s_addc_u32 s21, s21, 0
	s_add_u32 s63, s63, 0x100
	s_addc_u32 s64, s64, 0
	s_cmp_gt_u32 s65, 29
	s_cbranch_scc0 .LBB0_1446
	s_and_b64 vcc, exec, s[12:13]
	s_cbranch_vccz .LBB0_1449
	s_barrier
